# v58 + ldspipe on the unrolled P3/P4/P6 small_gemm chunks (fix: drain reads issued before a block that starts mid-chunk)
# baseline (speedup 1.0000x reference)
.LBB0_2090:
	s_mov_b32 s34, s47
	s_waitcnt vmcnt(63) expcnt(7) lgkmcnt(15)
	s_load_dwordx2 s[12:13], s[40:41], s34 offset:0xd8
	s_add_i32 s34, s34, s62
	v_readlane_b32 s0, v255, 43
	s_mul_i32 s0, s0, 0x1a00000
	v_readlane_b32 s1, v255, 44
	s_waitcnt lgkmcnt(0)
	s_add_u32 s10, s12, 0x9400000
	s_addc_u32 s11, s13, 0
	s_add_u32 s0, s12, s0
	s_addc_u32 s1, s13, 0
	s_add_u32 s14, s0, 0x800000
	s_addc_u32 s15, s1, 0
	v_readlane_b32 s0, v255, 18
	v_readlane_b32 s1, v255, 19
	s_add_i32 s46, s0, 0x10800
	s_lshl_b64 s[0:1], s[46:47], 2
	s_add_u32 s2, s12, s0
	s_addc_u32 s3, s13, s1
	s_add_u32 s2, s2, 0x100000
	s_addc_u32 s3, s3, 0
	s_bitcmp0_b32 s34, 0
	s_cselect_b64 s[16:17], -1, 0
	v_mov_b32_e32 v1, v0
	s_and_b64 vcc, exec, s[16:17]
	s_cbranch_vccnz .LBB0_2094
	v_mov_b32_e32 v1, v0
	s_lshl_b32 s5, s34, 3
	v_ashrrev_i32_e32 v2, 31, v1
	v_lshrrev_b32_e32 v2, 28, v2
	v_add_u32_e32 v2, v1, v2
	v_ashrrev_i32_e32 v17, 4, v2
	s_and_b32 s5, s5, 0xffffff80
	v_and_b32_e32 v2, -16, v2
	v_add_u32_e32 v4, s5, v17
	v_sub_u32_e32 v19, v1, v2
	v_ashrrev_i32_e32 v5, 31, v4
	v_lshlrev_b64 v[6:7], 13, v[4:5]
	v_lshlrev_b32_e32 v4, 3, v19
	v_ashrrev_i32_e32 v5, 31, v4
	v_lshlrev_b64 v[10:11], 1, v[4:5]
	v_lshl_add_u64 v[6:7], s[12:13], 0, v[6:7]
	v_lshl_add_u64 v[14:15], v[6:7], 0, v[10:11]
	s_mov_b32 s6, 0x31801000
	s_lshl_b32 s4, s34, 6
	v_add_co_u32_e32 v6, vcc, s6, v14
	s_and_b32 s4, s4, 0x3c0
	s_nop 0
	v_addc_co_u32_e32 v7, vcc, 0, v15, vcc
	s_mov_b32 s6, 0x31841000
	v_add_u32_e32 v8, s4, v17
	global_load_dwordx4 v[20:23], v[6:7], off
	v_add_co_u32_e32 v6, vcc, s6, v14
	v_ashrrev_i32_e32 v9, 31, v8
	s_nop 0
	v_addc_co_u32_e32 v7, vcc, 0, v15, vcc
	s_mov_b32 s6, 0x31881000
	v_lshlrev_b64 v[8:9], 11, v[8:9]
	v_add_co_u32_e32 v12, vcc, s6, v14
	v_lshl_add_u64 v[8:9], s[14:15], 0, v[8:9]
	s_nop 0
	v_addc_co_u32_e32 v13, vcc, 0, v15, vcc
	s_mov_b32 s6, 0x318c1000
	v_lshl_add_u64 v[4:5], v[8:9], 0, v[10:11]
	v_add_co_u32_e32 v8, vcc, s6, v14
	global_load_dwordx4 v[24:27], v[6:7], off
	global_load_dwordx4 v[28:31], v[12:13], off
	v_addc_co_u32_e32 v9, vcc, 0, v15, vcc
	global_load_dwordx4 v[32:35], v[8:9], off
	global_load_dwordx4 v[36:39], v[4:5], off
	v_add_co_u32_e32 v10, vcc, s63, v4
	s_mov_b64 s[8:9], 0x31801000
	s_nop 0
	v_addc_co_u32_e32 v11, vcc, 0, v5, vcc
	global_load_dwordx4 v[40:43], v[10:11], off
	v_lshl_add_u64 v[14:15], v[14:15], 0, s[8:9]
	global_load_dwordx4 v[44:47], v[4:5], off offset:256
	global_load_dwordx4 v[48:51], v[14:15], off offset:256
	global_load_dwordx4 v[52:55], v[6:7], off offset:256
	global_load_dwordx4 v[56:59], v[12:13], off offset:256
	global_load_dwordx4 v[60:63], v[8:9], off offset:256
	global_load_dwordx4 v[64:67], v[10:11], off offset:256
	v_mul_lo_u32 v17, v17, s81
	v_lshlrev_b32_e32 v19, 4, v19
	v_and_b32_e32 v16, 15, v1
	v_bfe_u32 v2, v1, 4, 2
	v_add3_u32 v17, v17, v19, 0
	v_lshlrev_b32_e32 v68, 4, v2
	v_mul_u32_u24_e32 v18, 0x110, v16
	v_add3_u32 v18, v18, v68, 0
	v_readfirstlane_b32 s6, v1
	s_ashr_i32 s6, s6, 2
	s_add_i32 s5, s5, 0x10000
	v_bfi_b32 v19, -16, s6, v1
	v_mul_lo_u32 v19, v19, s81
	v_add3_u32 v19, v19, v68, 0
	s_and_b32 s6, s6, -16
	s_lshl_b32 s46, s4, 1
	v_and_b32_e32 v1, 16, v1
	v_cmp_eq_u32_e32 vcc, 0, v1
	s_waitcnt vmcnt(0)
	ds_write_b128 v17, v[36:39] offset:34816
	ds_write_b128 v17, v[20:23]
	ds_write_b128 v17, v[24:27] offset:8704
	ds_write_b128 v17, v[28:31] offset:17408
	ds_write_b128 v17, v[32:35] offset:26112
	ds_write_b128 v17, v[40:43] offset:43520
	s_waitcnt lgkmcnt(0)
	s_barrier
	ds_read_b128 v[88:91], v18 offset:34816
	ds_read_b128 v[92:95], v19
	ds_read_b128 v[96:99], v19 offset:64
	ds_read_b128 v[100:103], v18 offset:34880
	ds_read_b128 v[104:107], v18 offset:39168
	ds_read_b128 v[108:111], v18 offset:39232
	ds_read_b128 v[112:115], v18 offset:43520
	s_waitcnt lgkmcnt(5)
	v_mfma_f32_16x16x32_bf16 v[20:23], v[88:91], v[92:95], 0
	ds_read_b128 v[88:91], v18 offset:43584
	ds_read_b128 v[116:119], v18 offset:47872
	ds_read_b128 v[120:123], v18 offset:47936
	s_waitcnt lgkmcnt(5)
	v_mfma_f32_16x16x32_bf16 v[36:39], v[104:107], v[92:95], 0
	s_waitcnt lgkmcnt(6)
	v_mfma_f32_16x16x32_bf16 v[20:23], v[100:103], v[96:99], v[20:23]
	ds_read_b128 v[100:103], v18 offset:34944
	s_waitcnt lgkmcnt(5)
	v_mfma_f32_16x16x32_bf16 v[32:35], v[108:111], v[96:99], v[36:39]
	ds_read_b128 v[104:107], v19 offset:128
	s_waitcnt lgkmcnt(5)
	v_mfma_f32_16x16x32_bf16 v[68:71], v[112:115], v[92:95], 0
	s_waitcnt lgkmcnt(3)
	v_mfma_f32_16x16x32_bf16 v[24:27], v[116:119], v[92:95], 0
	s_waitcnt lgkmcnt(4)
	v_mfma_f32_16x16x32_bf16 v[36:39], v[88:91], v[96:99], v[68:71]
	s_nop 2
	ds_read_b128 v[68:71], v19 offset:192
	ds_read_b128 v[72:75], v18 offset:35008
	ds_read_b128 v[88:91], v18 offset:39296
	s_waitcnt lgkmcnt(5)
	v_mfma_f32_16x16x32_bf16 v[24:27], v[120:123], v[96:99], v[24:27]
	ds_read_b128 v[76:79], v18 offset:39360
	ds_read_b128 v[92:95], v18 offset:43648
	s_waitcnt lgkmcnt(5)
	v_mfma_f32_16x16x32_bf16 v[40:43], v[100:103], v[104:107], v[20:23]
	ds_read_b128 v[80:83], v18 offset:43712
	ds_read_b128 v[96:99], v18 offset:48000
	ds_read_b128 v[84:87], v18 offset:48064
	s_waitcnt lgkmcnt(5)
	v_mfma_f32_16x16x32_bf16 v[32:35], v[88:91], v[104:107], v[32:35]
	s_waitcnt lgkmcnt(3)
	v_mfma_f32_16x16x32_bf16 v[36:39], v[92:95], v[104:107], v[36:39]
	s_waitcnt lgkmcnt(1)
	v_mfma_f32_16x16x32_bf16 v[24:27], v[96:99], v[104:107], v[24:27]
	s_waitcnt lgkmcnt(1)
	v_add_u32_e32 v21, 0xcc00, v17
	v_add_u32_e32 v22, 0x15400, v17
	v_add_u32_e32 v23, 0x17600, v17
	v_mfma_f32_16x16x32_bf16 v[28:31], v[72:75], v[68:71], v[40:43]
	s_nop 2
	global_load_dwordx4 v[40:43], v[6:7], off offset:512
	global_load_dwordx4 v[72:75], v[12:13], off offset:512
	v_add_u32_e32 v20, 0x8800, v18
	v_mfma_f32_16x16x32_bf16 v[32:35], v[76:79], v[68:71], v[32:35]
	global_load_dwordx4 v[76:79], v[14:15], off offset:512
	global_load_dwordx4 v[88:91], v[4:5], off offset:512
	global_load_dwordx4 v[92:95], v[8:9], off offset:512
	global_load_dwordx4 v[96:99], v[10:11], off offset:512
	ds_write_b128 v17, v[48:51] offset:52224
	ds_write_b128 v17, v[52:55] offset:60928
	ds_write_b128 v21, v[56:59] offset:17408
	ds_write_b128 v21, v[60:63] offset:26112
	ds_write_b128 v22, v[44:47]
	ds_write_b128 v23, v[64:67]
	s_waitcnt lgkmcnt(0)
	s_barrier
	ds_read_b128 v[100:103], v20 offset:52224
	ds_read_b128 v[104:107], v19 offset:52224
	ds_read_b128 v[108:111], v19 offset:52288
	ds_read_b128 v[112:115], v20 offset:52288
	ds_read_b128 v[116:119], v20 offset:56576
	ds_read_b128 v[120:123], v20 offset:56640
	ds_read_b128 v[124:127], v20 offset:60928
	s_waitcnt lgkmcnt(5)
	v_mfma_f32_16x16x32_bf16 v[28:31], v[100:103], v[104:107], v[28:31]
	v_mfma_f32_16x16x32_bf16 v[36:39], v[80:83], v[68:71], v[36:39]
	ds_read_b128 v[100:103], v20 offset:60992
	ds_read_b128 v[128:131], v20 offset:65280
	ds_read_b128 v[132:135], v20 offset:65344
	s_waitcnt lgkmcnt(5)
	v_mfma_f32_16x16x32_bf16 v[32:35], v[116:119], v[104:107], v[32:35]
	v_mfma_f32_16x16x32_bf16 v[24:27], v[84:87], v[68:71], v[24:27]
	ds_read_b128 v[116:119], v20 offset:52352
	ds_read_b128 v[136:139], v19 offset:52352
	s_waitcnt lgkmcnt(5)
	v_mfma_f32_16x16x32_bf16 v[36:39], v[124:127], v[104:107], v[36:39]
	ds_read_b128 v[52:55], v19 offset:52416
	ds_read_b128 v[56:59], v20 offset:52416
	s_waitcnt lgkmcnt(5)
	v_mfma_f32_16x16x32_bf16 v[24:27], v[128:131], v[104:107], v[24:27]
	s_waitcnt lgkmcnt(10)
	v_mfma_f32_16x16x32_bf16 v[28:31], v[112:115], v[108:111], v[28:31]
	s_waitcnt lgkmcnt(8)
	v_mfma_f32_16x16x32_bf16 v[32:35], v[120:123], v[108:111], v[32:35]
	s_waitcnt lgkmcnt(6)
	v_mfma_f32_16x16x32_bf16 v[36:39], v[100:103], v[108:111], v[36:39]
	ds_read_b128 v[100:103], v20 offset:56704
	s_waitcnt lgkmcnt(5)
	v_mfma_f32_16x16x32_bf16 v[24:27], v[132:135], v[108:111], v[24:27]
	ds_read_b128 v[60:63], v20 offset:56768
	ds_read_b128 v[104:107], v20 offset:61056
	s_waitcnt lgkmcnt(5)
	v_mfma_f32_16x16x32_bf16 v[28:31], v[116:119], v[136:139], v[28:31]
	ds_read_b128 v[64:67], v20 offset:61120
	ds_read_b128 v[108:111], v20 offset:65408
	ds_read_b128 v[68:71], v20 offset:65472
	s_waitcnt lgkmcnt(5)
	v_mfma_f32_16x16x32_bf16 v[32:35], v[100:103], v[136:139], v[32:35]
	s_waitcnt lgkmcnt(3)
	v_mfma_f32_16x16x32_bf16 v[36:39], v[104:107], v[136:139], v[36:39]
	s_waitcnt lgkmcnt(1)
	v_mfma_f32_16x16x32_bf16 v[24:27], v[108:111], v[136:139], v[24:27]
	s_waitcnt lgkmcnt(1)
	global_load_dwordx4 v[44:47], v[6:7], off offset:768
	global_load_dwordx4 v[48:51], v[12:13], off offset:768
	v_mfma_f32_16x16x32_bf16 v[28:31], v[56:59], v[52:55], v[28:31]
	v_mfma_f32_16x16x32_bf16 v[32:35], v[60:63], v[52:55], v[32:35]
	global_load_dwordx4 v[56:59], v[14:15], off offset:768
	global_load_dwordx4 v[60:63], v[4:5], off offset:768
	global_load_dwordx4 v[80:83], v[8:9], off offset:768
	global_load_dwordx4 v[84:87], v[10:11], off offset:768
	s_waitcnt vmcnt(9)
	ds_write_b128 v17, v[76:79]
	ds_write_b128 v17, v[40:43] offset:8704
	ds_write_b128 v17, v[72:75] offset:17408
	s_waitcnt vmcnt(7)
	ds_write_b128 v17, v[92:95] offset:26112
	ds_write_b128 v17, v[88:91] offset:34816
	s_waitcnt vmcnt(6)
	ds_write_b128 v17, v[96:99] offset:43520
	s_waitcnt lgkmcnt(0)
	s_barrier
	ds_read_b128 v[92:95], v18 offset:34816
	ds_read_b128 v[96:99], v19
	ds_read_b128 v[100:103], v19 offset:64
	ds_read_b128 v[104:107], v18 offset:34880
	ds_read_b128 v[108:111], v18 offset:39168
	v_mfma_f32_16x16x32_bf16 v[36:39], v[64:67], v[52:55], v[36:39]
	v_mfma_f32_16x16x32_bf16 v[24:27], v[68:71], v[52:55], v[24:27]
	ds_read_b128 v[112:115], v18 offset:39232
	ds_read_b128 v[116:119], v18 offset:43520
	s_waitcnt lgkmcnt(5)
	v_mfma_f32_16x16x32_bf16 v[28:31], v[92:95], v[96:99], v[28:31]
	ds_read_b128 v[92:95], v18 offset:43584
	ds_read_b128 v[120:123], v18 offset:47872
	ds_read_b128 v[124:127], v18 offset:47936
	s_waitcnt lgkmcnt(5)
	v_mfma_f32_16x16x32_bf16 v[32:35], v[108:111], v[96:99], v[32:35]
	ds_read_b128 v[108:111], v18 offset:34944
	ds_read_b128 v[128:131], v19 offset:128
	s_waitcnt lgkmcnt(5)
	v_mfma_f32_16x16x32_bf16 v[36:39], v[116:119], v[96:99], v[36:39]
	ds_read_b128 v[64:67], v19 offset:192
	ds_read_b128 v[68:71], v18 offset:35008
	s_waitcnt lgkmcnt(5)
	v_mfma_f32_16x16x32_bf16 v[24:27], v[120:123], v[96:99], v[24:27]
	s_waitcnt lgkmcnt(10)
	v_mfma_f32_16x16x32_bf16 v[28:31], v[104:107], v[100:103], v[28:31]
	s_waitcnt lgkmcnt(8)
	v_mfma_f32_16x16x32_bf16 v[32:35], v[112:115], v[100:103], v[32:35]
	s_waitcnt lgkmcnt(6)
	v_mfma_f32_16x16x32_bf16 v[36:39], v[92:95], v[100:103], v[36:39]
	ds_read_b128 v[92:95], v18 offset:39296
	s_waitcnt lgkmcnt(5)
	v_mfma_f32_16x16x32_bf16 v[24:27], v[124:127], v[100:103], v[24:27]
	ds_read_b128 v[72:75], v18 offset:39360
	ds_read_b128 v[96:99], v18 offset:43648
	s_waitcnt lgkmcnt(5)
	v_mfma_f32_16x16x32_bf16 v[28:31], v[108:111], v[128:131], v[28:31]
	ds_read_b128 v[76:79], v18 offset:43712
	ds_read_b128 v[100:103], v18 offset:48000
	ds_read_b128 v[88:91], v18 offset:48064
	s_waitcnt lgkmcnt(5)
	v_mfma_f32_16x16x32_bf16 v[32:35], v[92:95], v[128:131], v[32:35]
	s_waitcnt lgkmcnt(3)
	v_mfma_f32_16x16x32_bf16 v[36:39], v[96:99], v[128:131], v[36:39]
	s_waitcnt lgkmcnt(1)
	v_mfma_f32_16x16x32_bf16 v[24:27], v[100:103], v[128:131], v[24:27]
	s_waitcnt lgkmcnt(1)
	global_load_dwordx4 v[40:43], v[6:7], off offset:1024
	global_load_dwordx4 v[52:55], v[12:13], off offset:1024
	v_mfma_f32_16x16x32_bf16 v[28:31], v[68:71], v[64:67], v[28:31]
	v_mfma_f32_16x16x32_bf16 v[32:35], v[72:75], v[64:67], v[32:35]
	global_load_dwordx4 v[68:71], v[14:15], off offset:1024
	global_load_dwordx4 v[72:75], v[4:5], off offset:1024
	global_load_dwordx4 v[92:95], v[8:9], off offset:1024
	global_load_dwordx4 v[96:99], v[10:11], off offset:1024
	s_waitcnt vmcnt(9)
	ds_write_b128 v17, v[56:59] offset:52224
	ds_write_b128 v17, v[44:47] offset:60928
	ds_write_b128 v21, v[48:51] offset:17408
	s_waitcnt vmcnt(7)
	ds_write_b128 v21, v[80:83] offset:26112
	ds_write_b128 v22, v[60:63]
	s_waitcnt vmcnt(6)
	ds_write_b128 v23, v[84:87]
	s_waitcnt lgkmcnt(0)
	s_barrier
	ds_read_b128 v[84:87], v20 offset:52224
	ds_read_b128 v[100:103], v19 offset:52224
	ds_read_b128 v[104:107], v19 offset:52288
	ds_read_b128 v[108:111], v20 offset:52288
	ds_read_b128 v[112:115], v20 offset:56576
	v_mfma_f32_16x16x32_bf16 v[36:39], v[76:79], v[64:67], v[36:39]
	v_mfma_f32_16x16x32_bf16 v[24:27], v[88:91], v[64:67], v[24:27]
	ds_read_b128 v[116:119], v20 offset:56640
	ds_read_b128 v[120:123], v20 offset:60928
	s_waitcnt lgkmcnt(5)
	v_mfma_f32_16x16x32_bf16 v[28:31], v[84:87], v[100:103], v[28:31]
	ds_read_b128 v[84:87], v20 offset:60992
	ds_read_b128 v[124:127], v20 offset:65280
	ds_read_b128 v[128:131], v20 offset:65344
	s_waitcnt lgkmcnt(5)
	v_mfma_f32_16x16x32_bf16 v[32:35], v[112:115], v[100:103], v[32:35]
	ds_read_b128 v[112:115], v20 offset:52352
	ds_read_b128 v[132:135], v19 offset:52352
	s_waitcnt lgkmcnt(5)
	v_mfma_f32_16x16x32_bf16 v[36:39], v[120:123], v[100:103], v[36:39]
	ds_read_b128 v[56:59], v19 offset:52416
	ds_read_b128 v[60:63], v20 offset:52416
	s_waitcnt lgkmcnt(5)
	v_mfma_f32_16x16x32_bf16 v[24:27], v[124:127], v[100:103], v[24:27]
	s_waitcnt lgkmcnt(10)
	v_mfma_f32_16x16x32_bf16 v[28:31], v[108:111], v[104:107], v[28:31]
	s_waitcnt lgkmcnt(8)
	v_mfma_f32_16x16x32_bf16 v[32:35], v[116:119], v[104:107], v[32:35]
	s_waitcnt lgkmcnt(6)
	v_mfma_f32_16x16x32_bf16 v[36:39], v[84:87], v[104:107], v[36:39]
	ds_read_b128 v[84:87], v20 offset:56704
	s_waitcnt lgkmcnt(5)
	v_mfma_f32_16x16x32_bf16 v[24:27], v[128:131], v[104:107], v[24:27]
	ds_read_b128 v[64:67], v20 offset:56768
	ds_read_b128 v[100:103], v20 offset:61056
	s_waitcnt lgkmcnt(5)
	v_mfma_f32_16x16x32_bf16 v[28:31], v[112:115], v[132:135], v[28:31]
	ds_read_b128 v[76:79], v20 offset:61120
	ds_read_b128 v[104:107], v20 offset:65408
	ds_read_b128 v[80:83], v20 offset:65472
	s_waitcnt lgkmcnt(5)
	v_mfma_f32_16x16x32_bf16 v[32:35], v[84:87], v[132:135], v[32:35]
	s_waitcnt lgkmcnt(3)
	v_mfma_f32_16x16x32_bf16 v[36:39], v[100:103], v[132:135], v[36:39]
	s_waitcnt lgkmcnt(1)
	v_mfma_f32_16x16x32_bf16 v[24:27], v[104:107], v[132:135], v[24:27]
	s_waitcnt lgkmcnt(1)
	global_load_dwordx4 v[44:47], v[6:7], off offset:1280
	global_load_dwordx4 v[48:51], v[12:13], off offset:1280
	v_mfma_f32_16x16x32_bf16 v[28:31], v[60:63], v[56:59], v[28:31]
	v_mfma_f32_16x16x32_bf16 v[32:35], v[64:67], v[56:59], v[32:35]
	global_load_dwordx4 v[60:63], v[14:15], off offset:1280
	global_load_dwordx4 v[64:67], v[4:5], off offset:1280
	global_load_dwordx4 v[84:87], v[8:9], off offset:1280
	global_load_dwordx4 v[88:91], v[10:11], off offset:1280
	s_waitcnt vmcnt(9)
	ds_write_b128 v17, v[68:71]
	ds_write_b128 v17, v[40:43] offset:8704
	ds_write_b128 v17, v[52:55] offset:17408
	s_waitcnt vmcnt(7)
	ds_write_b128 v17, v[92:95] offset:26112
	ds_write_b128 v17, v[72:75] offset:34816
	s_waitcnt vmcnt(6)
	ds_write_b128 v17, v[96:99] offset:43520
	s_waitcnt lgkmcnt(0)
	s_barrier
	ds_read_b128 v[92:95], v18 offset:34816
	ds_read_b128 v[96:99], v19
	ds_read_b128 v[100:103], v19 offset:64
	ds_read_b128 v[104:107], v18 offset:34880
	ds_read_b128 v[108:111], v18 offset:39168
	v_mfma_f32_16x16x32_bf16 v[36:39], v[76:79], v[56:59], v[36:39]
	v_mfma_f32_16x16x32_bf16 v[24:27], v[80:83], v[56:59], v[24:27]
	ds_read_b128 v[112:115], v18 offset:39232
	ds_read_b128 v[116:119], v18 offset:43520
	s_waitcnt lgkmcnt(5)
	v_mfma_f32_16x16x32_bf16 v[28:31], v[92:95], v[96:99], v[28:31]
	ds_read_b128 v[92:95], v18 offset:43584
	ds_read_b128 v[120:123], v18 offset:47872
	ds_read_b128 v[124:127], v18 offset:47936
	s_waitcnt lgkmcnt(5)
	v_mfma_f32_16x16x32_bf16 v[32:35], v[108:111], v[96:99], v[32:35]
	ds_read_b128 v[108:111], v18 offset:34944
	ds_read_b128 v[128:131], v19 offset:128
	s_waitcnt lgkmcnt(5)
	v_mfma_f32_16x16x32_bf16 v[36:39], v[116:119], v[96:99], v[36:39]
	ds_read_b128 v[56:59], v19 offset:192
	ds_read_b128 v[68:71], v18 offset:35008
	s_waitcnt lgkmcnt(5)
	v_mfma_f32_16x16x32_bf16 v[24:27], v[120:123], v[96:99], v[24:27]
	s_waitcnt lgkmcnt(10)
	v_mfma_f32_16x16x32_bf16 v[28:31], v[104:107], v[100:103], v[28:31]
	s_waitcnt lgkmcnt(8)
	v_mfma_f32_16x16x32_bf16 v[32:35], v[112:115], v[100:103], v[32:35]
	s_waitcnt lgkmcnt(6)
	v_mfma_f32_16x16x32_bf16 v[36:39], v[92:95], v[100:103], v[36:39]
	ds_read_b128 v[92:95], v18 offset:39296
	s_waitcnt lgkmcnt(5)
	v_mfma_f32_16x16x32_bf16 v[24:27], v[124:127], v[100:103], v[24:27]
	ds_read_b128 v[72:75], v18 offset:39360
	ds_read_b128 v[96:99], v18 offset:43648
	s_waitcnt lgkmcnt(5)
	v_mfma_f32_16x16x32_bf16 v[28:31], v[108:111], v[128:131], v[28:31]
	ds_read_b128 v[76:79], v18 offset:43712
	ds_read_b128 v[100:103], v18 offset:48000
	ds_read_b128 v[80:83], v18 offset:48064
	s_waitcnt lgkmcnt(5)
	v_mfma_f32_16x16x32_bf16 v[32:35], v[92:95], v[128:131], v[32:35]
	s_waitcnt lgkmcnt(3)
	v_mfma_f32_16x16x32_bf16 v[36:39], v[96:99], v[128:131], v[36:39]
	s_waitcnt lgkmcnt(1)
	v_mfma_f32_16x16x32_bf16 v[24:27], v[100:103], v[128:131], v[24:27]
	s_waitcnt lgkmcnt(1)
	global_load_dwordx4 v[40:43], v[6:7], off offset:1536
	global_load_dwordx4 v[52:55], v[12:13], off offset:1536
	v_mfma_f32_16x16x32_bf16 v[28:31], v[68:71], v[56:59], v[28:31]
	v_mfma_f32_16x16x32_bf16 v[32:35], v[72:75], v[56:59], v[32:35]
	global_load_dwordx4 v[68:71], v[14:15], off offset:1536
	global_load_dwordx4 v[72:75], v[4:5], off offset:1536
	global_load_dwordx4 v[92:95], v[8:9], off offset:1536
	global_load_dwordx4 v[96:99], v[10:11], off offset:1536
	s_waitcnt vmcnt(9)
	ds_write_b128 v17, v[60:63] offset:52224
	ds_write_b128 v17, v[44:47] offset:60928
	ds_write_b128 v21, v[48:51] offset:17408
	s_waitcnt vmcnt(7)
	ds_write_b128 v21, v[84:87] offset:26112
	ds_write_b128 v22, v[64:67]
	s_waitcnt vmcnt(6)
	ds_write_b128 v23, v[88:91]
	s_waitcnt lgkmcnt(0)
	s_barrier
	ds_read_b128 v[84:87], v20 offset:52224
	ds_read_b128 v[88:91], v19 offset:52224
	ds_read_b128 v[100:103], v19 offset:52288
	ds_read_b128 v[104:107], v20 offset:52288
	ds_read_b128 v[108:111], v20 offset:56576
	v_mfma_f32_16x16x32_bf16 v[36:39], v[76:79], v[56:59], v[36:39]
	v_mfma_f32_16x16x32_bf16 v[24:27], v[80:83], v[56:59], v[24:27]
	ds_read_b128 v[112:115], v20 offset:56640
	ds_read_b128 v[116:119], v20 offset:60928
	s_waitcnt lgkmcnt(5)
	v_mfma_f32_16x16x32_bf16 v[28:31], v[84:87], v[88:91], v[28:31]
	ds_read_b128 v[84:87], v20 offset:60992
	ds_read_b128 v[120:123], v20 offset:65280
	ds_read_b128 v[124:127], v20 offset:65344
	s_waitcnt lgkmcnt(5)
	v_mfma_f32_16x16x32_bf16 v[32:35], v[108:111], v[88:91], v[32:35]
	ds_read_b128 v[108:111], v20 offset:52352
	ds_read_b128 v[128:131], v19 offset:52352
	s_waitcnt lgkmcnt(5)
	v_mfma_f32_16x16x32_bf16 v[36:39], v[116:119], v[88:91], v[36:39]
	ds_read_b128 v[56:59], v19 offset:52416
	ds_read_b128 v[60:63], v20 offset:52416
	s_waitcnt lgkmcnt(5)
	v_mfma_f32_16x16x32_bf16 v[24:27], v[120:123], v[88:91], v[24:27]
	s_waitcnt lgkmcnt(10)
	v_mfma_f32_16x16x32_bf16 v[28:31], v[104:107], v[100:103], v[28:31]
	s_waitcnt lgkmcnt(8)
	v_mfma_f32_16x16x32_bf16 v[32:35], v[112:115], v[100:103], v[32:35]
	s_waitcnt lgkmcnt(6)
	v_mfma_f32_16x16x32_bf16 v[36:39], v[84:87], v[100:103], v[36:39]
	ds_read_b128 v[84:87], v20 offset:56704
	s_waitcnt lgkmcnt(5)
	v_mfma_f32_16x16x32_bf16 v[24:27], v[124:127], v[100:103], v[24:27]
	ds_read_b128 v[64:67], v20 offset:56768
	ds_read_b128 v[88:91], v20 offset:61056
	s_waitcnt lgkmcnt(5)
	v_mfma_f32_16x16x32_bf16 v[28:31], v[108:111], v[128:131], v[28:31]
	ds_read_b128 v[76:79], v20 offset:61120
	ds_read_b128 v[100:103], v20 offset:65408
	ds_read_b128 v[80:83], v20 offset:65472
	s_waitcnt lgkmcnt(5)
	v_mfma_f32_16x16x32_bf16 v[32:35], v[84:87], v[128:131], v[32:35]
	s_waitcnt lgkmcnt(3)
	v_mfma_f32_16x16x32_bf16 v[36:39], v[88:91], v[128:131], v[36:39]
	s_waitcnt lgkmcnt(1)
	v_mfma_f32_16x16x32_bf16 v[24:27], v[100:103], v[128:131], v[24:27]
	s_waitcnt lgkmcnt(1)
	global_load_dwordx4 v[44:47], v[6:7], off offset:1792
	global_load_dwordx4 v[48:51], v[12:13], off offset:1792
	v_mfma_f32_16x16x32_bf16 v[28:31], v[60:63], v[56:59], v[28:31]
	global_load_dwordx4 v[12:15], v[14:15], off offset:1792
	s_nop 0
	global_load_dwordx4 v[4:7], v[4:5], off offset:1792
	s_nop 0
	global_load_dwordx4 v[60:63], v[8:9], off offset:1792
	s_nop 0
	global_load_dwordx4 v[8:11], v[10:11], off offset:1792
	s_waitcnt vmcnt(9)
	ds_write_b128 v17, v[68:71]
	ds_write_b128 v17, v[40:43] offset:8704
	ds_write_b128 v17, v[52:55] offset:17408
	s_waitcnt vmcnt(7)
	ds_write_b128 v17, v[92:95] offset:26112
	ds_write_b128 v17, v[72:75] offset:34816
	s_waitcnt vmcnt(6)
	ds_write_b128 v17, v[96:99] offset:43520
	s_waitcnt lgkmcnt(0)
	s_barrier
	ds_read_b128 v[84:87], v18 offset:34816
	ds_read_b128 v[88:91], v19
	ds_read_b128 v[92:95], v19 offset:64
	ds_read_b128 v[96:99], v18 offset:34880
	ds_read_b128 v[100:103], v18 offset:39168
	v_mfma_f32_16x16x32_bf16 v[32:35], v[64:67], v[56:59], v[32:35]
	v_mfma_f32_16x16x32_bf16 v[36:39], v[76:79], v[56:59], v[36:39]
	v_mfma_f32_16x16x32_bf16 v[24:27], v[80:83], v[56:59], v[24:27]
	ds_read_b128 v[104:107], v18 offset:39232
	ds_read_b128 v[108:111], v18 offset:43520
	s_waitcnt lgkmcnt(5)
	v_mfma_f32_16x16x32_bf16 v[28:31], v[84:87], v[88:91], v[28:31]
	ds_read_b128 v[84:87], v18 offset:43584
	ds_read_b128 v[112:115], v18 offset:47872
	ds_read_b128 v[116:119], v18 offset:47936
	s_waitcnt lgkmcnt(5)
	v_mfma_f32_16x16x32_bf16 v[32:35], v[100:103], v[88:91], v[32:35]
	ds_read_b128 v[100:103], v18 offset:34944
	ds_read_b128 v[52:55], v19 offset:128
	s_waitcnt lgkmcnt(5)
	v_mfma_f32_16x16x32_bf16 v[36:39], v[108:111], v[88:91], v[36:39]
	ds_read_b128 v[56:59], v19 offset:192
	ds_read_b128 v[64:67], v18 offset:35008
	s_waitcnt lgkmcnt(5)
	v_mfma_f32_16x16x32_bf16 v[24:27], v[112:115], v[88:91], v[24:27]
	s_waitcnt lgkmcnt(10)
	v_mfma_f32_16x16x32_bf16 v[28:31], v[96:99], v[92:95], v[28:31]
	s_waitcnt lgkmcnt(8)
	v_mfma_f32_16x16x32_bf16 v[32:35], v[104:107], v[92:95], v[32:35]
	s_waitcnt lgkmcnt(6)
	v_mfma_f32_16x16x32_bf16 v[36:39], v[84:87], v[92:95], v[36:39]
	ds_read_b128 v[84:87], v18 offset:39296
	s_waitcnt lgkmcnt(5)
	v_mfma_f32_16x16x32_bf16 v[24:27], v[116:119], v[92:95], v[24:27]
	ds_read_b128 v[68:71], v18 offset:39360
	ds_read_b128 v[88:91], v18 offset:43648
	s_waitcnt lgkmcnt(5)
	v_mfma_f32_16x16x32_bf16 v[28:31], v[100:103], v[52:55], v[28:31]
	ds_read_b128 v[72:75], v18 offset:43712
	s_waitcnt lgkmcnt(3)
	v_mfma_f32_16x16x32_bf16 v[32:35], v[84:87], v[52:55], v[32:35]
	s_waitcnt lgkmcnt(1)
	v_mfma_f32_16x16x32_bf16 v[36:39], v[88:91], v[52:55], v[36:39]
	s_waitcnt lgkmcnt(1)
	ds_read_b128 v[40:43], v18 offset:48000
	ds_read_b128 v[76:79], v18 offset:48064
	s_waitcnt vmcnt(3)
	ds_write_b128 v17, v[12:15] offset:52224
	ds_write_b128 v17, v[44:47] offset:60928
	ds_write_b128 v21, v[48:51] offset:17408
	s_waitcnt vmcnt(1)
	ds_write_b128 v21, v[60:63] offset:26112
	ds_write_b128 v22, v[4:7]
	s_waitcnt vmcnt(0)
	ds_write_b128 v23, v[8:11]
	s_waitcnt lgkmcnt(0)
	s_barrier
	v_mfma_f32_16x16x32_bf16 v[12:15], v[64:67], v[56:59], v[28:31]
	v_mfma_f32_16x16x32_bf16 v[4:7], v[68:71], v[56:59], v[32:35]
	s_nop 1
	ds_read_b128 v[28:31], v20 offset:52224
	ds_read_b128 v[32:35], v19 offset:52224
	s_waitcnt lgkmcnt(9)
	v_mfma_f32_16x16x32_bf16 v[24:27], v[40:43], v[52:55], v[24:27]
	v_mfma_f32_16x16x32_bf16 v[8:11], v[72:75], v[56:59], v[36:39]
	s_nop 2
	ds_read_b128 v[36:39], v20 offset:56576
	ds_read_b128 v[40:43], v19 offset:52288
	ds_read_b128 v[44:47], v20 offset:52288
	s_waitcnt lgkmcnt(11)
	v_mfma_f32_16x16x32_bf16 v[22:25], v[76:79], v[56:59], v[24:27]
	s_waitcnt lgkmcnt(3)
	v_mfma_f32_16x16x32_bf16 v[12:15], v[28:31], v[32:35], v[12:15]
	s_nop 0
	ds_read_b128 v[26:29], v20 offset:60928
	ds_read_b128 v[48:51], v20 offset:65280
	ds_read_b128 v[52:55], v20 offset:56640
	s_waitcnt lgkmcnt(5)
	v_mfma_f32_16x16x32_bf16 v[4:7], v[36:39], v[32:35], v[4:7]
	ds_read_b128 v[36:39], v20 offset:60992
	ds_read_b128 v[56:59], v20 offset:65344
	s_waitcnt lgkmcnt(4)
	v_mfma_f32_16x16x32_bf16 v[8:11], v[26:29], v[32:35], v[8:11]
	ds_read_b128 v[26:29], v19 offset:52352
	ds_read_b128 v[60:63], v19 offset:52416
	ds_read_b128 v[64:67], v20 offset:52352
	ds_read_b128 v[68:71], v20 offset:52416
	s_waitcnt lgkmcnt(6)
	v_mfma_f32_16x16x32_bf16 v[52:55], v[52:55], v[40:43], v[4:7]
	s_nop 2
	v_or_b32_e32 v4, s5, v16
	v_mfma_f32_16x16x32_bf16 v[12:15], v[44:47], v[40:43], v[12:15]
	v_add_u32_e32 v4, s6, v4
	v_ashrrev_i32_e32 v5, 31, v4
	s_waitcnt lgkmcnt(5)
	v_mfma_f32_16x16x32_bf16 v[6:9], v[36:39], v[40:43], v[8:11]
	s_nop 2
	v_lshlrev_b64 v[10:11], 11, v[4:5]
	v_lshl_add_u64 v[10:11], s[10:11], 0, v[10:11]
	v_mfma_f32_16x16x32_bf16 v[22:25], v[48:51], v[32:35], v[22:25]
	ds_read_b128 v[30:33], v20 offset:56704
	ds_read_b128 v[48:51], v20 offset:56768
	ds_read_b128 v[72:75], v20 offset:61056
	ds_read_b128 v[76:79], v20 offset:61120
	v_lshl_add_u64 v[16:17], v[10:11], 0, s[46:47]
	ds_read_b128 v[44:47], v20 offset:65408
	ds_read_b128 v[18:21], v20 offset:65472
	s_waitcnt lgkmcnt(7)
	v_mfma_f32_16x16x32_bf16 v[10:13], v[64:67], v[26:29], v[12:15]
	s_waitcnt lgkmcnt(0)
	s_barrier
	s_waitcnt lgkmcnt(6)
	v_mfma_f32_16x16x32_bf16 v[10:13], v[68:71], v[60:63], v[10:13]
	v_lshlrev_b32_e32 v14, 3, v2
	v_mov_b32_e32 v15, v3
	v_lshl_add_u64 v[34:35], v[16:17], 0, v[14:15]
	s_waitcnt lgkmcnt(5)
	v_mfma_f32_16x16x32_bf16 v[14:17], v[30:33], v[26:29], v[52:55]
	global_load_dwordx2 v[30:31], v[34:35], off
	s_waitcnt vmcnt(0)
	v_lshlrev_b32_e32 v32, 16, v30
	v_mfma_f32_16x16x32_bf16 v[22:25], v[56:59], v[40:43], v[22:25]
	v_and_b32_e32 v33, 0xffff0000, v30
	v_lshlrev_b32_e32 v30, 16, v31
	v_and_b32_e32 v31, 0xffff0000, v31
	v_pk_add_f32 v[12:13], v[12:13], v[30:31]
	v_pk_add_f32 v[10:11], v[10:11], v[32:33]
	s_waitcnt lgkmcnt(4)
	v_mfma_f32_16x16x32_bf16 v[14:17], v[48:51], v[60:63], v[14:17]
	v_cvt_pk_bf16_f32 v30, v10, v11
	v_cvt_pk_bf16_f32 v31, v12, v13
	global_store_dwordx2 v[34:35], v[30:31], off
	s_waitcnt lgkmcnt(1)
	v_mfma_f32_16x16x32_bf16 v[10:13], v[44:47], v[26:29], v[22:25]
	v_lshlrev_b32_e32 v2, 16, v30
	s_nop 1
	global_load_dwordx2 v[22:23], v[34:35], off offset:32
	v_mfma_f32_16x16x32_bf16 v[6:9], v[72:75], v[26:29], v[6:9]
	s_waitcnt vmcnt(0)
	v_lshlrev_b32_e32 v24, 16, v22
	v_and_b32_e32 v25, 0xffff0000, v22
	v_lshlrev_b32_e32 v22, 16, v23
	v_and_b32_e32 v23, 0xffff0000, v23
	v_pk_add_f32 v[16:17], v[16:17], v[22:23]
	v_pk_add_f32 v[14:15], v[14:15], v[24:25]
	v_mfma_f32_16x16x32_bf16 v[6:9], v[76:79], v[60:63], v[6:9]
	v_cvt_pk_bf16_f32 v14, v14, v15
	v_cvt_pk_bf16_f32 v15, v16, v17
	global_load_dwordx2 v[16:17], v[34:35], off offset:64
	s_waitcnt vmcnt(0)
	v_lshlrev_b32_e32 v22, 16, v16
	v_and_b32_e32 v23, 0xffff0000, v16
	v_lshlrev_b32_e32 v16, 16, v17
	v_and_b32_e32 v17, 0xffff0000, v17
	global_store_dwordx2 v[34:35], v[14:15], off offset:32
	s_nop 0
	v_pk_add_f32 v[8:9], v[8:9], v[16:17]
	v_pk_add_f32 v[6:7], v[6:7], v[22:23]
	s_nop 0
	v_cvt_pk_bf16_f32 v16, v6, v7
	v_cvt_pk_bf16_f32 v17, v8, v9
	global_load_dwordx2 v[22:23], v[34:35], off offset:96
	s_waitcnt lgkmcnt(0)
	v_mfma_f32_16x16x32_bf16 v[6:9], v[18:21], v[60:63], v[10:13]
	global_store_dwordx2 v[34:35], v[16:17], off offset:64
	s_nop 1
	v_and_b32_e32 v10, 0xffff0000, v30
	v_and_b32_e32 v12, 0xffff0000, v31
	v_lshlrev_b32_e32 v11, 16, v31
	v_mul_f32_e32 v10, v10, v10
	v_mul_f32_e32 v12, v12, v12
	v_fmac_f32_e32 v10, v2, v2
	v_fmac_f32_e32 v12, v11, v11
	v_and_b32_e32 v11, 0xffff0000, v14
	v_and_b32_e32 v13, 0xffff0000, v15
	v_add_f32_e32 v2, v10, v12
	v_lshlrev_b32_e32 v10, 16, v14
	v_lshlrev_b32_e32 v12, 16, v15
	v_mul_f32_e32 v11, v11, v11
	v_mul_f32_e32 v13, v13, v13
	v_fmac_f32_e32 v11, v10, v10
	v_fmac_f32_e32 v13, v12, v12
	v_add_f32_e32 v10, v11, v13
	v_and_b32_e32 v11, 0xffff0000, v16
	v_and_b32_e32 v13, 0xffff0000, v17
	v_add_f32_e32 v2, v2, v10
	v_lshlrev_b32_e32 v10, 16, v16
	v_lshlrev_b32_e32 v12, 16, v17
	v_mul_f32_e32 v11, v11, v11
	v_mul_f32_e32 v13, v13, v13
	v_fmac_f32_e32 v11, v10, v10
	v_fmac_f32_e32 v13, v12, v12
	v_add_f32_e32 v10, v11, v13
	v_add_f32_e32 v2, v2, v10
	s_waitcnt vmcnt(1)
	v_lshlrev_b32_e32 v10, 16, v22
	v_and_b32_e32 v11, 0xffff0000, v22
	v_lshlrev_b32_e32 v12, 16, v23
	v_and_b32_e32 v13, 0xffff0000, v23
	v_pk_add_f32 v[8:9], v[8:9], v[12:13]
	v_pk_add_f32 v[6:7], v[6:7], v[10:11]
	s_nop 0
	v_cvt_pk_bf16_f32 v10, v6, v7
	v_cvt_pk_bf16_f32 v11, v8, v9
	global_store_dwordx2 v[34:35], v[10:11], off offset:96
	v_and_b32_e32 v7, 0xffff0000, v10
	v_and_b32_e32 v9, 0xffff0000, v11
	v_lshlrev_b32_e32 v6, 16, v10
	v_lshlrev_b32_e32 v8, 16, v11
	v_mul_f32_e32 v7, v7, v7
	v_mul_f32_e32 v9, v9, v9
	v_fmac_f32_e32 v7, v6, v6
	v_fmac_f32_e32 v9, v8, v8
	v_add_f32_e32 v6, v7, v9
	v_add_f32_e32 v2, v2, v6
	ds_swizzle_b32 v6, v2 offset:swizzle(SWAP,16)
	s_and_saveexec_b64 s[4:5], vcc
	s_cbranch_execz .LBB0_2093
	v_lshl_add_u64 v[4:5], v[4:5], 2, s[2:3]
	s_waitcnt lgkmcnt(0)
	v_add_f32_e32 v1, v2, v6
	global_atomic_add_f32 v[4:5], v1, off

.LBB0_2106:
	s_waitcnt vmcnt(0)
	v_readlane_b32 s28, v255, 8
	s_andn2_b64 vcc, exec, s[16:17]
	v_readlane_b32 s29, v255, 9
	s_barrier
	s_cbranch_vccnz .LBB0_2110
	v_mov_b32_e32 v1, v0
	s_lshl_b32 s5, s34, 3
	v_ashrrev_i32_e32 v2, 31, v1
	v_lshrrev_b32_e32 v2, 28, v2
	v_add_u32_e32 v2, v1, v2
	v_ashrrev_i32_e32 v17, 4, v2
	s_and_b32 s5, s5, 0xffffff80
	v_and_b32_e32 v2, -16, v2
	v_add_u32_e32 v4, s5, v17
	v_sub_u32_e32 v19, v1, v2
	v_ashrrev_i32_e32 v5, 31, v4
	v_lshlrev_b64 v[6:7], 13, v[4:5]
	v_lshlrev_b32_e32 v4, 3, v19
	v_ashrrev_i32_e32 v5, 31, v4
	v_lshlrev_b64 v[10:11], 1, v[4:5]
	v_lshl_add_u64 v[6:7], s[12:13], 0, v[6:7]
	v_lshl_add_u64 v[14:15], v[6:7], 0, v[10:11]
	s_mov_b32 s6, 0x31801000
	s_lshl_b32 s4, s34, 6
	v_add_co_u32_e32 v6, vcc, s6, v14
	s_and_b32 s4, s4, 0x380
	s_nop 0
	v_addc_co_u32_e32 v7, vcc, 0, v15, vcc
	s_mov_b32 s6, 0x31841000
	v_add_u32_e32 v8, s4, v17
	global_load_dwordx4 v[20:23], v[6:7], off
	v_add_co_u32_e32 v6, vcc, s6, v14
	v_ashrrev_i32_e32 v9, 31, v8
	s_nop 0
	v_addc_co_u32_e32 v7, vcc, 0, v15, vcc
	s_mov_b32 s6, 0x31881000
	v_lshlrev_b64 v[8:9], 11, v[8:9]
	v_add_co_u32_e32 v12, vcc, s6, v14
	v_lshl_add_u64 v[8:9], s[14:15], 0, v[8:9]
	s_nop 0
	v_addc_co_u32_e32 v13, vcc, 0, v15, vcc
	s_mov_b32 s6, 0x318c1000
	v_lshl_add_u64 v[4:5], v[8:9], 0, v[10:11]
	v_add_co_u32_e32 v8, vcc, s6, v14
	global_load_dwordx4 v[24:27], v[6:7], off
	global_load_dwordx4 v[28:31], v[12:13], off
	v_addc_co_u32_e32 v9, vcc, 0, v15, vcc
	global_load_dwordx4 v[32:35], v[8:9], off
	global_load_dwordx4 v[36:39], v[4:5], off
	v_add_co_u32_e32 v10, vcc, s63, v4
	s_mov_b64 s[8:9], 0x31801000
	s_nop 0
	v_addc_co_u32_e32 v11, vcc, 0, v5, vcc
	global_load_dwordx4 v[40:43], v[10:11], off
	v_lshl_add_u64 v[14:15], v[14:15], 0, s[8:9]
	global_load_dwordx4 v[44:47], v[4:5], off offset:256
	global_load_dwordx4 v[48:51], v[14:15], off offset:256
	global_load_dwordx4 v[52:55], v[6:7], off offset:256
	global_load_dwordx4 v[56:59], v[12:13], off offset:256
	global_load_dwordx4 v[60:63], v[8:9], off offset:256
	global_load_dwordx4 v[64:67], v[10:11], off offset:256
	v_mul_lo_u32 v17, v17, s81
	v_lshlrev_b32_e32 v19, 4, v19
	v_and_b32_e32 v16, 15, v1
	v_bfe_u32 v2, v1, 4, 2
	v_add3_u32 v17, v17, v19, 0
	v_lshlrev_b32_e32 v68, 4, v2
	v_mul_u32_u24_e32 v18, 0x110, v16
	v_add3_u32 v18, v18, v68, 0
	v_readfirstlane_b32 s6, v1
	s_ashr_i32 s6, s6, 2
	s_add_i32 s5, s5, 0x10000
	v_bfi_b32 v19, -16, s6, v1
	v_mul_lo_u32 v19, v19, s81
	v_add3_u32 v19, v19, v68, 0
	s_and_b32 s6, s6, -16
	s_lshl_b32 s46, s4, 1
	v_and_b32_e32 v1, 16, v1
	v_cmp_eq_u32_e32 vcc, 0, v1
	s_waitcnt vmcnt(7)
	ds_write_b128 v17, v[36:39] offset:34816
	ds_write_b128 v17, v[20:23]
	ds_write_b128 v17, v[24:27] offset:8704
	ds_write_b128 v17, v[28:31] offset:17408
	ds_write_b128 v17, v[32:35] offset:26112
	s_waitcnt vmcnt(6)
	ds_write_b128 v17, v[40:43] offset:43520
	s_waitcnt lgkmcnt(0)
	s_barrier
	ds_read_b128 v[88:91], v18 offset:34816
	ds_read_b128 v[92:95], v19
	ds_read_b128 v[96:99], v19 offset:64
	ds_read_b128 v[100:103], v18 offset:34880
	ds_read_b128 v[104:107], v18 offset:39168
	ds_read_b128 v[108:111], v18 offset:39232
	ds_read_b128 v[112:115], v18 offset:43520
	s_waitcnt lgkmcnt(5)
	v_mfma_f32_16x16x32_bf16 v[20:23], v[88:91], v[92:95], 0
	ds_read_b128 v[88:91], v18 offset:43584
	ds_read_b128 v[116:119], v18 offset:47872
	ds_read_b128 v[120:123], v18 offset:47936
	s_waitcnt lgkmcnt(5)
	v_mfma_f32_16x16x32_bf16 v[36:39], v[104:107], v[92:95], 0
	s_waitcnt lgkmcnt(6)
	v_mfma_f32_16x16x32_bf16 v[20:23], v[100:103], v[96:99], v[20:23]
	ds_read_b128 v[100:103], v18 offset:34944
	s_waitcnt lgkmcnt(5)
	v_mfma_f32_16x16x32_bf16 v[32:35], v[108:111], v[96:99], v[36:39]
	ds_read_b128 v[104:107], v19 offset:128
	s_waitcnt lgkmcnt(5)
	v_mfma_f32_16x16x32_bf16 v[68:71], v[112:115], v[92:95], 0
	s_waitcnt lgkmcnt(3)
	v_mfma_f32_16x16x32_bf16 v[24:27], v[116:119], v[92:95], 0
	s_waitcnt lgkmcnt(4)
	v_mfma_f32_16x16x32_bf16 v[36:39], v[88:91], v[96:99], v[68:71]
	s_nop 2
	ds_read_b128 v[68:71], v19 offset:192
	ds_read_b128 v[72:75], v18 offset:35008
	ds_read_b128 v[88:91], v18 offset:39296
	s_waitcnt lgkmcnt(5)
	v_mfma_f32_16x16x32_bf16 v[24:27], v[120:123], v[96:99], v[24:27]
	ds_read_b128 v[76:79], v18 offset:39360
	ds_read_b128 v[92:95], v18 offset:43648
	s_waitcnt lgkmcnt(5)
	v_mfma_f32_16x16x32_bf16 v[40:43], v[100:103], v[104:107], v[20:23]
	ds_read_b128 v[80:83], v18 offset:43712
	ds_read_b128 v[96:99], v18 offset:48000
	ds_read_b128 v[84:87], v18 offset:48064
	s_waitcnt lgkmcnt(5)
	v_mfma_f32_16x16x32_bf16 v[32:35], v[88:91], v[104:107], v[32:35]
	s_waitcnt lgkmcnt(3)
	v_mfma_f32_16x16x32_bf16 v[36:39], v[92:95], v[104:107], v[36:39]
	s_waitcnt lgkmcnt(1)
	v_mfma_f32_16x16x32_bf16 v[24:27], v[96:99], v[104:107], v[24:27]
	s_waitcnt lgkmcnt(1)
	v_add_u32_e32 v21, 0xcc00, v17
	v_add_u32_e32 v22, 0x15400, v17
	v_add_u32_e32 v23, 0x17600, v17
	v_mfma_f32_16x16x32_bf16 v[28:31], v[72:75], v[68:71], v[40:43]
	s_nop 2
	global_load_dwordx4 v[40:43], v[6:7], off offset:512
	global_load_dwordx4 v[72:75], v[12:13], off offset:512
	v_add_u32_e32 v20, 0x8800, v18
	v_mfma_f32_16x16x32_bf16 v[32:35], v[76:79], v[68:71], v[32:35]
	global_load_dwordx4 v[76:79], v[14:15], off offset:512
	global_load_dwordx4 v[88:91], v[4:5], off offset:512
	global_load_dwordx4 v[92:95], v[8:9], off offset:512
	global_load_dwordx4 v[96:99], v[10:11], off offset:512
	s_waitcnt vmcnt(10)
	ds_write_b128 v17, v[48:51] offset:52224
	s_waitcnt vmcnt(9)
	ds_write_b128 v17, v[52:55] offset:60928
	s_waitcnt vmcnt(8)
	ds_write_b128 v21, v[56:59] offset:17408
	s_waitcnt vmcnt(7)
	ds_write_b128 v21, v[60:63] offset:26112
	ds_write_b128 v22, v[44:47]
	s_waitcnt vmcnt(6)
	ds_write_b128 v23, v[64:67]
	s_waitcnt lgkmcnt(0)
	s_barrier
	ds_read_b128 v[100:103], v20 offset:52224
	ds_read_b128 v[104:107], v19 offset:52224
	ds_read_b128 v[108:111], v19 offset:52288
	ds_read_b128 v[112:115], v20 offset:52288
	ds_read_b128 v[116:119], v20 offset:56576
	ds_read_b128 v[120:123], v20 offset:56640
	ds_read_b128 v[124:127], v20 offset:60928
	s_waitcnt lgkmcnt(5)
	v_mfma_f32_16x16x32_bf16 v[28:31], v[100:103], v[104:107], v[28:31]
	v_mfma_f32_16x16x32_bf16 v[36:39], v[80:83], v[68:71], v[36:39]
	ds_read_b128 v[100:103], v20 offset:60992
	ds_read_b128 v[128:131], v20 offset:65280
	ds_read_b128 v[132:135], v20 offset:65344
	s_waitcnt lgkmcnt(5)
	v_mfma_f32_16x16x32_bf16 v[32:35], v[116:119], v[104:107], v[32:35]
	v_mfma_f32_16x16x32_bf16 v[24:27], v[84:87], v[68:71], v[24:27]
	ds_read_b128 v[116:119], v20 offset:52352
	ds_read_b128 v[136:139], v19 offset:52352
	s_waitcnt lgkmcnt(5)
	v_mfma_f32_16x16x32_bf16 v[36:39], v[124:127], v[104:107], v[36:39]
	ds_read_b128 v[52:55], v19 offset:52416
	ds_read_b128 v[56:59], v20 offset:52416
	s_waitcnt lgkmcnt(5)
	v_mfma_f32_16x16x32_bf16 v[24:27], v[128:131], v[104:107], v[24:27]
	s_waitcnt lgkmcnt(10)
	v_mfma_f32_16x16x32_bf16 v[28:31], v[112:115], v[108:111], v[28:31]
	s_waitcnt lgkmcnt(8)
	v_mfma_f32_16x16x32_bf16 v[32:35], v[120:123], v[108:111], v[32:35]
	s_waitcnt lgkmcnt(6)
	v_mfma_f32_16x16x32_bf16 v[36:39], v[100:103], v[108:111], v[36:39]
	ds_read_b128 v[100:103], v20 offset:56704
	s_waitcnt lgkmcnt(5)
	v_mfma_f32_16x16x32_bf16 v[24:27], v[132:135], v[108:111], v[24:27]
	ds_read_b128 v[60:63], v20 offset:56768
	ds_read_b128 v[104:107], v20 offset:61056
	s_waitcnt lgkmcnt(5)
	v_mfma_f32_16x16x32_bf16 v[28:31], v[116:119], v[136:139], v[28:31]
	ds_read_b128 v[64:67], v20 offset:61120
	ds_read_b128 v[108:111], v20 offset:65408
	ds_read_b128 v[68:71], v20 offset:65472
	s_waitcnt lgkmcnt(5)
	v_mfma_f32_16x16x32_bf16 v[32:35], v[100:103], v[136:139], v[32:35]
	s_waitcnt lgkmcnt(3)
	v_mfma_f32_16x16x32_bf16 v[36:39], v[104:107], v[136:139], v[36:39]
	s_waitcnt lgkmcnt(1)
	v_mfma_f32_16x16x32_bf16 v[24:27], v[108:111], v[136:139], v[24:27]
	s_waitcnt lgkmcnt(1)
	global_load_dwordx4 v[44:47], v[6:7], off offset:768
	global_load_dwordx4 v[48:51], v[12:13], off offset:768
	v_mfma_f32_16x16x32_bf16 v[28:31], v[56:59], v[52:55], v[28:31]
	v_mfma_f32_16x16x32_bf16 v[32:35], v[60:63], v[52:55], v[32:35]
	global_load_dwordx4 v[56:59], v[14:15], off offset:768
	global_load_dwordx4 v[60:63], v[4:5], off offset:768
	global_load_dwordx4 v[80:83], v[8:9], off offset:768
	global_load_dwordx4 v[84:87], v[10:11], off offset:768
	s_waitcnt vmcnt(9)
	ds_write_b128 v17, v[76:79]
	ds_write_b128 v17, v[40:43] offset:8704
	ds_write_b128 v17, v[72:75] offset:17408
	s_waitcnt vmcnt(7)
	ds_write_b128 v17, v[92:95] offset:26112
	ds_write_b128 v17, v[88:91] offset:34816
	s_waitcnt vmcnt(6)
	ds_write_b128 v17, v[96:99] offset:43520
	s_waitcnt lgkmcnt(0)
	s_barrier
	ds_read_b128 v[92:95], v18 offset:34816
	ds_read_b128 v[96:99], v19
	ds_read_b128 v[100:103], v19 offset:64
	ds_read_b128 v[104:107], v18 offset:34880
	ds_read_b128 v[108:111], v18 offset:39168
	v_mfma_f32_16x16x32_bf16 v[36:39], v[64:67], v[52:55], v[36:39]
	v_mfma_f32_16x16x32_bf16 v[24:27], v[68:71], v[52:55], v[24:27]
	ds_read_b128 v[112:115], v18 offset:39232
	ds_read_b128 v[116:119], v18 offset:43520
	s_waitcnt lgkmcnt(5)
	v_mfma_f32_16x16x32_bf16 v[28:31], v[92:95], v[96:99], v[28:31]
	ds_read_b128 v[92:95], v18 offset:43584
	ds_read_b128 v[120:123], v18 offset:47872
	ds_read_b128 v[124:127], v18 offset:47936
	s_waitcnt lgkmcnt(5)
	v_mfma_f32_16x16x32_bf16 v[32:35], v[108:111], v[96:99], v[32:35]
	ds_read_b128 v[108:111], v18 offset:34944
	ds_read_b128 v[128:131], v19 offset:128
	s_waitcnt lgkmcnt(5)
	v_mfma_f32_16x16x32_bf16 v[36:39], v[116:119], v[96:99], v[36:39]
	ds_read_b128 v[64:67], v19 offset:192
	ds_read_b128 v[68:71], v18 offset:35008
	s_waitcnt lgkmcnt(5)
	v_mfma_f32_16x16x32_bf16 v[24:27], v[120:123], v[96:99], v[24:27]
	s_waitcnt lgkmcnt(10)
	v_mfma_f32_16x16x32_bf16 v[28:31], v[104:107], v[100:103], v[28:31]
	s_waitcnt lgkmcnt(8)
	v_mfma_f32_16x16x32_bf16 v[32:35], v[112:115], v[100:103], v[32:35]
	s_waitcnt lgkmcnt(6)
	v_mfma_f32_16x16x32_bf16 v[36:39], v[92:95], v[100:103], v[36:39]
	ds_read_b128 v[92:95], v18 offset:39296
	s_waitcnt lgkmcnt(5)
	v_mfma_f32_16x16x32_bf16 v[24:27], v[124:127], v[100:103], v[24:27]
	ds_read_b128 v[72:75], v18 offset:39360
	ds_read_b128 v[96:99], v18 offset:43648
	s_waitcnt lgkmcnt(5)
	v_mfma_f32_16x16x32_bf16 v[28:31], v[108:111], v[128:131], v[28:31]
	ds_read_b128 v[76:79], v18 offset:43712
	ds_read_b128 v[100:103], v18 offset:48000
	ds_read_b128 v[88:91], v18 offset:48064
	s_waitcnt lgkmcnt(5)
	v_mfma_f32_16x16x32_bf16 v[32:35], v[92:95], v[128:131], v[32:35]
	s_waitcnt lgkmcnt(3)
	v_mfma_f32_16x16x32_bf16 v[36:39], v[96:99], v[128:131], v[36:39]
	s_waitcnt lgkmcnt(1)
	v_mfma_f32_16x16x32_bf16 v[24:27], v[100:103], v[128:131], v[24:27]
	s_waitcnt lgkmcnt(1)
	global_load_dwordx4 v[40:43], v[6:7], off offset:1024
	global_load_dwordx4 v[52:55], v[12:13], off offset:1024
	v_mfma_f32_16x16x32_bf16 v[28:31], v[68:71], v[64:67], v[28:31]
	v_mfma_f32_16x16x32_bf16 v[32:35], v[72:75], v[64:67], v[32:35]
	global_load_dwordx4 v[68:71], v[14:15], off offset:1024
	global_load_dwordx4 v[72:75], v[4:5], off offset:1024
	global_load_dwordx4 v[92:95], v[8:9], off offset:1024
	global_load_dwordx4 v[96:99], v[10:11], off offset:1024
	s_waitcnt vmcnt(9)
	ds_write_b128 v17, v[56:59] offset:52224
	ds_write_b128 v17, v[44:47] offset:60928
	ds_write_b128 v21, v[48:51] offset:17408
	s_waitcnt vmcnt(7)
	ds_write_b128 v21, v[80:83] offset:26112
	ds_write_b128 v22, v[60:63]
	s_waitcnt vmcnt(6)
	ds_write_b128 v23, v[84:87]
	s_waitcnt lgkmcnt(0)
	s_barrier
	ds_read_b128 v[84:87], v20 offset:52224
	ds_read_b128 v[100:103], v19 offset:52224
	ds_read_b128 v[104:107], v19 offset:52288
	ds_read_b128 v[108:111], v20 offset:52288
	ds_read_b128 v[112:115], v20 offset:56576
	v_mfma_f32_16x16x32_bf16 v[36:39], v[76:79], v[64:67], v[36:39]
	v_mfma_f32_16x16x32_bf16 v[24:27], v[88:91], v[64:67], v[24:27]
	ds_read_b128 v[116:119], v20 offset:56640
	ds_read_b128 v[120:123], v20 offset:60928
	s_waitcnt lgkmcnt(5)
	v_mfma_f32_16x16x32_bf16 v[28:31], v[84:87], v[100:103], v[28:31]
	ds_read_b128 v[84:87], v20 offset:60992
	ds_read_b128 v[124:127], v20 offset:65280
	ds_read_b128 v[128:131], v20 offset:65344
	s_waitcnt lgkmcnt(5)
	v_mfma_f32_16x16x32_bf16 v[32:35], v[112:115], v[100:103], v[32:35]
	ds_read_b128 v[112:115], v20 offset:52352
	ds_read_b128 v[132:135], v19 offset:52352
	s_waitcnt lgkmcnt(5)
	v_mfma_f32_16x16x32_bf16 v[36:39], v[120:123], v[100:103], v[36:39]
	ds_read_b128 v[56:59], v19 offset:52416
	ds_read_b128 v[60:63], v20 offset:52416
	s_waitcnt lgkmcnt(5)
	v_mfma_f32_16x16x32_bf16 v[24:27], v[124:127], v[100:103], v[24:27]
	s_waitcnt lgkmcnt(10)
	v_mfma_f32_16x16x32_bf16 v[28:31], v[108:111], v[104:107], v[28:31]
	s_waitcnt lgkmcnt(8)
	v_mfma_f32_16x16x32_bf16 v[32:35], v[116:119], v[104:107], v[32:35]
	s_waitcnt lgkmcnt(6)
	v_mfma_f32_16x16x32_bf16 v[36:39], v[84:87], v[104:107], v[36:39]
	ds_read_b128 v[84:87], v20 offset:56704
	s_waitcnt lgkmcnt(5)
	v_mfma_f32_16x16x32_bf16 v[24:27], v[128:131], v[104:107], v[24:27]
	ds_read_b128 v[64:67], v20 offset:56768
	ds_read_b128 v[100:103], v20 offset:61056
	s_waitcnt lgkmcnt(5)
	v_mfma_f32_16x16x32_bf16 v[28:31], v[112:115], v[132:135], v[28:31]
	ds_read_b128 v[76:79], v20 offset:61120
	ds_read_b128 v[104:107], v20 offset:65408
	ds_read_b128 v[80:83], v20 offset:65472
	s_waitcnt lgkmcnt(5)
	v_mfma_f32_16x16x32_bf16 v[32:35], v[84:87], v[132:135], v[32:35]
	s_waitcnt lgkmcnt(3)
	v_mfma_f32_16x16x32_bf16 v[36:39], v[100:103], v[132:135], v[36:39]
	s_waitcnt lgkmcnt(1)
	v_mfma_f32_16x16x32_bf16 v[24:27], v[104:107], v[132:135], v[24:27]
	s_waitcnt lgkmcnt(1)
	global_load_dwordx4 v[44:47], v[6:7], off offset:1280
	global_load_dwordx4 v[48:51], v[12:13], off offset:1280
	v_mfma_f32_16x16x32_bf16 v[28:31], v[60:63], v[56:59], v[28:31]
	v_mfma_f32_16x16x32_bf16 v[32:35], v[64:67], v[56:59], v[32:35]
	global_load_dwordx4 v[60:63], v[14:15], off offset:1280
	global_load_dwordx4 v[64:67], v[4:5], off offset:1280
	global_load_dwordx4 v[84:87], v[8:9], off offset:1280
	global_load_dwordx4 v[88:91], v[10:11], off offset:1280
	s_waitcnt vmcnt(9)
	ds_write_b128 v17, v[68:71]
	ds_write_b128 v17, v[40:43] offset:8704
	ds_write_b128 v17, v[52:55] offset:17408
	s_waitcnt vmcnt(7)
	ds_write_b128 v17, v[92:95] offset:26112
	ds_write_b128 v17, v[72:75] offset:34816
	s_waitcnt vmcnt(6)
	ds_write_b128 v17, v[96:99] offset:43520
	s_waitcnt lgkmcnt(0)
	s_barrier
	ds_read_b128 v[92:95], v18 offset:34816
	ds_read_b128 v[96:99], v19
	ds_read_b128 v[100:103], v19 offset:64
	ds_read_b128 v[104:107], v18 offset:34880
	ds_read_b128 v[108:111], v18 offset:39168
	v_mfma_f32_16x16x32_bf16 v[36:39], v[76:79], v[56:59], v[36:39]
	v_mfma_f32_16x16x32_bf16 v[24:27], v[80:83], v[56:59], v[24:27]
	ds_read_b128 v[112:115], v18 offset:39232
	ds_read_b128 v[116:119], v18 offset:43520
	s_waitcnt lgkmcnt(5)
	v_mfma_f32_16x16x32_bf16 v[28:31], v[92:95], v[96:99], v[28:31]
	ds_read_b128 v[92:95], v18 offset:43584
	ds_read_b128 v[120:123], v18 offset:47872
	ds_read_b128 v[124:127], v18 offset:47936
	s_waitcnt lgkmcnt(5)
	v_mfma_f32_16x16x32_bf16 v[32:35], v[108:111], v[96:99], v[32:35]
	ds_read_b128 v[108:111], v18 offset:34944
	ds_read_b128 v[128:131], v19 offset:128
	s_waitcnt lgkmcnt(5)
	v_mfma_f32_16x16x32_bf16 v[36:39], v[116:119], v[96:99], v[36:39]
	ds_read_b128 v[56:59], v19 offset:192
	ds_read_b128 v[68:71], v18 offset:35008
	s_waitcnt lgkmcnt(5)
	v_mfma_f32_16x16x32_bf16 v[24:27], v[120:123], v[96:99], v[24:27]
	s_waitcnt lgkmcnt(10)
	v_mfma_f32_16x16x32_bf16 v[28:31], v[104:107], v[100:103], v[28:31]
	s_waitcnt lgkmcnt(8)
	v_mfma_f32_16x16x32_bf16 v[32:35], v[112:115], v[100:103], v[32:35]
	s_waitcnt lgkmcnt(6)
	v_mfma_f32_16x16x32_bf16 v[36:39], v[92:95], v[100:103], v[36:39]
	ds_read_b128 v[92:95], v18 offset:39296
	s_waitcnt lgkmcnt(5)
	v_mfma_f32_16x16x32_bf16 v[24:27], v[124:127], v[100:103], v[24:27]
	ds_read_b128 v[72:75], v18 offset:39360
	ds_read_b128 v[96:99], v18 offset:43648
	s_waitcnt lgkmcnt(5)
	v_mfma_f32_16x16x32_bf16 v[28:31], v[108:111], v[128:131], v[28:31]
	ds_read_b128 v[76:79], v18 offset:43712
	ds_read_b128 v[100:103], v18 offset:48000
	ds_read_b128 v[80:83], v18 offset:48064
	s_waitcnt lgkmcnt(5)
	v_mfma_f32_16x16x32_bf16 v[32:35], v[92:95], v[128:131], v[32:35]
	s_waitcnt lgkmcnt(3)
	v_mfma_f32_16x16x32_bf16 v[36:39], v[96:99], v[128:131], v[36:39]
	s_waitcnt lgkmcnt(1)
	v_mfma_f32_16x16x32_bf16 v[24:27], v[100:103], v[128:131], v[24:27]
	s_waitcnt lgkmcnt(1)
	global_load_dwordx4 v[40:43], v[6:7], off offset:1536
	global_load_dwordx4 v[52:55], v[12:13], off offset:1536
	v_mfma_f32_16x16x32_bf16 v[28:31], v[68:71], v[56:59], v[28:31]
	v_mfma_f32_16x16x32_bf16 v[32:35], v[72:75], v[56:59], v[32:35]
	global_load_dwordx4 v[68:71], v[14:15], off offset:1536
	global_load_dwordx4 v[72:75], v[4:5], off offset:1536
	global_load_dwordx4 v[92:95], v[8:9], off offset:1536
	global_load_dwordx4 v[96:99], v[10:11], off offset:1536
	s_waitcnt vmcnt(9)
	ds_write_b128 v17, v[60:63] offset:52224
	ds_write_b128 v17, v[44:47] offset:60928
	ds_write_b128 v21, v[48:51] offset:17408
	s_waitcnt vmcnt(7)
	ds_write_b128 v21, v[84:87] offset:26112
	ds_write_b128 v22, v[64:67]
	s_waitcnt vmcnt(6)
	ds_write_b128 v23, v[88:91]
	s_waitcnt lgkmcnt(0)
	s_barrier
	ds_read_b128 v[84:87], v20 offset:52224
	ds_read_b128 v[88:91], v19 offset:52224
	ds_read_b128 v[100:103], v19 offset:52288
	ds_read_b128 v[104:107], v20 offset:52288
	ds_read_b128 v[108:111], v20 offset:56576
	v_mfma_f32_16x16x32_bf16 v[36:39], v[76:79], v[56:59], v[36:39]
	v_mfma_f32_16x16x32_bf16 v[24:27], v[80:83], v[56:59], v[24:27]
	ds_read_b128 v[112:115], v20 offset:56640
	ds_read_b128 v[116:119], v20 offset:60928
	s_waitcnt lgkmcnt(5)
	v_mfma_f32_16x16x32_bf16 v[28:31], v[84:87], v[88:91], v[28:31]
	ds_read_b128 v[84:87], v20 offset:60992
	ds_read_b128 v[120:123], v20 offset:65280
	ds_read_b128 v[124:127], v20 offset:65344
	s_waitcnt lgkmcnt(5)
	v_mfma_f32_16x16x32_bf16 v[32:35], v[108:111], v[88:91], v[32:35]
	ds_read_b128 v[108:111], v20 offset:52352
	ds_read_b128 v[128:131], v19 offset:52352
	s_waitcnt lgkmcnt(5)
	v_mfma_f32_16x16x32_bf16 v[36:39], v[116:119], v[88:91], v[36:39]
	ds_read_b128 v[56:59], v19 offset:52416
	ds_read_b128 v[60:63], v20 offset:52416
	s_waitcnt lgkmcnt(5)
	v_mfma_f32_16x16x32_bf16 v[24:27], v[120:123], v[88:91], v[24:27]
	s_waitcnt lgkmcnt(10)
	v_mfma_f32_16x16x32_bf16 v[28:31], v[104:107], v[100:103], v[28:31]
	s_waitcnt lgkmcnt(8)
	v_mfma_f32_16x16x32_bf16 v[32:35], v[112:115], v[100:103], v[32:35]
	s_waitcnt lgkmcnt(6)
	v_mfma_f32_16x16x32_bf16 v[36:39], v[84:87], v[100:103], v[36:39]
	ds_read_b128 v[84:87], v20 offset:56704
	s_waitcnt lgkmcnt(5)
	v_mfma_f32_16x16x32_bf16 v[24:27], v[124:127], v[100:103], v[24:27]
	ds_read_b128 v[64:67], v20 offset:56768
	ds_read_b128 v[88:91], v20 offset:61056
	s_waitcnt lgkmcnt(5)
	v_mfma_f32_16x16x32_bf16 v[28:31], v[108:111], v[128:131], v[28:31]
	ds_read_b128 v[76:79], v20 offset:61120
	ds_read_b128 v[100:103], v20 offset:65408
	ds_read_b128 v[80:83], v20 offset:65472
	s_waitcnt lgkmcnt(5)
	v_mfma_f32_16x16x32_bf16 v[32:35], v[84:87], v[128:131], v[32:35]
	s_waitcnt lgkmcnt(3)
	v_mfma_f32_16x16x32_bf16 v[36:39], v[88:91], v[128:131], v[36:39]
	s_waitcnt lgkmcnt(1)
	v_mfma_f32_16x16x32_bf16 v[24:27], v[100:103], v[128:131], v[24:27]
	s_waitcnt lgkmcnt(1)
	global_load_dwordx4 v[44:47], v[6:7], off offset:1792
	global_load_dwordx4 v[48:51], v[12:13], off offset:1792
	v_mfma_f32_16x16x32_bf16 v[28:31], v[60:63], v[56:59], v[28:31]
	global_load_dwordx4 v[12:15], v[14:15], off offset:1792
	s_nop 0
	global_load_dwordx4 v[4:7], v[4:5], off offset:1792
	s_nop 0
	global_load_dwordx4 v[60:63], v[8:9], off offset:1792
	s_nop 0
	global_load_dwordx4 v[8:11], v[10:11], off offset:1792
	s_waitcnt vmcnt(9)
	ds_write_b128 v17, v[68:71]
	ds_write_b128 v17, v[40:43] offset:8704
	ds_write_b128 v17, v[52:55] offset:17408
	s_waitcnt vmcnt(7)
	ds_write_b128 v17, v[92:95] offset:26112
	ds_write_b128 v17, v[72:75] offset:34816
	s_waitcnt vmcnt(6)
	ds_write_b128 v17, v[96:99] offset:43520
	s_waitcnt lgkmcnt(0)
	s_barrier
	ds_read_b128 v[84:87], v18 offset:34816
	ds_read_b128 v[88:91], v19
	ds_read_b128 v[92:95], v19 offset:64
	ds_read_b128 v[96:99], v18 offset:34880
	ds_read_b128 v[100:103], v18 offset:39168
	v_mfma_f32_16x16x32_bf16 v[32:35], v[64:67], v[56:59], v[32:35]
	v_mfma_f32_16x16x32_bf16 v[36:39], v[76:79], v[56:59], v[36:39]
	v_mfma_f32_16x16x32_bf16 v[24:27], v[80:83], v[56:59], v[24:27]
	ds_read_b128 v[104:107], v18 offset:39232
	ds_read_b128 v[108:111], v18 offset:43520
	s_waitcnt lgkmcnt(5)
	v_mfma_f32_16x16x32_bf16 v[28:31], v[84:87], v[88:91], v[28:31]
	ds_read_b128 v[84:87], v18 offset:43584
	ds_read_b128 v[112:115], v18 offset:47872
	ds_read_b128 v[116:119], v18 offset:47936
	s_waitcnt lgkmcnt(5)
	v_mfma_f32_16x16x32_bf16 v[32:35], v[100:103], v[88:91], v[32:35]
	ds_read_b128 v[100:103], v18 offset:34944
	ds_read_b128 v[52:55], v19 offset:128
	s_waitcnt lgkmcnt(5)
	v_mfma_f32_16x16x32_bf16 v[36:39], v[108:111], v[88:91], v[36:39]
	ds_read_b128 v[56:59], v19 offset:192
	ds_read_b128 v[64:67], v18 offset:35008
	s_waitcnt lgkmcnt(5)
	v_mfma_f32_16x16x32_bf16 v[24:27], v[112:115], v[88:91], v[24:27]
	s_waitcnt lgkmcnt(10)
	v_mfma_f32_16x16x32_bf16 v[28:31], v[96:99], v[92:95], v[28:31]
	s_waitcnt lgkmcnt(8)
	v_mfma_f32_16x16x32_bf16 v[32:35], v[104:107], v[92:95], v[32:35]
	s_waitcnt lgkmcnt(6)
	v_mfma_f32_16x16x32_bf16 v[36:39], v[84:87], v[92:95], v[36:39]
	ds_read_b128 v[84:87], v18 offset:39296
	s_waitcnt lgkmcnt(5)
	v_mfma_f32_16x16x32_bf16 v[24:27], v[116:119], v[92:95], v[24:27]
	ds_read_b128 v[68:71], v18 offset:39360
	ds_read_b128 v[88:91], v18 offset:43648
	s_waitcnt lgkmcnt(5)
	v_mfma_f32_16x16x32_bf16 v[28:31], v[100:103], v[52:55], v[28:31]
	ds_read_b128 v[72:75], v18 offset:43712
	s_waitcnt lgkmcnt(3)
	v_mfma_f32_16x16x32_bf16 v[32:35], v[84:87], v[52:55], v[32:35]
	s_waitcnt lgkmcnt(1)
	v_mfma_f32_16x16x32_bf16 v[36:39], v[88:91], v[52:55], v[36:39]
	s_waitcnt lgkmcnt(1)
	ds_read_b128 v[40:43], v18 offset:48000
	ds_read_b128 v[76:79], v18 offset:48064
	s_waitcnt vmcnt(3)
	ds_write_b128 v17, v[12:15] offset:52224
	ds_write_b128 v17, v[44:47] offset:60928
	ds_write_b128 v21, v[48:51] offset:17408
	s_waitcnt vmcnt(1)
	ds_write_b128 v21, v[60:63] offset:26112
	ds_write_b128 v22, v[4:7]
	s_waitcnt vmcnt(0)
	ds_write_b128 v23, v[8:11]
	s_waitcnt lgkmcnt(0)
	s_barrier
	v_mfma_f32_16x16x32_bf16 v[12:15], v[64:67], v[56:59], v[28:31]
	v_mfma_f32_16x16x32_bf16 v[4:7], v[68:71], v[56:59], v[32:35]
	s_nop 1
	ds_read_b128 v[28:31], v20 offset:52224
	ds_read_b128 v[32:35], v19 offset:52224
	s_waitcnt lgkmcnt(9)
	v_mfma_f32_16x16x32_bf16 v[24:27], v[40:43], v[52:55], v[24:27]
	v_mfma_f32_16x16x32_bf16 v[8:11], v[72:75], v[56:59], v[36:39]
	s_nop 2
	ds_read_b128 v[36:39], v20 offset:56576
	ds_read_b128 v[40:43], v19 offset:52288
	ds_read_b128 v[44:47], v20 offset:52288
	s_waitcnt lgkmcnt(11)
	v_mfma_f32_16x16x32_bf16 v[22:25], v[76:79], v[56:59], v[24:27]
	s_waitcnt lgkmcnt(3)
	v_mfma_f32_16x16x32_bf16 v[12:15], v[28:31], v[32:35], v[12:15]
	s_nop 0
	ds_read_b128 v[26:29], v20 offset:60928
	ds_read_b128 v[48:51], v20 offset:65280
	ds_read_b128 v[52:55], v20 offset:56640
	s_waitcnt lgkmcnt(5)
	v_mfma_f32_16x16x32_bf16 v[4:7], v[36:39], v[32:35], v[4:7]
	ds_read_b128 v[36:39], v20 offset:60992
	ds_read_b128 v[56:59], v20 offset:65344
	s_waitcnt lgkmcnt(4)
	v_mfma_f32_16x16x32_bf16 v[8:11], v[26:29], v[32:35], v[8:11]
	ds_read_b128 v[26:29], v19 offset:52352
	ds_read_b128 v[60:63], v19 offset:52416
	ds_read_b128 v[64:67], v20 offset:52352
	ds_read_b128 v[68:71], v20 offset:52416
	s_waitcnt lgkmcnt(6)
	v_mfma_f32_16x16x32_bf16 v[52:55], v[52:55], v[40:43], v[4:7]
	s_nop 2
	v_or_b32_e32 v4, s5, v16
	v_mfma_f32_16x16x32_bf16 v[12:15], v[44:47], v[40:43], v[12:15]
	v_add_u32_e32 v4, s6, v4
	v_ashrrev_i32_e32 v5, 31, v4
	s_waitcnt lgkmcnt(5)
	v_mfma_f32_16x16x32_bf16 v[6:9], v[36:39], v[40:43], v[8:11]
	s_nop 2
	v_lshlrev_b64 v[10:11], 11, v[4:5]
	v_lshl_add_u64 v[10:11], s[10:11], 0, v[10:11]
	v_mfma_f32_16x16x32_bf16 v[22:25], v[48:51], v[32:35], v[22:25]
	ds_read_b128 v[30:33], v20 offset:56704
	ds_read_b128 v[48:51], v20 offset:56768
	ds_read_b128 v[72:75], v20 offset:61056
	ds_read_b128 v[76:79], v20 offset:61120
	v_lshl_add_u64 v[16:17], v[10:11], 0, s[46:47]
	ds_read_b128 v[44:47], v20 offset:65408
	ds_read_b128 v[18:21], v20 offset:65472
	s_waitcnt lgkmcnt(7)
	v_mfma_f32_16x16x32_bf16 v[10:13], v[64:67], v[26:29], v[12:15]
	s_waitcnt lgkmcnt(0)
	s_barrier
	s_waitcnt lgkmcnt(6)
	v_mfma_f32_16x16x32_bf16 v[10:13], v[68:71], v[60:63], v[10:13]
	v_lshlrev_b32_e32 v14, 3, v2
	v_mov_b32_e32 v15, v3
	v_lshl_add_u64 v[34:35], v[16:17], 0, v[14:15]
	s_waitcnt lgkmcnt(5)
	v_mfma_f32_16x16x32_bf16 v[14:17], v[30:33], v[26:29], v[52:55]
	global_load_dwordx2 v[30:31], v[34:35], off
	s_waitcnt vmcnt(0)
	v_lshlrev_b32_e32 v32, 16, v30
	v_mfma_f32_16x16x32_bf16 v[22:25], v[56:59], v[40:43], v[22:25]
	v_and_b32_e32 v33, 0xffff0000, v30
	v_lshlrev_b32_e32 v30, 16, v31
	v_and_b32_e32 v31, 0xffff0000, v31
	v_pk_add_f32 v[12:13], v[12:13], v[30:31]
	v_pk_add_f32 v[10:11], v[10:11], v[32:33]
	s_waitcnt lgkmcnt(4)
	v_mfma_f32_16x16x32_bf16 v[14:17], v[48:51], v[60:63], v[14:17]
	v_cvt_pk_bf16_f32 v30, v10, v11
	v_cvt_pk_bf16_f32 v31, v12, v13
	global_store_dwordx2 v[34:35], v[30:31], off
	s_waitcnt lgkmcnt(1)
	v_mfma_f32_16x16x32_bf16 v[10:13], v[44:47], v[26:29], v[22:25]
	v_lshlrev_b32_e32 v2, 16, v30
	s_nop 1
	global_load_dwordx2 v[22:23], v[34:35], off offset:32
	v_mfma_f32_16x16x32_bf16 v[6:9], v[72:75], v[26:29], v[6:9]
	s_waitcnt vmcnt(0)
	v_lshlrev_b32_e32 v24, 16, v22
	v_and_b32_e32 v25, 0xffff0000, v22
	v_lshlrev_b32_e32 v22, 16, v23
	v_and_b32_e32 v23, 0xffff0000, v23
	v_pk_add_f32 v[16:17], v[16:17], v[22:23]
	v_pk_add_f32 v[14:15], v[14:15], v[24:25]
	v_mfma_f32_16x16x32_bf16 v[6:9], v[76:79], v[60:63], v[6:9]
	v_cvt_pk_bf16_f32 v14, v14, v15
	v_cvt_pk_bf16_f32 v15, v16, v17
	global_load_dwordx2 v[16:17], v[34:35], off offset:64
	s_waitcnt vmcnt(0)
	v_lshlrev_b32_e32 v22, 16, v16
	v_and_b32_e32 v23, 0xffff0000, v16
	v_lshlrev_b32_e32 v16, 16, v17
	v_and_b32_e32 v17, 0xffff0000, v17
	global_store_dwordx2 v[34:35], v[14:15], off offset:32
	s_nop 0
	v_pk_add_f32 v[8:9], v[8:9], v[16:17]
	v_pk_add_f32 v[6:7], v[6:7], v[22:23]
	s_nop 0
	v_cvt_pk_bf16_f32 v16, v6, v7
	v_cvt_pk_bf16_f32 v17, v8, v9
	global_load_dwordx2 v[22:23], v[34:35], off offset:96
	s_waitcnt lgkmcnt(0)
	v_mfma_f32_16x16x32_bf16 v[6:9], v[18:21], v[60:63], v[10:13]
	global_store_dwordx2 v[34:35], v[16:17], off offset:64
	s_nop 1
	v_and_b32_e32 v10, 0xffff0000, v30
	v_and_b32_e32 v12, 0xffff0000, v31
	v_lshlrev_b32_e32 v11, 16, v31
	v_mul_f32_e32 v10, v10, v10
	v_mul_f32_e32 v12, v12, v12
	v_fmac_f32_e32 v10, v2, v2
	v_fmac_f32_e32 v12, v11, v11
	v_and_b32_e32 v11, 0xffff0000, v14
	v_and_b32_e32 v13, 0xffff0000, v15
	v_add_f32_e32 v2, v10, v12
	v_lshlrev_b32_e32 v10, 16, v14
	v_lshlrev_b32_e32 v12, 16, v15
	v_mul_f32_e32 v11, v11, v11
	v_mul_f32_e32 v13, v13, v13
	v_fmac_f32_e32 v11, v10, v10
	v_fmac_f32_e32 v13, v12, v12
	v_add_f32_e32 v10, v11, v13
	v_and_b32_e32 v11, 0xffff0000, v16
	v_and_b32_e32 v13, 0xffff0000, v17
	v_add_f32_e32 v2, v2, v10
	v_lshlrev_b32_e32 v10, 16, v16
	v_lshlrev_b32_e32 v12, 16, v17
	v_mul_f32_e32 v11, v11, v11
	v_mul_f32_e32 v13, v13, v13
	v_fmac_f32_e32 v11, v10, v10
	v_fmac_f32_e32 v13, v12, v12
	v_add_f32_e32 v10, v11, v13
	v_add_f32_e32 v2, v2, v10
	s_waitcnt vmcnt(1)
	v_lshlrev_b32_e32 v10, 16, v22
	v_and_b32_e32 v11, 0xffff0000, v22
	v_lshlrev_b32_e32 v12, 16, v23
	v_and_b32_e32 v13, 0xffff0000, v23
	v_pk_add_f32 v[8:9], v[8:9], v[12:13]
	v_pk_add_f32 v[6:7], v[6:7], v[10:11]
	s_nop 0
	v_cvt_pk_bf16_f32 v10, v6, v7
	v_cvt_pk_bf16_f32 v11, v8, v9
	global_store_dwordx2 v[34:35], v[10:11], off offset:96
	v_and_b32_e32 v7, 0xffff0000, v10
	v_and_b32_e32 v9, 0xffff0000, v11
	v_lshlrev_b32_e32 v6, 16, v10
	v_lshlrev_b32_e32 v8, 16, v11
	v_mul_f32_e32 v7, v7, v7
	v_mul_f32_e32 v9, v9, v9
	v_fmac_f32_e32 v7, v6, v6
	v_fmac_f32_e32 v9, v8, v8
	v_add_f32_e32 v6, v7, v9
	v_add_f32_e32 v2, v2, v6
	ds_swizzle_b32 v6, v2 offset:swizzle(SWAP,16)
	s_and_saveexec_b64 s[4:5], vcc
	s_cbranch_execz .LBB0_2109
	v_lshl_add_u64 v[4:5], v[4:5], 2, s[2:3]
	s_waitcnt lgkmcnt(0)
	v_add_f32_e32 v1, v2, v6
	global_atomic_add_f32 v[4:5], v1, off

.LBB0_2181:
	s_mov_b32 s30, s47
	s_load_dwordx2 s[6:7], s[28:29], s30 offset:0xd8
	v_readlane_b32 s2, v255, 43
	s_add_i32 s30, s30, s62
	s_mul_i32 s2, s2, 0x1a00000
	v_readlane_b32 s3, v255, 44
	s_waitcnt lgkmcnt(0)
	s_add_u32 s2, s6, s2
	s_addc_u32 s3, s7, 0
	s_add_u32 s8, s2, 0xa00000
	s_addc_u32 s9, s3, 0
	s_add_u32 s0, s6, s0
	s_addc_u32 s1, s7, s1
	s_add_u32 s2, s0, 0x100000
	s_addc_u32 s3, s1, 0
	s_add_u32 s0, s6, 0x11800000
	s_addc_u32 s1, s7, 0
	s_bitcmp0_b32 s30, 0
	s_cselect_b64 s[10:11], -1, 0
	v_mov_b32_e32 v1, v0
	s_and_b64 vcc, exec, s[10:11]
	s_cbranch_vccnz .LBB0_2183
	v_mov_b32_e32 v66, v0
	s_lshl_b32 s4, s30, 6
	v_ashrrev_i32_e32 v1, 31, v66
	v_lshrrev_b32_e32 v1, 28, v1
	s_and_b32 s12, s4, 0x3c0
	v_add_u32_e32 v1, v66, v1
	s_lshl_b32 s4, s30, 3
	v_ashrrev_i32_e32 v16, 4, v1
	s_and_b32 s4, s4, 0xffffff80
	v_and_b32_e32 v1, -16, v1
	v_add_u32_e32 v4, s4, v16
	v_sub_u32_e32 v42, v66, v1
	v_ashrrev_i32_e32 v5, 31, v4
	v_lshlrev_b64 v[6:7], 11, v[4:5]
	v_lshlrev_b32_e32 v4, 3, v42
	v_ashrrev_i32_e32 v5, 31, v4
	v_add_u32_e32 v8, s12, v16
	v_lshlrev_b64 v[10:11], 1, v[4:5]
	v_lshl_add_u64 v[6:7], s[6:7], 0, v[6:7]
	v_ashrrev_i32_e32 v9, 31, v8
	v_lshl_add_u64 v[14:15], v[6:7], 0, v[10:11]
	v_lshlrev_b64 v[8:9], 11, v[8:9]
	v_add_co_u32_e32 v6, vcc, s74, v14
	v_lshl_add_u64 v[8:9], s[8:9], 0, v[8:9]
	s_nop 0
	v_addc_co_u32_e32 v7, vcc, 0, v15, vcc
	s_mov_b32 s5, 0x11410000
	v_lshl_add_u64 v[4:5], v[8:9], 0, v[10:11]
	v_add_co_u32_e32 v10, vcc, s5, v14
	s_mov_b32 s5, 0x11430000
	s_nop 0
	v_addc_co_u32_e32 v11, vcc, 0, v15, vcc
	v_add_co_u32_e32 v12, vcc, s75, v14
	global_load_dwordx4 v[18:21], v[6:7], off
	global_load_dwordx4 v[22:25], v[10:11], off
	v_addc_co_u32_e32 v13, vcc, 0, v15, vcc
	v_add_co_u32_e32 v6, vcc, s5, v14
	global_load_dwordx4 v[26:29], v[12:13], off
	s_nop 0
	v_addc_co_u32_e32 v7, vcc, 0, v15, vcc
	global_load_dwordx4 v[30:33], v[6:7], off
	global_load_dwordx4 v[34:37], v[4:5], off
	v_add_co_u32_e32 v8, vcc, s63, v4
	v_mul_lo_u32 v16, v16, s81
	s_nop 0
	v_addc_co_u32_e32 v9, vcc, 0, v5, vcc
	global_load_dwordx4 v[38:41], v[8:9], off
	v_lshlrev_b32_e32 v42, 4, v42
	v_add3_u32 v16, v16, v42, 0
	v_lshl_add_u64 v[14:15], v[14:15], 0, s[72:73]
	global_load_dwordx4 v[42:45], v[4:5], off offset:256
	global_load_dwordx4 v[46:49], v[14:15], off offset:256
	global_load_dwordx4 v[50:53], v[10:11], off offset:256
	global_load_dwordx4 v[54:57], v[12:13], off offset:256
	global_load_dwordx4 v[58:61], v[6:7], off offset:256
	global_load_dwordx4 v[62:65], v[8:9], off offset:256
	v_and_b32_e32 v2, 15, v66
	v_bfe_u32 v1, v66, 4, 2
	v_lshlrev_b32_e32 v67, 4, v1
	v_mul_u32_u24_e32 v17, 0x110, v2
	v_add3_u32 v17, v17, v67, 0
	v_readfirstlane_b32 s5, v66
	s_ashr_i32 s5, s5, 2
	s_add_i32 s4, s4, 0x10000
	v_or_b32_e32 v2, s4, v2
	s_lshl_b32 s46, s12, 1
	s_waitcnt vmcnt(7)
	ds_write_b128 v16, v[34:37] offset:34816
	ds_write_b128 v16, v[18:21]
	ds_write_b128 v16, v[22:25] offset:8704
	ds_write_b128 v16, v[26:29] offset:17408
	ds_write_b128 v16, v[30:33] offset:26112
	s_waitcnt vmcnt(6)
	ds_write_b128 v16, v[38:41] offset:43520
	s_waitcnt lgkmcnt(0)
	s_barrier
	ds_read_b128 v[20:23], v17 offset:34816
	v_bfi_b32 v18, -16, s5, v66
	v_mul_lo_u32 v18, v18, s81
	v_add3_u32 v18, v18, v67, 0
	ds_read_b128 v[24:27], v18
	ds_read_b128 v[28:31], v18 offset:64
	ds_read_b128 v[32:35], v17 offset:34880
	ds_read_b128 v[36:39], v17 offset:39168
	ds_read_b128 v[66:69], v17 offset:39232
	s_waitcnt lgkmcnt(4)
	v_mfma_f32_16x16x32_bf16 v[20:23], v[20:23], v[24:27], 0
	ds_read_b128 v[70:73], v17 offset:43520
	ds_read_b128 v[74:77], v17 offset:43584
	ds_read_b128 v[78:81], v17 offset:47872
	ds_read_b128 v[82:85], v17 offset:47936
	v_add_u32_e32 v19, 0x8800, v17
	s_waitcnt lgkmcnt(5)
	v_mfma_f32_16x16x32_bf16 v[36:39], v[36:39], v[24:27], 0
	s_and_b32 s5, s5, -16
	v_mfma_f32_16x16x32_bf16 v[20:23], v[32:35], v[28:31], v[20:23]
	s_waitcnt lgkmcnt(4)
	v_mfma_f32_16x16x32_bf16 v[32:35], v[66:69], v[28:31], v[36:39]
	s_waitcnt lgkmcnt(0)
	ds_read_b128 v[90:93], v17 offset:34944
	ds_read_b128 v[94:97], v18 offset:128
	v_mfma_f32_16x16x32_bf16 v[70:73], v[70:73], v[24:27], 0
	v_mfma_f32_16x16x32_bf16 v[24:27], v[78:81], v[24:27], 0
	v_mfma_f32_16x16x32_bf16 v[36:39], v[74:77], v[28:31], v[70:73]
	s_nop 2
	ds_read_b128 v[70:73], v18 offset:192
	ds_read_b128 v[74:77], v17 offset:35008
	ds_read_b128 v[98:101], v17 offset:39296
	v_mfma_f32_16x16x32_bf16 v[24:27], v[82:85], v[28:31], v[24:27]
	ds_read_b128 v[78:81], v17 offset:39360
	ds_read_b128 v[102:105], v17 offset:43648
	s_waitcnt lgkmcnt(5)
	v_mfma_f32_16x16x32_bf16 v[66:69], v[90:93], v[94:97], v[20:23]
	ds_read_b128 v[82:85], v17 offset:43712
	ds_read_b128 v[90:93], v17 offset:48000
	ds_read_b128 v[86:89], v17 offset:48064
	s_waitcnt lgkmcnt(5)
	v_mfma_f32_16x16x32_bf16 v[32:35], v[98:101], v[94:97], v[32:35]
	s_waitcnt lgkmcnt(3)
	v_mfma_f32_16x16x32_bf16 v[36:39], v[102:105], v[94:97], v[36:39]
	s_waitcnt lgkmcnt(1)
	v_mfma_f32_16x16x32_bf16 v[24:27], v[90:93], v[94:97], v[24:27]
	s_waitcnt lgkmcnt(1)
	v_add_u32_e32 v20, 0xcc00, v16
	v_add_u32_e32 v22, 0x15400, v16
	v_add_u32_e32 v21, 0x17600, v16
	v_mfma_f32_16x16x32_bf16 v[28:31], v[74:77], v[70:73], v[66:69]
	s_nop 2
	global_load_dwordx4 v[66:69], v[10:11], off offset:512
	global_load_dwordx4 v[74:77], v[12:13], off offset:512
	v_mfma_f32_16x16x32_bf16 v[32:35], v[78:81], v[70:73], v[32:35]
	global_load_dwordx4 v[78:81], v[14:15], off offset:512
	global_load_dwordx4 v[90:93], v[4:5], off offset:512
	global_load_dwordx4 v[94:97], v[6:7], off offset:512
	global_load_dwordx4 v[98:101], v[8:9], off offset:512
	s_waitcnt vmcnt(10)
	ds_write_b128 v16, v[46:49] offset:52224
	s_waitcnt vmcnt(9)
	ds_write_b128 v16, v[50:53] offset:60928
	s_waitcnt vmcnt(8)
	ds_write_b128 v20, v[54:57] offset:17408
	s_waitcnt vmcnt(7)
	ds_write_b128 v20, v[58:61] offset:26112
	ds_write_b128 v22, v[42:45]
	s_waitcnt vmcnt(6)
	ds_write_b128 v21, v[62:65]
	s_waitcnt lgkmcnt(0)
	s_barrier
	ds_read_b128 v[102:105], v19 offset:52224
	ds_read_b128 v[106:109], v18 offset:52224
	ds_read_b128 v[110:113], v18 offset:52288
	ds_read_b128 v[114:117], v19 offset:52288
	ds_read_b128 v[118:121], v19 offset:56576
	ds_read_b128 v[122:125], v19 offset:56640
	ds_read_b128 v[126:129], v19 offset:60928
	s_waitcnt lgkmcnt(5)
	v_mfma_f32_16x16x32_bf16 v[28:31], v[102:105], v[106:109], v[28:31]
	v_mfma_f32_16x16x32_bf16 v[36:39], v[82:85], v[70:73], v[36:39]
	ds_read_b128 v[102:105], v19 offset:60992
	ds_read_b128 v[130:133], v19 offset:65280
	ds_read_b128 v[134:137], v19 offset:65344
	s_waitcnt lgkmcnt(5)
	v_mfma_f32_16x16x32_bf16 v[32:35], v[118:121], v[106:109], v[32:35]
	v_mfma_f32_16x16x32_bf16 v[24:27], v[86:89], v[70:73], v[24:27]
	ds_read_b128 v[118:121], v19 offset:52352
	ds_read_b128 v[138:141], v18 offset:52352
	s_waitcnt lgkmcnt(5)
	v_mfma_f32_16x16x32_bf16 v[36:39], v[126:129], v[106:109], v[36:39]
	ds_read_b128 v[48:51], v18 offset:52416
	ds_read_b128 v[52:55], v19 offset:52416
	s_waitcnt lgkmcnt(5)
	v_mfma_f32_16x16x32_bf16 v[24:27], v[130:133], v[106:109], v[24:27]
	s_waitcnt lgkmcnt(10)
	v_mfma_f32_16x16x32_bf16 v[28:31], v[114:117], v[110:113], v[28:31]
	s_waitcnt lgkmcnt(8)
	v_mfma_f32_16x16x32_bf16 v[32:35], v[122:125], v[110:113], v[32:35]
	s_waitcnt lgkmcnt(6)
	v_mfma_f32_16x16x32_bf16 v[36:39], v[102:105], v[110:113], v[36:39]
	ds_read_b128 v[102:105], v19 offset:56704
	s_waitcnt lgkmcnt(5)
	v_mfma_f32_16x16x32_bf16 v[24:27], v[134:137], v[110:113], v[24:27]
	ds_read_b128 v[56:59], v19 offset:56768
	ds_read_b128 v[106:109], v19 offset:61056
	s_waitcnt lgkmcnt(5)
	v_mfma_f32_16x16x32_bf16 v[28:31], v[118:121], v[138:141], v[28:31]
	ds_read_b128 v[60:63], v19 offset:61120
	ds_read_b128 v[110:113], v19 offset:65408
	ds_read_b128 v[70:73], v19 offset:65472
	s_waitcnt lgkmcnt(5)
	v_mfma_f32_16x16x32_bf16 v[32:35], v[102:105], v[138:141], v[32:35]
	s_waitcnt lgkmcnt(3)
	v_mfma_f32_16x16x32_bf16 v[36:39], v[106:109], v[138:141], v[36:39]
	s_waitcnt lgkmcnt(1)
	v_mfma_f32_16x16x32_bf16 v[24:27], v[110:113], v[138:141], v[24:27]
	s_waitcnt lgkmcnt(1)
	global_load_dwordx4 v[40:43], v[10:11], off offset:768
	global_load_dwordx4 v[44:47], v[12:13], off offset:768
	v_mfma_f32_16x16x32_bf16 v[28:31], v[52:55], v[48:51], v[28:31]
	v_mfma_f32_16x16x32_bf16 v[32:35], v[56:59], v[48:51], v[32:35]
	global_load_dwordx4 v[52:55], v[14:15], off offset:768
	global_load_dwordx4 v[56:59], v[4:5], off offset:768
	global_load_dwordx4 v[82:85], v[6:7], off offset:768
	global_load_dwordx4 v[86:89], v[8:9], off offset:768
	s_waitcnt vmcnt(9)
	ds_write_b128 v16, v[78:81]
	ds_write_b128 v16, v[66:69] offset:8704
	ds_write_b128 v16, v[74:77] offset:17408
	s_waitcnt vmcnt(7)
	ds_write_b128 v16, v[94:97] offset:26112
	ds_write_b128 v16, v[90:93] offset:34816
	s_waitcnt vmcnt(6)
	ds_write_b128 v16, v[98:101] offset:43520
	s_waitcnt lgkmcnt(0)
	s_barrier
	v_mfma_f32_16x16x32_bf16 v[36:39], v[60:63], v[48:51], v[36:39]
	ds_read_b128 v[94:97], v17 offset:34816
	ds_read_b128 v[98:101], v18
	ds_read_b128 v[102:105], v18 offset:64
	ds_read_b128 v[106:109], v17 offset:34880
	ds_read_b128 v[110:113], v17 offset:39168
	v_mfma_f32_16x16x32_bf16 v[24:27], v[70:73], v[48:51], v[24:27]
	ds_read_b128 v[114:117], v17 offset:39232
	ds_read_b128 v[118:121], v17 offset:43520
	s_waitcnt lgkmcnt(5)
	v_mfma_f32_16x16x32_bf16 v[28:31], v[94:97], v[98:101], v[28:31]
	ds_read_b128 v[94:97], v17 offset:43584
	ds_read_b128 v[122:125], v17 offset:47872
	ds_read_b128 v[126:129], v17 offset:47936
	s_waitcnt lgkmcnt(5)
	v_mfma_f32_16x16x32_bf16 v[32:35], v[110:113], v[98:101], v[32:35]
	ds_read_b128 v[110:113], v17 offset:34944
	ds_read_b128 v[130:133], v18 offset:128
	s_waitcnt lgkmcnt(5)
	v_mfma_f32_16x16x32_bf16 v[36:39], v[118:121], v[98:101], v[36:39]
	ds_read_b128 v[64:67], v18 offset:192
	ds_read_b128 v[68:71], v17 offset:35008
	s_waitcnt lgkmcnt(5)
	v_mfma_f32_16x16x32_bf16 v[24:27], v[122:125], v[98:101], v[24:27]
	s_waitcnt lgkmcnt(10)
	v_mfma_f32_16x16x32_bf16 v[28:31], v[106:109], v[102:105], v[28:31]
	s_waitcnt lgkmcnt(8)
	v_mfma_f32_16x16x32_bf16 v[32:35], v[114:117], v[102:105], v[32:35]
	s_waitcnt lgkmcnt(6)
	v_mfma_f32_16x16x32_bf16 v[36:39], v[94:97], v[102:105], v[36:39]
	ds_read_b128 v[94:97], v17 offset:39296
	s_waitcnt lgkmcnt(5)
	v_mfma_f32_16x16x32_bf16 v[24:27], v[126:129], v[102:105], v[24:27]
	ds_read_b128 v[72:75], v17 offset:39360
	ds_read_b128 v[98:101], v17 offset:43648
	s_waitcnt lgkmcnt(5)
	v_mfma_f32_16x16x32_bf16 v[28:31], v[110:113], v[130:133], v[28:31]
	ds_read_b128 v[76:79], v17 offset:43712
	ds_read_b128 v[102:105], v17 offset:48000
	ds_read_b128 v[90:93], v17 offset:48064
	s_waitcnt lgkmcnt(5)
	v_mfma_f32_16x16x32_bf16 v[32:35], v[94:97], v[130:133], v[32:35]
	s_waitcnt lgkmcnt(3)
	v_mfma_f32_16x16x32_bf16 v[36:39], v[98:101], v[130:133], v[36:39]
	s_waitcnt lgkmcnt(1)
	v_mfma_f32_16x16x32_bf16 v[24:27], v[102:105], v[130:133], v[24:27]
	s_waitcnt lgkmcnt(1)
	global_load_dwordx4 v[48:51], v[10:11], off offset:1024
	global_load_dwordx4 v[60:63], v[12:13], off offset:1024
	v_mfma_f32_16x16x32_bf16 v[28:31], v[68:71], v[64:67], v[28:31]
	v_mfma_f32_16x16x32_bf16 v[32:35], v[72:75], v[64:67], v[32:35]
	global_load_dwordx4 v[68:71], v[14:15], off offset:1024
	global_load_dwordx4 v[72:75], v[4:5], off offset:1024
	global_load_dwordx4 v[94:97], v[6:7], off offset:1024
	global_load_dwordx4 v[98:101], v[8:9], off offset:1024
	s_waitcnt vmcnt(9)
	ds_write_b128 v16, v[52:55] offset:52224
	ds_write_b128 v16, v[40:43] offset:60928
	ds_write_b128 v20, v[44:47] offset:17408
	s_waitcnt vmcnt(7)
	ds_write_b128 v20, v[82:85] offset:26112
	ds_write_b128 v22, v[56:59]
	s_waitcnt vmcnt(6)
	ds_write_b128 v21, v[86:89]
	s_waitcnt lgkmcnt(0)
	s_barrier
	ds_read_b128 v[84:87], v19 offset:52224
	ds_read_b128 v[102:105], v18 offset:52224
	ds_read_b128 v[106:109], v18 offset:52288
	ds_read_b128 v[110:113], v19 offset:52288
	ds_read_b128 v[114:117], v19 offset:56576
	v_mfma_f32_16x16x32_bf16 v[36:39], v[76:79], v[64:67], v[36:39]
	v_mfma_f32_16x16x32_bf16 v[24:27], v[90:93], v[64:67], v[24:27]
	ds_read_b128 v[118:121], v19 offset:56640
	ds_read_b128 v[122:125], v19 offset:60928
	s_waitcnt lgkmcnt(5)
	v_mfma_f32_16x16x32_bf16 v[28:31], v[84:87], v[102:105], v[28:31]
	ds_read_b128 v[84:87], v19 offset:60992
	ds_read_b128 v[126:129], v19 offset:65280
	ds_read_b128 v[130:133], v19 offset:65344
	s_waitcnt lgkmcnt(5)
	v_mfma_f32_16x16x32_bf16 v[32:35], v[114:117], v[102:105], v[32:35]
	ds_read_b128 v[114:117], v19 offset:52352
	ds_read_b128 v[134:137], v18 offset:52352
	s_waitcnt lgkmcnt(5)
	v_mfma_f32_16x16x32_bf16 v[36:39], v[122:125], v[102:105], v[36:39]
	ds_read_b128 v[52:55], v18 offset:52416
	ds_read_b128 v[56:59], v19 offset:52416
	s_waitcnt lgkmcnt(5)
	v_mfma_f32_16x16x32_bf16 v[24:27], v[126:129], v[102:105], v[24:27]
	s_waitcnt lgkmcnt(10)
	v_mfma_f32_16x16x32_bf16 v[28:31], v[110:113], v[106:109], v[28:31]
	s_waitcnt lgkmcnt(8)
	v_mfma_f32_16x16x32_bf16 v[32:35], v[118:121], v[106:109], v[32:35]
	s_waitcnt lgkmcnt(6)
	v_mfma_f32_16x16x32_bf16 v[36:39], v[84:87], v[106:109], v[36:39]
	ds_read_b128 v[84:87], v19 offset:56704
	s_waitcnt lgkmcnt(5)
	v_mfma_f32_16x16x32_bf16 v[24:27], v[130:133], v[106:109], v[24:27]
	ds_read_b128 v[64:67], v19 offset:56768
	ds_read_b128 v[102:105], v19 offset:61056
	s_waitcnt lgkmcnt(5)
	v_mfma_f32_16x16x32_bf16 v[28:31], v[114:117], v[134:137], v[28:31]
	ds_read_b128 v[76:79], v19 offset:61120
	ds_read_b128 v[106:109], v19 offset:65408
	ds_read_b128 v[80:83], v19 offset:65472
	s_waitcnt lgkmcnt(5)
	v_mfma_f32_16x16x32_bf16 v[32:35], v[84:87], v[134:137], v[32:35]
	s_waitcnt lgkmcnt(3)
	v_mfma_f32_16x16x32_bf16 v[36:39], v[102:105], v[134:137], v[36:39]
	s_waitcnt lgkmcnt(1)
	v_mfma_f32_16x16x32_bf16 v[24:27], v[106:109], v[134:137], v[24:27]
	s_waitcnt lgkmcnt(1)
	global_load_dwordx4 v[40:43], v[10:11], off offset:1280
	global_load_dwordx4 v[44:47], v[12:13], off offset:1280
	v_mfma_f32_16x16x32_bf16 v[28:31], v[56:59], v[52:55], v[28:31]
	v_mfma_f32_16x16x32_bf16 v[32:35], v[64:67], v[52:55], v[32:35]
	global_load_dwordx4 v[56:59], v[14:15], off offset:1280
	global_load_dwordx4 v[64:67], v[4:5], off offset:1280
	global_load_dwordx4 v[84:87], v[6:7], off offset:1280
	global_load_dwordx4 v[88:91], v[8:9], off offset:1280
	s_waitcnt vmcnt(9)
	ds_write_b128 v16, v[68:71]
	ds_write_b128 v16, v[48:51] offset:8704
	ds_write_b128 v16, v[60:63] offset:17408
	s_waitcnt vmcnt(7)
	ds_write_b128 v16, v[94:97] offset:26112
	ds_write_b128 v16, v[72:75] offset:34816
	s_waitcnt vmcnt(6)
	ds_write_b128 v16, v[98:101] offset:43520
	s_waitcnt lgkmcnt(0)
	s_barrier
	ds_read_b128 v[92:95], v17 offset:34816
	ds_read_b128 v[96:99], v18
	ds_read_b128 v[100:103], v18 offset:64
	ds_read_b128 v[104:107], v17 offset:34880
	ds_read_b128 v[108:111], v17 offset:39168
	v_mfma_f32_16x16x32_bf16 v[36:39], v[76:79], v[52:55], v[36:39]
	v_mfma_f32_16x16x32_bf16 v[24:27], v[80:83], v[52:55], v[24:27]
	ds_read_b128 v[112:115], v17 offset:39232
	ds_read_b128 v[116:119], v17 offset:43520
	s_waitcnt lgkmcnt(5)
	v_mfma_f32_16x16x32_bf16 v[28:31], v[92:95], v[96:99], v[28:31]
	ds_read_b128 v[92:95], v17 offset:43584
	ds_read_b128 v[120:123], v17 offset:47872
	ds_read_b128 v[124:127], v17 offset:47936
	s_waitcnt lgkmcnt(5)
	v_mfma_f32_16x16x32_bf16 v[32:35], v[108:111], v[96:99], v[32:35]
	ds_read_b128 v[108:111], v17 offset:34944
	ds_read_b128 v[128:131], v18 offset:128
	s_waitcnt lgkmcnt(5)
	v_mfma_f32_16x16x32_bf16 v[36:39], v[116:119], v[96:99], v[36:39]
	ds_read_b128 v[60:63], v18 offset:192
	ds_read_b128 v[68:71], v17 offset:35008
	s_waitcnt lgkmcnt(5)
	v_mfma_f32_16x16x32_bf16 v[24:27], v[120:123], v[96:99], v[24:27]
	s_waitcnt lgkmcnt(10)
	v_mfma_f32_16x16x32_bf16 v[28:31], v[104:107], v[100:103], v[28:31]
	s_waitcnt lgkmcnt(8)
	v_mfma_f32_16x16x32_bf16 v[32:35], v[112:115], v[100:103], v[32:35]
	s_waitcnt lgkmcnt(6)
	v_mfma_f32_16x16x32_bf16 v[36:39], v[92:95], v[100:103], v[36:39]
	ds_read_b128 v[92:95], v17 offset:39296
	s_waitcnt lgkmcnt(5)
	v_mfma_f32_16x16x32_bf16 v[24:27], v[124:127], v[100:103], v[24:27]
	ds_read_b128 v[72:75], v17 offset:39360
	ds_read_b128 v[96:99], v17 offset:43648
	s_waitcnt lgkmcnt(5)
	v_mfma_f32_16x16x32_bf16 v[28:31], v[108:111], v[128:131], v[28:31]
	ds_read_b128 v[76:79], v17 offset:43712
	ds_read_b128 v[100:103], v17 offset:48000
	ds_read_b128 v[80:83], v17 offset:48064
	s_waitcnt lgkmcnt(5)
	v_mfma_f32_16x16x32_bf16 v[32:35], v[92:95], v[128:131], v[32:35]
	s_waitcnt lgkmcnt(3)
	v_mfma_f32_16x16x32_bf16 v[36:39], v[96:99], v[128:131], v[36:39]
	s_waitcnt lgkmcnt(1)
	v_mfma_f32_16x16x32_bf16 v[24:27], v[100:103], v[128:131], v[24:27]
	s_waitcnt lgkmcnt(1)
	global_load_dwordx4 v[48:51], v[10:11], off offset:1536
	global_load_dwordx4 v[52:55], v[12:13], off offset:1536
	v_mfma_f32_16x16x32_bf16 v[28:31], v[68:71], v[60:63], v[28:31]
	v_mfma_f32_16x16x32_bf16 v[32:35], v[72:75], v[60:63], v[32:35]
	global_load_dwordx4 v[68:71], v[14:15], off offset:1536
	global_load_dwordx4 v[72:75], v[4:5], off offset:1536
	global_load_dwordx4 v[92:95], v[6:7], off offset:1536
	global_load_dwordx4 v[96:99], v[8:9], off offset:1536
	s_waitcnt vmcnt(9)
	ds_write_b128 v16, v[56:59] offset:52224
	ds_write_b128 v16, v[40:43] offset:60928
	ds_write_b128 v20, v[44:47] offset:17408
	s_waitcnt vmcnt(7)
	ds_write_b128 v20, v[84:87] offset:26112
	ds_write_b128 v22, v[64:67]
	s_waitcnt vmcnt(6)
	ds_write_b128 v21, v[88:91]
	s_waitcnt lgkmcnt(0)
	s_barrier
	ds_read_b128 v[84:87], v19 offset:52224
	ds_read_b128 v[88:91], v18 offset:52224
	ds_read_b128 v[100:103], v18 offset:52288
	ds_read_b128 v[104:107], v19 offset:52288
	ds_read_b128 v[108:111], v19 offset:56576
	v_mfma_f32_16x16x32_bf16 v[36:39], v[76:79], v[60:63], v[36:39]
	v_mfma_f32_16x16x32_bf16 v[24:27], v[80:83], v[60:63], v[24:27]
	ds_read_b128 v[112:115], v19 offset:56640
	ds_read_b128 v[116:119], v19 offset:60928
	s_waitcnt lgkmcnt(5)
	v_mfma_f32_16x16x32_bf16 v[28:31], v[84:87], v[88:91], v[28:31]
	ds_read_b128 v[84:87], v19 offset:60992
	ds_read_b128 v[120:123], v19 offset:65280
	ds_read_b128 v[124:127], v19 offset:65344
	s_waitcnt lgkmcnt(5)
	v_mfma_f32_16x16x32_bf16 v[32:35], v[108:111], v[88:91], v[32:35]
	ds_read_b128 v[108:111], v19 offset:52352
	ds_read_b128 v[128:131], v18 offset:52352
	s_waitcnt lgkmcnt(5)
	v_mfma_f32_16x16x32_bf16 v[36:39], v[116:119], v[88:91], v[36:39]
	ds_read_b128 v[56:59], v18 offset:52416
	ds_read_b128 v[60:63], v19 offset:52416
	s_waitcnt lgkmcnt(5)
	v_mfma_f32_16x16x32_bf16 v[24:27], v[120:123], v[88:91], v[24:27]
	s_waitcnt lgkmcnt(10)
	v_mfma_f32_16x16x32_bf16 v[28:31], v[104:107], v[100:103], v[28:31]
	s_waitcnt lgkmcnt(8)
	v_mfma_f32_16x16x32_bf16 v[32:35], v[112:115], v[100:103], v[32:35]
	s_waitcnt lgkmcnt(6)
	v_mfma_f32_16x16x32_bf16 v[36:39], v[84:87], v[100:103], v[36:39]
	ds_read_b128 v[84:87], v19 offset:56704
	s_waitcnt lgkmcnt(5)
	v_mfma_f32_16x16x32_bf16 v[24:27], v[124:127], v[100:103], v[24:27]
	ds_read_b128 v[64:67], v19 offset:56768
	ds_read_b128 v[88:91], v19 offset:61056
	s_waitcnt lgkmcnt(5)
	v_mfma_f32_16x16x32_bf16 v[28:31], v[108:111], v[128:131], v[28:31]
	ds_read_b128 v[76:79], v19 offset:61120
	ds_read_b128 v[100:103], v19 offset:65408
	ds_read_b128 v[80:83], v19 offset:65472
	s_waitcnt lgkmcnt(5)
	v_mfma_f32_16x16x32_bf16 v[32:35], v[84:87], v[128:131], v[32:35]
	s_waitcnt lgkmcnt(3)
	v_mfma_f32_16x16x32_bf16 v[36:39], v[88:91], v[128:131], v[36:39]
	s_waitcnt lgkmcnt(1)
	v_mfma_f32_16x16x32_bf16 v[24:27], v[100:103], v[128:131], v[24:27]
	s_waitcnt lgkmcnt(1)
	global_load_dwordx4 v[40:43], v[10:11], off offset:1792
	s_nop 0
	global_load_dwordx4 v[10:13], v[12:13], off offset:1792
	v_mfma_f32_16x16x32_bf16 v[28:31], v[60:63], v[56:59], v[28:31]
	v_mfma_f32_16x16x32_bf16 v[32:35], v[64:67], v[56:59], v[32:35]
	global_load_dwordx4 v[44:47], v[14:15], off offset:1792
	global_load_dwordx4 v[60:63], v[4:5], off offset:1792
	s_nop 0
	global_load_dwordx4 v[4:7], v[6:7], off offset:1792
	s_nop 0
	global_load_dwordx4 v[64:67], v[8:9], off offset:1792
	s_waitcnt vmcnt(9)
	ds_write_b128 v16, v[68:71]
	ds_write_b128 v16, v[48:51] offset:8704
	ds_write_b128 v16, v[52:55] offset:17408
	s_waitcnt vmcnt(7)
	ds_write_b128 v16, v[92:95] offset:26112
	ds_write_b128 v16, v[72:75] offset:34816
	s_waitcnt vmcnt(6)
	ds_write_b128 v16, v[96:99] offset:43520
	s_waitcnt lgkmcnt(0)
	s_barrier
	ds_read_b128 v[84:87], v17 offset:34816
	ds_read_b128 v[88:91], v18
	ds_read_b128 v[92:95], v18 offset:64
	ds_read_b128 v[96:99], v17 offset:34880
	ds_read_b128 v[100:103], v17 offset:39168
	v_mfma_f32_16x16x32_bf16 v[36:39], v[76:79], v[56:59], v[36:39]
	v_mfma_f32_16x16x32_bf16 v[24:27], v[80:83], v[56:59], v[24:27]
	ds_read_b128 v[104:107], v17 offset:39232
	ds_read_b128 v[108:111], v17 offset:43520
	s_waitcnt lgkmcnt(5)
	v_mfma_f32_16x16x32_bf16 v[28:31], v[84:87], v[88:91], v[28:31]
	ds_read_b128 v[84:87], v17 offset:43584
	ds_read_b128 v[112:115], v17 offset:47872
	ds_read_b128 v[116:119], v17 offset:47936
	s_waitcnt lgkmcnt(5)
	v_mfma_f32_16x16x32_bf16 v[32:35], v[100:103], v[88:91], v[32:35]
	ds_read_b128 v[100:103], v17 offset:34944
	ds_read_b128 v[120:123], v17 offset:39296
	s_waitcnt lgkmcnt(5)
	v_mfma_f32_16x16x32_bf16 v[36:39], v[108:111], v[88:91], v[36:39]
	ds_read_b128 v[56:59], v18 offset:128
	ds_read_b128 v[68:71], v18 offset:192
	s_waitcnt lgkmcnt(5)
	v_mfma_f32_16x16x32_bf16 v[24:27], v[112:115], v[88:91], v[24:27]
	s_waitcnt lgkmcnt(10)
	v_mfma_f32_16x16x32_bf16 v[28:31], v[96:99], v[92:95], v[28:31]
	s_waitcnt lgkmcnt(8)
	v_mfma_f32_16x16x32_bf16 v[32:35], v[104:107], v[92:95], v[32:35]
	s_waitcnt lgkmcnt(6)
	v_mfma_f32_16x16x32_bf16 v[36:39], v[84:87], v[92:95], v[36:39]
	ds_read_b128 v[72:75], v17 offset:35008
	s_waitcnt lgkmcnt(5)
	v_mfma_f32_16x16x32_bf16 v[24:27], v[116:119], v[92:95], v[24:27]
	ds_read_b128 v[84:87], v17 offset:43648
	ds_read_b128 v[76:79], v17 offset:39360
	ds_read_b128 v[80:83], v17 offset:43712
	s_waitcnt lgkmcnt(5)
	v_mfma_f32_16x16x32_bf16 v[28:31], v[100:103], v[56:59], v[28:31]
	s_waitcnt lgkmcnt(5)
	v_mfma_f32_16x16x32_bf16 v[32:35], v[120:123], v[56:59], v[32:35]
	ds_read_b128 v[52:55], v17 offset:48000
	s_waitcnt lgkmcnt(3)
	v_mfma_f32_16x16x32_bf16 v[36:39], v[84:87], v[56:59], v[36:39]
	s_waitcnt lgkmcnt(3)
	ds_read_b128 v[48:51], v17 offset:48064
	s_waitcnt vmcnt(3)
	ds_write_b128 v16, v[44:47] offset:52224
	ds_write_b128 v16, v[40:43] offset:60928
	ds_write_b128 v20, v[10:13] offset:17408
	s_waitcnt vmcnt(1)
	ds_write_b128 v20, v[4:7] offset:26112
	ds_write_b128 v22, v[60:63]
	s_waitcnt vmcnt(0)
	ds_write_b128 v21, v[64:67]
	s_waitcnt lgkmcnt(0)
	s_barrier
	s_waitcnt lgkmcnt(7)
	v_mfma_f32_16x16x32_bf16 v[14:17], v[52:55], v[56:59], v[24:27]
	ds_read_b128 v[20:23], v18 offset:52224
	s_nop 1
	ds_read_b128 v[24:27], v18 offset:52288
	v_mfma_f32_16x16x32_bf16 v[4:7], v[72:75], v[68:71], v[28:31]
	v_mfma_f32_16x16x32_bf16 v[8:11], v[76:79], v[68:71], v[32:35]
	v_mfma_f32_16x16x32_bf16 v[28:31], v[80:83], v[68:71], v[36:39]
	s_nop 1
	ds_read_b128 v[32:35], v19 offset:52224
	ds_read_b128 v[36:39], v19 offset:52288
	ds_read_b128 v[40:43], v19 offset:56576
	ds_read_b128 v[44:47], v19 offset:56640
	s_waitcnt lgkmcnt(3)
	v_mfma_f32_16x16x32_bf16 v[4:7], v[32:35], v[20:23], v[4:7]
	v_mfma_f32_16x16x32_bf16 v[12:15], v[48:51], v[68:71], v[14:17]
	ds_read_b128 v[48:51], v19 offset:60928
	ds_read_b128 v[52:55], v19 offset:60992
	ds_read_b128 v[56:59], v19 offset:65280
	ds_read_b128 v[60:63], v19 offset:65344
	ds_read_b128 v[32:35], v18 offset:52352
	ds_read_b128 v[64:67], v18 offset:52416
	ds_read_b128 v[68:71], v19 offset:52352
	ds_read_b128 v[72:75], v19 offset:52416
	s_waitcnt lgkmcnt(10)
	v_mfma_f32_16x16x32_bf16 v[4:7], v[36:39], v[24:27], v[4:7]
	v_add_u32_e32 v36, s5, v2
	v_ashrrev_i32_e32 v37, 31, v36
	s_waitcnt lgkmcnt(9)
	v_mfma_f32_16x16x32_bf16 v[8:11], v[40:43], v[20:23], v[8:11]
	ds_read_b128 v[40:43], v19 offset:56704
	ds_read_b128 v[76:79], v19 offset:56768
	ds_read_b128 v[80:83], v19 offset:61056
	ds_read_b128 v[84:87], v19 offset:61120
	s_waitcnt lgkmcnt(11)
	v_mfma_f32_16x16x32_bf16 v[28:31], v[48:51], v[20:23], v[28:31]
	ds_read_b128 v[48:51], v19 offset:65408
	ds_read_b128 v[16:19], v19 offset:65472
	s_waitcnt lgkmcnt(0)
	s_barrier
	s_waitcnt lgkmcnt(11)
	v_mfma_f32_16x16x32_bf16 v[12:15], v[56:59], v[20:23], v[12:15]
	v_lshl_add_u64 v[20:21], v[36:37], 2, s[2:3]
	global_load_dword v2, v[20:21], off
	v_mfma_f32_16x16x32_bf16 v[20:23], v[52:55], v[24:27], v[28:31]
	s_waitcnt vmcnt(0)
	v_fmamk_f32 v2, v2, 0x3a800000, v208
	s_nop 0
	v_mul_f32_e32 v28, 0x4f800000, v2
	v_cmp_gt_f32_e32 vcc, s90, v2
	v_mfma_f32_16x16x32_bf16 v[8:11], v[44:47], v[24:27], v[8:11]
	s_nop 0
	v_cndmask_b32_e32 v2, v2, v28, vcc
	s_waitcnt lgkmcnt(10)
	v_mfma_f32_16x16x32_bf16 v[12:15], v[60:63], v[24:27], v[12:15]
	v_sqrt_f32_e32 v24, v2
	s_nop 0
	v_add_u32_e32 v25, -1, v24
	v_fma_f32 v26, -v25, v24, v2
	v_cmp_ge_f32_e64 s[4:5], 0, v26
	v_add_u32_e32 v26, 1, v24
	s_waitcnt lgkmcnt(7)
	v_mfma_f32_16x16x32_bf16 v[4:7], v[68:71], v[32:35], v[4:7]
	v_cndmask_b32_e64 v25, v24, v25, s[4:5]
	v_fma_f32 v24, -v26, v24, v2
	v_cmp_lt_f32_e64 s[4:5], 0, v24
	s_waitcnt lgkmcnt(5)
	v_mfma_f32_16x16x32_bf16 v[8:11], v[40:43], v[32:35], v[8:11]
	v_cndmask_b32_e64 v24, v25, v26, s[4:5]
	v_mul_f32_e32 v25, 0x37800000, v24
	v_cndmask_b32_e32 v24, v24, v25, vcc
	v_cmp_class_f32_e32 vcc, v2, v209
	v_mfma_f32_16x16x32_bf16 v[4:7], v[72:75], v[64:67], v[4:7]
	s_nop 0
	v_cndmask_b32_e32 v2, v24, v2, vcc
	v_div_scale_f32 v24, s[4:5], v2, v2, 1.0
	v_rcp_f32_e32 v25, v24
	s_waitcnt lgkmcnt(3)
	v_mfma_f32_16x16x32_bf16 v[20:23], v[80:83], v[32:35], v[20:23]
	v_fma_f32 v26, -v24, v25, 1.0
	v_fmac_f32_e32 v25, v26, v25
	v_div_scale_f32 v26, vcc, 1.0, v2, 1.0
	v_mul_f32_e32 v27, v26, v25
	v_fma_f32 v28, -v24, v27, v26
	v_fmac_f32_e32 v27, v28, v25
	v_fma_f32 v24, -v24, v27, v26
	v_div_fmas_f32 v24, v24, v25, v27
	v_div_fixup_f32 v2, v24, v2, 1.0
	s_waitcnt lgkmcnt(1)
	v_mfma_f32_16x16x32_bf16 v[12:15], v[48:51], v[32:35], v[12:15]
	v_mul_f32_e32 v2, 0x3db8aa3b, v2
	v_pk_mul_f32 v[6:7], v[6:7], v[2:3] op_sel_hi:[1,0]
	v_pk_mul_f32 v[4:5], v[4:5], v[2:3] op_sel_hi:[1,0]
	v_mfma_f32_16x16x32_bf16 v[8:11], v[76:79], v[64:67], v[8:11]
	v_cvt_pk_bf16_f32 v4, v4, v5
	v_cvt_pk_bf16_f32 v5, v6, v7
	v_lshlrev_b64 v[6:7], 13, v[36:37]
	v_mfma_f32_16x16x32_bf16 v[20:23], v[84:87], v[64:67], v[20:23]
	v_lshl_add_u64 v[6:7], s[0:1], 0, v[6:7]
	v_lshl_add_u64 v[6:7], v[6:7], 0, s[46:47]
	s_nop 3
	v_pk_mul_f32 v[8:9], v[8:9], v[2:3] op_sel_hi:[1,0]
	s_waitcnt lgkmcnt(0)
	v_mfma_f32_16x16x32_bf16 v[12:15], v[16:19], v[64:67], v[12:15]
	v_lshlrev_b32_e32 v16, 3, v1
	v_mov_b32_e32 v17, v3
	v_lshl_add_u64 v[6:7], v[6:7], 0, v[16:17]
	global_store_dwordx2 v[6:7], v[4:5], off
	v_pk_mul_f32 v[4:5], v[10:11], v[2:3] op_sel_hi:[1,0]
	v_cvt_pk_bf16_f32 v8, v8, v9
	s_nop 0
	v_cvt_pk_bf16_f32 v9, v4, v5
	global_store_dwordx2 v[6:7], v[8:9], off offset:32
	v_pk_mul_f32 v[8:9], v[20:21], v[2:3] op_sel_hi:[1,0]
	v_pk_mul_f32 v[4:5], v[22:23], v[2:3] op_sel_hi:[1,0]
	v_cvt_pk_bf16_f32 v8, v8, v9
	s_nop 0
	v_cvt_pk_bf16_f32 v9, v4, v5
	global_store_dwordx2 v[6:7], v[8:9], off offset:64
	v_pk_mul_f32 v[8:9], v[12:13], v[2:3] op_sel_hi:[1,0]
	v_pk_mul_f32 v[4:5], v[14:15], v[2:3] op_sel_hi:[1,0]
	v_cvt_pk_bf16_f32 v8, v8, v9
	s_nop 0
	v_cvt_pk_bf16_f32 v9, v4, v5
	global_store_dwordx2 v[6:7], v[8:9], off offset:96

.LBB0_2195:
	s_waitcnt vmcnt(0)
	s_andn2_b64 vcc, exec, s[10:11]
	s_barrier
	s_cbranch_vccnz .LBB0_2197
	v_mov_b32_e32 v66, v0
	s_lshl_b32 s4, s30, 6
	v_ashrrev_i32_e32 v1, 31, v66
	v_lshrrev_b32_e32 v1, 28, v1
	s_and_b32 s10, s4, 0x380
	v_add_u32_e32 v1, v66, v1
	s_lshl_b32 s4, s30, 3
	v_ashrrev_i32_e32 v16, 4, v1
	s_and_b32 s4, s4, 0xffffff80
	v_and_b32_e32 v1, -16, v1
	v_add_u32_e32 v4, s4, v16
	v_sub_u32_e32 v42, v66, v1
	v_ashrrev_i32_e32 v5, 31, v4
	v_lshlrev_b64 v[6:7], 11, v[4:5]
	v_lshlrev_b32_e32 v4, 3, v42
	v_ashrrev_i32_e32 v5, 31, v4
	v_add_u32_e32 v8, s10, v16
	v_lshlrev_b64 v[10:11], 1, v[4:5]
	v_lshl_add_u64 v[6:7], s[6:7], 0, v[6:7]
	v_ashrrev_i32_e32 v9, 31, v8
	v_lshl_add_u64 v[14:15], v[6:7], 0, v[10:11]
	v_lshlrev_b64 v[8:9], 11, v[8:9]
	v_add_co_u32_e32 v6, vcc, s74, v14
	v_lshl_add_u64 v[8:9], s[8:9], 0, v[8:9]
	s_nop 0
	v_addc_co_u32_e32 v7, vcc, 0, v15, vcc
	s_mov_b32 s5, 0x11410000
	v_lshl_add_u64 v[4:5], v[8:9], 0, v[10:11]
	v_add_co_u32_e32 v10, vcc, s5, v14
	s_mov_b32 s5, 0x11430000
	s_nop 0
	v_addc_co_u32_e32 v11, vcc, 0, v15, vcc
	v_add_co_u32_e32 v12, vcc, s75, v14
	global_load_dwordx4 v[18:21], v[6:7], off
	global_load_dwordx4 v[22:25], v[10:11], off
	v_addc_co_u32_e32 v13, vcc, 0, v15, vcc
	v_add_co_u32_e32 v6, vcc, s5, v14
	global_load_dwordx4 v[26:29], v[12:13], off
	s_nop 0
	v_addc_co_u32_e32 v7, vcc, 0, v15, vcc
	global_load_dwordx4 v[30:33], v[6:7], off
	global_load_dwordx4 v[34:37], v[4:5], off
	v_add_co_u32_e32 v8, vcc, s63, v4
	v_mul_lo_u32 v16, v16, s81
	s_nop 0
	v_addc_co_u32_e32 v9, vcc, 0, v5, vcc
	global_load_dwordx4 v[38:41], v[8:9], off
	v_lshlrev_b32_e32 v42, 4, v42
	v_add3_u32 v16, v16, v42, 0
	v_lshl_add_u64 v[14:15], v[14:15], 0, s[72:73]
	global_load_dwordx4 v[42:45], v[4:5], off offset:256
	global_load_dwordx4 v[46:49], v[14:15], off offset:256
	global_load_dwordx4 v[50:53], v[10:11], off offset:256
	global_load_dwordx4 v[54:57], v[12:13], off offset:256
	global_load_dwordx4 v[58:61], v[6:7], off offset:256
	global_load_dwordx4 v[62:65], v[8:9], off offset:256
	v_and_b32_e32 v2, 15, v66
	v_bfe_u32 v1, v66, 4, 2
	v_lshlrev_b32_e32 v67, 4, v1
	v_mul_u32_u24_e32 v17, 0x110, v2
	v_add3_u32 v17, v17, v67, 0
	v_readfirstlane_b32 s5, v66
	s_ashr_i32 s5, s5, 2
	s_add_i32 s4, s4, 0x10000
	v_or_b32_e32 v2, s4, v2
	s_lshl_b32 s46, s10, 1
	s_waitcnt vmcnt(7)
	ds_write_b128 v16, v[34:37] offset:34816
	ds_write_b128 v16, v[18:21]
	ds_write_b128 v16, v[22:25] offset:8704
	ds_write_b128 v16, v[26:29] offset:17408
	ds_write_b128 v16, v[30:33] offset:26112
	s_waitcnt vmcnt(6)
	ds_write_b128 v16, v[38:41] offset:43520
	s_waitcnt lgkmcnt(0)
	s_barrier
	ds_read_b128 v[20:23], v17 offset:34816
	v_bfi_b32 v18, -16, s5, v66
	v_mul_lo_u32 v18, v18, s81
	v_add3_u32 v18, v18, v67, 0
	ds_read_b128 v[24:27], v18
	ds_read_b128 v[28:31], v18 offset:64
	ds_read_b128 v[32:35], v17 offset:34880
	ds_read_b128 v[36:39], v17 offset:39168
	ds_read_b128 v[66:69], v17 offset:39232
	s_waitcnt lgkmcnt(4)
	v_mfma_f32_16x16x32_bf16 v[20:23], v[20:23], v[24:27], 0
	ds_read_b128 v[70:73], v17 offset:43520
	ds_read_b128 v[74:77], v17 offset:43584
	ds_read_b128 v[78:81], v17 offset:47872
	ds_read_b128 v[82:85], v17 offset:47936
	v_add_u32_e32 v19, 0x8800, v17
	s_waitcnt lgkmcnt(5)
	v_mfma_f32_16x16x32_bf16 v[36:39], v[36:39], v[24:27], 0
	s_and_b32 s5, s5, -16
	v_mfma_f32_16x16x32_bf16 v[20:23], v[32:35], v[28:31], v[20:23]
	s_waitcnt lgkmcnt(4)
	v_mfma_f32_16x16x32_bf16 v[32:35], v[66:69], v[28:31], v[36:39]
	s_waitcnt lgkmcnt(0)
	ds_read_b128 v[90:93], v17 offset:34944
	ds_read_b128 v[94:97], v18 offset:128
	v_mfma_f32_16x16x32_bf16 v[70:73], v[70:73], v[24:27], 0
	v_mfma_f32_16x16x32_bf16 v[24:27], v[78:81], v[24:27], 0
	v_mfma_f32_16x16x32_bf16 v[36:39], v[74:77], v[28:31], v[70:73]
	s_nop 2
	ds_read_b128 v[70:73], v18 offset:192
	ds_read_b128 v[74:77], v17 offset:35008
	ds_read_b128 v[98:101], v17 offset:39296
	v_mfma_f32_16x16x32_bf16 v[24:27], v[82:85], v[28:31], v[24:27]
	ds_read_b128 v[78:81], v17 offset:39360
	ds_read_b128 v[102:105], v17 offset:43648
	s_waitcnt lgkmcnt(5)
	v_mfma_f32_16x16x32_bf16 v[66:69], v[90:93], v[94:97], v[20:23]
	ds_read_b128 v[82:85], v17 offset:43712
	ds_read_b128 v[90:93], v17 offset:48000
	ds_read_b128 v[86:89], v17 offset:48064
	s_waitcnt lgkmcnt(5)
	v_mfma_f32_16x16x32_bf16 v[32:35], v[98:101], v[94:97], v[32:35]
	s_waitcnt lgkmcnt(3)
	v_mfma_f32_16x16x32_bf16 v[36:39], v[102:105], v[94:97], v[36:39]
	s_waitcnt lgkmcnt(1)
	v_mfma_f32_16x16x32_bf16 v[24:27], v[90:93], v[94:97], v[24:27]
	s_waitcnt lgkmcnt(1)
	v_add_u32_e32 v20, 0xcc00, v16
	v_add_u32_e32 v22, 0x15400, v16
	v_add_u32_e32 v21, 0x17600, v16
	v_mfma_f32_16x16x32_bf16 v[28:31], v[74:77], v[70:73], v[66:69]
	s_nop 2
	global_load_dwordx4 v[66:69], v[10:11], off offset:512
	global_load_dwordx4 v[74:77], v[12:13], off offset:512
	v_mfma_f32_16x16x32_bf16 v[32:35], v[78:81], v[70:73], v[32:35]
	global_load_dwordx4 v[78:81], v[14:15], off offset:512
	global_load_dwordx4 v[90:93], v[4:5], off offset:512
	global_load_dwordx4 v[94:97], v[6:7], off offset:512
	global_load_dwordx4 v[98:101], v[8:9], off offset:512
	s_waitcnt vmcnt(10)
	ds_write_b128 v16, v[46:49] offset:52224
	s_waitcnt vmcnt(9)
	ds_write_b128 v16, v[50:53] offset:60928
	s_waitcnt vmcnt(8)
	ds_write_b128 v20, v[54:57] offset:17408
	s_waitcnt vmcnt(7)
	ds_write_b128 v20, v[58:61] offset:26112
	ds_write_b128 v22, v[42:45]
	s_waitcnt vmcnt(6)
	ds_write_b128 v21, v[62:65]
	s_waitcnt lgkmcnt(0)
	s_barrier
	ds_read_b128 v[102:105], v19 offset:52224
	ds_read_b128 v[106:109], v18 offset:52224
	ds_read_b128 v[110:113], v18 offset:52288
	ds_read_b128 v[114:117], v19 offset:52288
	ds_read_b128 v[118:121], v19 offset:56576
	ds_read_b128 v[122:125], v19 offset:56640
	ds_read_b128 v[126:129], v19 offset:60928
	s_waitcnt lgkmcnt(5)
	v_mfma_f32_16x16x32_bf16 v[28:31], v[102:105], v[106:109], v[28:31]
	v_mfma_f32_16x16x32_bf16 v[36:39], v[82:85], v[70:73], v[36:39]
	ds_read_b128 v[102:105], v19 offset:60992
	ds_read_b128 v[130:133], v19 offset:65280
	ds_read_b128 v[134:137], v19 offset:65344
	s_waitcnt lgkmcnt(5)
	v_mfma_f32_16x16x32_bf16 v[32:35], v[118:121], v[106:109], v[32:35]
	v_mfma_f32_16x16x32_bf16 v[24:27], v[86:89], v[70:73], v[24:27]
	ds_read_b128 v[118:121], v19 offset:52352
	ds_read_b128 v[138:141], v18 offset:52352
	s_waitcnt lgkmcnt(5)
	v_mfma_f32_16x16x32_bf16 v[36:39], v[126:129], v[106:109], v[36:39]
	ds_read_b128 v[48:51], v18 offset:52416
	ds_read_b128 v[52:55], v19 offset:52416
	s_waitcnt lgkmcnt(5)
	v_mfma_f32_16x16x32_bf16 v[24:27], v[130:133], v[106:109], v[24:27]
	s_waitcnt lgkmcnt(10)
	v_mfma_f32_16x16x32_bf16 v[28:31], v[114:117], v[110:113], v[28:31]
	s_waitcnt lgkmcnt(8)
	v_mfma_f32_16x16x32_bf16 v[32:35], v[122:125], v[110:113], v[32:35]
	s_waitcnt lgkmcnt(6)
	v_mfma_f32_16x16x32_bf16 v[36:39], v[102:105], v[110:113], v[36:39]
	ds_read_b128 v[102:105], v19 offset:56704
	s_waitcnt lgkmcnt(5)
	v_mfma_f32_16x16x32_bf16 v[24:27], v[134:137], v[110:113], v[24:27]
	ds_read_b128 v[56:59], v19 offset:56768
	ds_read_b128 v[106:109], v19 offset:61056
	s_waitcnt lgkmcnt(5)
	v_mfma_f32_16x16x32_bf16 v[28:31], v[118:121], v[138:141], v[28:31]
	ds_read_b128 v[60:63], v19 offset:61120
	ds_read_b128 v[110:113], v19 offset:65408
	ds_read_b128 v[70:73], v19 offset:65472
	s_waitcnt lgkmcnt(5)
	v_mfma_f32_16x16x32_bf16 v[32:35], v[102:105], v[138:141], v[32:35]
	s_waitcnt lgkmcnt(3)
	v_mfma_f32_16x16x32_bf16 v[36:39], v[106:109], v[138:141], v[36:39]
	s_waitcnt lgkmcnt(1)
	v_mfma_f32_16x16x32_bf16 v[24:27], v[110:113], v[138:141], v[24:27]
	s_waitcnt lgkmcnt(1)
	global_load_dwordx4 v[40:43], v[10:11], off offset:768
	global_load_dwordx4 v[44:47], v[12:13], off offset:768
	v_mfma_f32_16x16x32_bf16 v[28:31], v[52:55], v[48:51], v[28:31]
	v_mfma_f32_16x16x32_bf16 v[32:35], v[56:59], v[48:51], v[32:35]
	global_load_dwordx4 v[52:55], v[14:15], off offset:768
	global_load_dwordx4 v[56:59], v[4:5], off offset:768
	global_load_dwordx4 v[82:85], v[6:7], off offset:768
	global_load_dwordx4 v[86:89], v[8:9], off offset:768
	s_waitcnt vmcnt(9)
	ds_write_b128 v16, v[78:81]
	ds_write_b128 v16, v[66:69] offset:8704
	ds_write_b128 v16, v[74:77] offset:17408
	s_waitcnt vmcnt(7)
	ds_write_b128 v16, v[94:97] offset:26112
	ds_write_b128 v16, v[90:93] offset:34816
	s_waitcnt vmcnt(6)
	ds_write_b128 v16, v[98:101] offset:43520
	s_waitcnt lgkmcnt(0)
	s_barrier
	v_mfma_f32_16x16x32_bf16 v[36:39], v[60:63], v[48:51], v[36:39]
	ds_read_b128 v[94:97], v17 offset:34816
	ds_read_b128 v[98:101], v18
	ds_read_b128 v[102:105], v18 offset:64
	ds_read_b128 v[106:109], v17 offset:34880
	ds_read_b128 v[110:113], v17 offset:39168
	v_mfma_f32_16x16x32_bf16 v[24:27], v[70:73], v[48:51], v[24:27]
	ds_read_b128 v[114:117], v17 offset:39232
	ds_read_b128 v[118:121], v17 offset:43520
	s_waitcnt lgkmcnt(5)
	v_mfma_f32_16x16x32_bf16 v[28:31], v[94:97], v[98:101], v[28:31]
	ds_read_b128 v[94:97], v17 offset:43584
	ds_read_b128 v[122:125], v17 offset:47872
	ds_read_b128 v[126:129], v17 offset:47936
	s_waitcnt lgkmcnt(5)
	v_mfma_f32_16x16x32_bf16 v[32:35], v[110:113], v[98:101], v[32:35]
	ds_read_b128 v[110:113], v17 offset:34944
	ds_read_b128 v[130:133], v18 offset:128
	s_waitcnt lgkmcnt(5)
	v_mfma_f32_16x16x32_bf16 v[36:39], v[118:121], v[98:101], v[36:39]
	ds_read_b128 v[64:67], v18 offset:192
	ds_read_b128 v[68:71], v17 offset:35008
	s_waitcnt lgkmcnt(5)
	v_mfma_f32_16x16x32_bf16 v[24:27], v[122:125], v[98:101], v[24:27]
	s_waitcnt lgkmcnt(10)
	v_mfma_f32_16x16x32_bf16 v[28:31], v[106:109], v[102:105], v[28:31]
	s_waitcnt lgkmcnt(8)
	v_mfma_f32_16x16x32_bf16 v[32:35], v[114:117], v[102:105], v[32:35]
	s_waitcnt lgkmcnt(6)
	v_mfma_f32_16x16x32_bf16 v[36:39], v[94:97], v[102:105], v[36:39]
	ds_read_b128 v[94:97], v17 offset:39296
	s_waitcnt lgkmcnt(5)
	v_mfma_f32_16x16x32_bf16 v[24:27], v[126:129], v[102:105], v[24:27]
	ds_read_b128 v[72:75], v17 offset:39360
	ds_read_b128 v[98:101], v17 offset:43648
	s_waitcnt lgkmcnt(5)
	v_mfma_f32_16x16x32_bf16 v[28:31], v[110:113], v[130:133], v[28:31]
	ds_read_b128 v[76:79], v17 offset:43712
	ds_read_b128 v[102:105], v17 offset:48000
	ds_read_b128 v[90:93], v17 offset:48064
	s_waitcnt lgkmcnt(5)
	v_mfma_f32_16x16x32_bf16 v[32:35], v[94:97], v[130:133], v[32:35]
	s_waitcnt lgkmcnt(3)
	v_mfma_f32_16x16x32_bf16 v[36:39], v[98:101], v[130:133], v[36:39]
	s_waitcnt lgkmcnt(1)
	v_mfma_f32_16x16x32_bf16 v[24:27], v[102:105], v[130:133], v[24:27]
	s_waitcnt lgkmcnt(1)
	global_load_dwordx4 v[48:51], v[10:11], off offset:1024
	global_load_dwordx4 v[60:63], v[12:13], off offset:1024
	v_mfma_f32_16x16x32_bf16 v[28:31], v[68:71], v[64:67], v[28:31]
	v_mfma_f32_16x16x32_bf16 v[32:35], v[72:75], v[64:67], v[32:35]
	global_load_dwordx4 v[68:71], v[14:15], off offset:1024
	global_load_dwordx4 v[72:75], v[4:5], off offset:1024
	global_load_dwordx4 v[94:97], v[6:7], off offset:1024
	global_load_dwordx4 v[98:101], v[8:9], off offset:1024
	s_waitcnt vmcnt(9)
	ds_write_b128 v16, v[52:55] offset:52224
	ds_write_b128 v16, v[40:43] offset:60928
	ds_write_b128 v20, v[44:47] offset:17408
	s_waitcnt vmcnt(7)
	ds_write_b128 v20, v[82:85] offset:26112
	ds_write_b128 v22, v[56:59]
	s_waitcnt vmcnt(6)
	ds_write_b128 v21, v[86:89]
	s_waitcnt lgkmcnt(0)
	s_barrier
	ds_read_b128 v[84:87], v19 offset:52224
	ds_read_b128 v[102:105], v18 offset:52224
	ds_read_b128 v[106:109], v18 offset:52288
	ds_read_b128 v[110:113], v19 offset:52288
	ds_read_b128 v[114:117], v19 offset:56576
	v_mfma_f32_16x16x32_bf16 v[36:39], v[76:79], v[64:67], v[36:39]
	v_mfma_f32_16x16x32_bf16 v[24:27], v[90:93], v[64:67], v[24:27]
	ds_read_b128 v[118:121], v19 offset:56640
	ds_read_b128 v[122:125], v19 offset:60928
	s_waitcnt lgkmcnt(5)
	v_mfma_f32_16x16x32_bf16 v[28:31], v[84:87], v[102:105], v[28:31]
	ds_read_b128 v[84:87], v19 offset:60992
	ds_read_b128 v[126:129], v19 offset:65280
	ds_read_b128 v[130:133], v19 offset:65344
	s_waitcnt lgkmcnt(5)
	v_mfma_f32_16x16x32_bf16 v[32:35], v[114:117], v[102:105], v[32:35]
	ds_read_b128 v[114:117], v19 offset:52352
	ds_read_b128 v[134:137], v18 offset:52352
	s_waitcnt lgkmcnt(5)
	v_mfma_f32_16x16x32_bf16 v[36:39], v[122:125], v[102:105], v[36:39]
	ds_read_b128 v[52:55], v18 offset:52416
	ds_read_b128 v[56:59], v19 offset:52416
	s_waitcnt lgkmcnt(5)
	v_mfma_f32_16x16x32_bf16 v[24:27], v[126:129], v[102:105], v[24:27]
	s_waitcnt lgkmcnt(10)
	v_mfma_f32_16x16x32_bf16 v[28:31], v[110:113], v[106:109], v[28:31]
	s_waitcnt lgkmcnt(8)
	v_mfma_f32_16x16x32_bf16 v[32:35], v[118:121], v[106:109], v[32:35]
	s_waitcnt lgkmcnt(6)
	v_mfma_f32_16x16x32_bf16 v[36:39], v[84:87], v[106:109], v[36:39]
	ds_read_b128 v[84:87], v19 offset:56704
	s_waitcnt lgkmcnt(5)
	v_mfma_f32_16x16x32_bf16 v[24:27], v[130:133], v[106:109], v[24:27]
	ds_read_b128 v[64:67], v19 offset:56768
	ds_read_b128 v[102:105], v19 offset:61056
	s_waitcnt lgkmcnt(5)
	v_mfma_f32_16x16x32_bf16 v[28:31], v[114:117], v[134:137], v[28:31]
	ds_read_b128 v[76:79], v19 offset:61120
	ds_read_b128 v[106:109], v19 offset:65408
	ds_read_b128 v[80:83], v19 offset:65472
	s_waitcnt lgkmcnt(5)
	v_mfma_f32_16x16x32_bf16 v[32:35], v[84:87], v[134:137], v[32:35]
	s_waitcnt lgkmcnt(3)
	v_mfma_f32_16x16x32_bf16 v[36:39], v[102:105], v[134:137], v[36:39]
	s_waitcnt lgkmcnt(1)
	v_mfma_f32_16x16x32_bf16 v[24:27], v[106:109], v[134:137], v[24:27]
	s_waitcnt lgkmcnt(1)
	global_load_dwordx4 v[40:43], v[10:11], off offset:1280
	global_load_dwordx4 v[44:47], v[12:13], off offset:1280
	v_mfma_f32_16x16x32_bf16 v[28:31], v[56:59], v[52:55], v[28:31]
	v_mfma_f32_16x16x32_bf16 v[32:35], v[64:67], v[52:55], v[32:35]
	global_load_dwordx4 v[56:59], v[14:15], off offset:1280
	global_load_dwordx4 v[64:67], v[4:5], off offset:1280
	global_load_dwordx4 v[84:87], v[6:7], off offset:1280
	global_load_dwordx4 v[88:91], v[8:9], off offset:1280
	s_waitcnt vmcnt(9)
	ds_write_b128 v16, v[68:71]
	ds_write_b128 v16, v[48:51] offset:8704
	ds_write_b128 v16, v[60:63] offset:17408
	s_waitcnt vmcnt(7)
	ds_write_b128 v16, v[94:97] offset:26112
	ds_write_b128 v16, v[72:75] offset:34816
	s_waitcnt vmcnt(6)
	ds_write_b128 v16, v[98:101] offset:43520
	s_waitcnt lgkmcnt(0)
	s_barrier
	ds_read_b128 v[92:95], v17 offset:34816
	ds_read_b128 v[96:99], v18
	ds_read_b128 v[100:103], v18 offset:64
	ds_read_b128 v[104:107], v17 offset:34880
	ds_read_b128 v[108:111], v17 offset:39168
	v_mfma_f32_16x16x32_bf16 v[36:39], v[76:79], v[52:55], v[36:39]
	v_mfma_f32_16x16x32_bf16 v[24:27], v[80:83], v[52:55], v[24:27]
	ds_read_b128 v[112:115], v17 offset:39232
	ds_read_b128 v[116:119], v17 offset:43520
	s_waitcnt lgkmcnt(5)
	v_mfma_f32_16x16x32_bf16 v[28:31], v[92:95], v[96:99], v[28:31]
	ds_read_b128 v[92:95], v17 offset:43584
	ds_read_b128 v[120:123], v17 offset:47872
	ds_read_b128 v[124:127], v17 offset:47936
	s_waitcnt lgkmcnt(5)
	v_mfma_f32_16x16x32_bf16 v[32:35], v[108:111], v[96:99], v[32:35]
	ds_read_b128 v[108:111], v17 offset:34944
	ds_read_b128 v[128:131], v18 offset:128
	s_waitcnt lgkmcnt(5)
	v_mfma_f32_16x16x32_bf16 v[36:39], v[116:119], v[96:99], v[36:39]
	ds_read_b128 v[60:63], v18 offset:192
	ds_read_b128 v[68:71], v17 offset:35008
	s_waitcnt lgkmcnt(5)
	v_mfma_f32_16x16x32_bf16 v[24:27], v[120:123], v[96:99], v[24:27]
	s_waitcnt lgkmcnt(10)
	v_mfma_f32_16x16x32_bf16 v[28:31], v[104:107], v[100:103], v[28:31]
	s_waitcnt lgkmcnt(8)
	v_mfma_f32_16x16x32_bf16 v[32:35], v[112:115], v[100:103], v[32:35]
	s_waitcnt lgkmcnt(6)
	v_mfma_f32_16x16x32_bf16 v[36:39], v[92:95], v[100:103], v[36:39]
	ds_read_b128 v[92:95], v17 offset:39296
	s_waitcnt lgkmcnt(5)
	v_mfma_f32_16x16x32_bf16 v[24:27], v[124:127], v[100:103], v[24:27]
	ds_read_b128 v[72:75], v17 offset:39360
	ds_read_b128 v[96:99], v17 offset:43648
	s_waitcnt lgkmcnt(5)
	v_mfma_f32_16x16x32_bf16 v[28:31], v[108:111], v[128:131], v[28:31]
	ds_read_b128 v[76:79], v17 offset:43712
	ds_read_b128 v[100:103], v17 offset:48000
	ds_read_b128 v[80:83], v17 offset:48064
	s_waitcnt lgkmcnt(5)
	v_mfma_f32_16x16x32_bf16 v[32:35], v[92:95], v[128:131], v[32:35]
	s_waitcnt lgkmcnt(3)
	v_mfma_f32_16x16x32_bf16 v[36:39], v[96:99], v[128:131], v[36:39]
	s_waitcnt lgkmcnt(1)
	v_mfma_f32_16x16x32_bf16 v[24:27], v[100:103], v[128:131], v[24:27]
	s_waitcnt lgkmcnt(1)
	global_load_dwordx4 v[48:51], v[10:11], off offset:1536
	global_load_dwordx4 v[52:55], v[12:13], off offset:1536
	v_mfma_f32_16x16x32_bf16 v[28:31], v[68:71], v[60:63], v[28:31]
	v_mfma_f32_16x16x32_bf16 v[32:35], v[72:75], v[60:63], v[32:35]
	global_load_dwordx4 v[68:71], v[14:15], off offset:1536
	global_load_dwordx4 v[72:75], v[4:5], off offset:1536
	global_load_dwordx4 v[92:95], v[6:7], off offset:1536
	global_load_dwordx4 v[96:99], v[8:9], off offset:1536
	s_waitcnt vmcnt(9)
	ds_write_b128 v16, v[56:59] offset:52224
	ds_write_b128 v16, v[40:43] offset:60928
	ds_write_b128 v20, v[44:47] offset:17408
	s_waitcnt vmcnt(7)
	ds_write_b128 v20, v[84:87] offset:26112
	ds_write_b128 v22, v[64:67]
	s_waitcnt vmcnt(6)
	ds_write_b128 v21, v[88:91]
	s_waitcnt lgkmcnt(0)
	s_barrier
	ds_read_b128 v[84:87], v19 offset:52224
	ds_read_b128 v[88:91], v18 offset:52224
	ds_read_b128 v[100:103], v18 offset:52288
	ds_read_b128 v[104:107], v19 offset:52288
	ds_read_b128 v[108:111], v19 offset:56576
	v_mfma_f32_16x16x32_bf16 v[36:39], v[76:79], v[60:63], v[36:39]
	v_mfma_f32_16x16x32_bf16 v[24:27], v[80:83], v[60:63], v[24:27]
	ds_read_b128 v[112:115], v19 offset:56640
	ds_read_b128 v[116:119], v19 offset:60928
	s_waitcnt lgkmcnt(5)
	v_mfma_f32_16x16x32_bf16 v[28:31], v[84:87], v[88:91], v[28:31]
	ds_read_b128 v[84:87], v19 offset:60992
	ds_read_b128 v[120:123], v19 offset:65280
	ds_read_b128 v[124:127], v19 offset:65344
	s_waitcnt lgkmcnt(5)
	v_mfma_f32_16x16x32_bf16 v[32:35], v[108:111], v[88:91], v[32:35]
	ds_read_b128 v[108:111], v19 offset:52352
	ds_read_b128 v[128:131], v18 offset:52352
	s_waitcnt lgkmcnt(5)
	v_mfma_f32_16x16x32_bf16 v[36:39], v[116:119], v[88:91], v[36:39]
	ds_read_b128 v[56:59], v18 offset:52416
	ds_read_b128 v[60:63], v19 offset:52416
	s_waitcnt lgkmcnt(5)
	v_mfma_f32_16x16x32_bf16 v[24:27], v[120:123], v[88:91], v[24:27]
	s_waitcnt lgkmcnt(10)
	v_mfma_f32_16x16x32_bf16 v[28:31], v[104:107], v[100:103], v[28:31]
	s_waitcnt lgkmcnt(8)
	v_mfma_f32_16x16x32_bf16 v[32:35], v[112:115], v[100:103], v[32:35]
	s_waitcnt lgkmcnt(6)
	v_mfma_f32_16x16x32_bf16 v[36:39], v[84:87], v[100:103], v[36:39]
	ds_read_b128 v[84:87], v19 offset:56704
	s_waitcnt lgkmcnt(5)
	v_mfma_f32_16x16x32_bf16 v[24:27], v[124:127], v[100:103], v[24:27]
	ds_read_b128 v[64:67], v19 offset:56768
	ds_read_b128 v[88:91], v19 offset:61056
	s_waitcnt lgkmcnt(5)
	v_mfma_f32_16x16x32_bf16 v[28:31], v[108:111], v[128:131], v[28:31]
	ds_read_b128 v[76:79], v19 offset:61120
	ds_read_b128 v[100:103], v19 offset:65408
	ds_read_b128 v[80:83], v19 offset:65472
	s_waitcnt lgkmcnt(5)
	v_mfma_f32_16x16x32_bf16 v[32:35], v[84:87], v[128:131], v[32:35]
	s_waitcnt lgkmcnt(3)
	v_mfma_f32_16x16x32_bf16 v[36:39], v[88:91], v[128:131], v[36:39]
	s_waitcnt lgkmcnt(1)
	v_mfma_f32_16x16x32_bf16 v[24:27], v[100:103], v[128:131], v[24:27]
	s_waitcnt lgkmcnt(1)
	global_load_dwordx4 v[40:43], v[10:11], off offset:1792
	s_nop 0
	global_load_dwordx4 v[10:13], v[12:13], off offset:1792
	v_mfma_f32_16x16x32_bf16 v[28:31], v[60:63], v[56:59], v[28:31]
	v_mfma_f32_16x16x32_bf16 v[32:35], v[64:67], v[56:59], v[32:35]
	global_load_dwordx4 v[44:47], v[14:15], off offset:1792
	global_load_dwordx4 v[60:63], v[4:5], off offset:1792
	s_nop 0
	global_load_dwordx4 v[4:7], v[6:7], off offset:1792
	s_nop 0
	global_load_dwordx4 v[64:67], v[8:9], off offset:1792
	s_waitcnt vmcnt(9)
	ds_write_b128 v16, v[68:71]
	ds_write_b128 v16, v[48:51] offset:8704
	ds_write_b128 v16, v[52:55] offset:17408
	s_waitcnt vmcnt(7)
	ds_write_b128 v16, v[92:95] offset:26112
	ds_write_b128 v16, v[72:75] offset:34816
	s_waitcnt vmcnt(6)
	ds_write_b128 v16, v[96:99] offset:43520
	s_waitcnt lgkmcnt(0)
	s_barrier
	ds_read_b128 v[84:87], v17 offset:34816
	ds_read_b128 v[88:91], v18
	ds_read_b128 v[92:95], v18 offset:64
	ds_read_b128 v[96:99], v17 offset:34880
	ds_read_b128 v[100:103], v17 offset:39168
	v_mfma_f32_16x16x32_bf16 v[36:39], v[76:79], v[56:59], v[36:39]
	v_mfma_f32_16x16x32_bf16 v[24:27], v[80:83], v[56:59], v[24:27]
	ds_read_b128 v[104:107], v17 offset:39232
	ds_read_b128 v[108:111], v17 offset:43520
	s_waitcnt lgkmcnt(5)
	v_mfma_f32_16x16x32_bf16 v[28:31], v[84:87], v[88:91], v[28:31]
	ds_read_b128 v[84:87], v17 offset:43584
	ds_read_b128 v[112:115], v17 offset:47872
	ds_read_b128 v[116:119], v17 offset:47936
	s_waitcnt lgkmcnt(5)
	v_mfma_f32_16x16x32_bf16 v[32:35], v[100:103], v[88:91], v[32:35]
	ds_read_b128 v[100:103], v17 offset:34944
	ds_read_b128 v[120:123], v17 offset:39296
	s_waitcnt lgkmcnt(5)
	v_mfma_f32_16x16x32_bf16 v[36:39], v[108:111], v[88:91], v[36:39]
	ds_read_b128 v[56:59], v18 offset:128
	ds_read_b128 v[68:71], v18 offset:192
	s_waitcnt lgkmcnt(5)
	v_mfma_f32_16x16x32_bf16 v[24:27], v[112:115], v[88:91], v[24:27]
	s_waitcnt lgkmcnt(10)
	v_mfma_f32_16x16x32_bf16 v[28:31], v[96:99], v[92:95], v[28:31]
	s_waitcnt lgkmcnt(8)
	v_mfma_f32_16x16x32_bf16 v[32:35], v[104:107], v[92:95], v[32:35]
	s_waitcnt lgkmcnt(6)
	v_mfma_f32_16x16x32_bf16 v[36:39], v[84:87], v[92:95], v[36:39]
	ds_read_b128 v[72:75], v17 offset:35008
	s_waitcnt lgkmcnt(5)
	v_mfma_f32_16x16x32_bf16 v[24:27], v[116:119], v[92:95], v[24:27]
	ds_read_b128 v[84:87], v17 offset:43648
	ds_read_b128 v[76:79], v17 offset:39360
	ds_read_b128 v[80:83], v17 offset:43712
	s_waitcnt lgkmcnt(5)
	v_mfma_f32_16x16x32_bf16 v[28:31], v[100:103], v[56:59], v[28:31]
	s_waitcnt lgkmcnt(5)
	v_mfma_f32_16x16x32_bf16 v[32:35], v[120:123], v[56:59], v[32:35]
	ds_read_b128 v[52:55], v17 offset:48000
	s_waitcnt lgkmcnt(3)
	v_mfma_f32_16x16x32_bf16 v[36:39], v[84:87], v[56:59], v[36:39]
	s_waitcnt lgkmcnt(3)
	ds_read_b128 v[48:51], v17 offset:48064
	s_waitcnt vmcnt(3)
	ds_write_b128 v16, v[44:47] offset:52224
	ds_write_b128 v16, v[40:43] offset:60928
	ds_write_b128 v20, v[10:13] offset:17408
	s_waitcnt vmcnt(1)
	ds_write_b128 v20, v[4:7] offset:26112
	ds_write_b128 v22, v[60:63]
	s_waitcnt vmcnt(0)
	ds_write_b128 v21, v[64:67]
	s_waitcnt lgkmcnt(0)
	s_barrier
	s_waitcnt lgkmcnt(7)
	v_mfma_f32_16x16x32_bf16 v[14:17], v[52:55], v[56:59], v[24:27]
	ds_read_b128 v[20:23], v18 offset:52224
	s_nop 1
	ds_read_b128 v[24:27], v18 offset:52288
	v_mfma_f32_16x16x32_bf16 v[4:7], v[72:75], v[68:71], v[28:31]
	v_mfma_f32_16x16x32_bf16 v[8:11], v[76:79], v[68:71], v[32:35]
	v_mfma_f32_16x16x32_bf16 v[28:31], v[80:83], v[68:71], v[36:39]
	s_nop 1
	ds_read_b128 v[32:35], v19 offset:52224
	ds_read_b128 v[36:39], v19 offset:52288
	ds_read_b128 v[40:43], v19 offset:56576
	ds_read_b128 v[44:47], v19 offset:56640
	s_waitcnt lgkmcnt(3)
	v_mfma_f32_16x16x32_bf16 v[4:7], v[32:35], v[20:23], v[4:7]
	v_mfma_f32_16x16x32_bf16 v[12:15], v[48:51], v[68:71], v[14:17]
	ds_read_b128 v[48:51], v19 offset:60928
	ds_read_b128 v[52:55], v19 offset:60992
	ds_read_b128 v[56:59], v19 offset:65280
	ds_read_b128 v[60:63], v19 offset:65344
	ds_read_b128 v[32:35], v18 offset:52352
	ds_read_b128 v[64:67], v18 offset:52416
	ds_read_b128 v[68:71], v19 offset:52352
	ds_read_b128 v[72:75], v19 offset:52416
	s_waitcnt lgkmcnt(10)
	v_mfma_f32_16x16x32_bf16 v[4:7], v[36:39], v[24:27], v[4:7]
	v_add_u32_e32 v36, s5, v2
	v_ashrrev_i32_e32 v37, 31, v36
	s_waitcnt lgkmcnt(9)
	v_mfma_f32_16x16x32_bf16 v[8:11], v[40:43], v[20:23], v[8:11]
	ds_read_b128 v[40:43], v19 offset:56704
	ds_read_b128 v[76:79], v19 offset:56768
	ds_read_b128 v[80:83], v19 offset:61056
	ds_read_b128 v[84:87], v19 offset:61120
	s_waitcnt lgkmcnt(11)
	v_mfma_f32_16x16x32_bf16 v[28:31], v[48:51], v[20:23], v[28:31]
	ds_read_b128 v[48:51], v19 offset:65408
	ds_read_b128 v[16:19], v19 offset:65472
	s_waitcnt lgkmcnt(0)
	s_barrier
	s_waitcnt lgkmcnt(11)
	v_mfma_f32_16x16x32_bf16 v[12:15], v[56:59], v[20:23], v[12:15]
	v_lshl_add_u64 v[20:21], v[36:37], 2, s[2:3]
	global_load_dword v2, v[20:21], off
	v_mfma_f32_16x16x32_bf16 v[20:23], v[52:55], v[24:27], v[28:31]
	s_waitcnt vmcnt(0)
	v_fmamk_f32 v2, v2, 0x3a800000, v208
	s_nop 0
	v_mul_f32_e32 v28, 0x4f800000, v2
	v_cmp_gt_f32_e32 vcc, s90, v2
	v_mfma_f32_16x16x32_bf16 v[8:11], v[44:47], v[24:27], v[8:11]
	s_nop 0
	v_cndmask_b32_e32 v2, v2, v28, vcc
	s_waitcnt lgkmcnt(10)
	v_mfma_f32_16x16x32_bf16 v[12:15], v[60:63], v[24:27], v[12:15]
	v_sqrt_f32_e32 v24, v2
	s_nop 0
	v_add_u32_e32 v25, -1, v24
	v_fma_f32 v26, -v25, v24, v2
	v_cmp_ge_f32_e64 s[4:5], 0, v26
	v_add_u32_e32 v26, 1, v24
	s_waitcnt lgkmcnt(7)
	v_mfma_f32_16x16x32_bf16 v[4:7], v[68:71], v[32:35], v[4:7]
	v_cndmask_b32_e64 v25, v24, v25, s[4:5]
	v_fma_f32 v24, -v26, v24, v2
	v_cmp_lt_f32_e64 s[4:5], 0, v24
	s_waitcnt lgkmcnt(5)
	v_mfma_f32_16x16x32_bf16 v[8:11], v[40:43], v[32:35], v[8:11]
	v_cndmask_b32_e64 v24, v25, v26, s[4:5]
	v_mul_f32_e32 v25, 0x37800000, v24
	v_cndmask_b32_e32 v24, v24, v25, vcc
	v_cmp_class_f32_e32 vcc, v2, v209
	v_mfma_f32_16x16x32_bf16 v[4:7], v[72:75], v[64:67], v[4:7]
	s_nop 0
	v_cndmask_b32_e32 v2, v24, v2, vcc
	v_div_scale_f32 v24, s[2:3], v2, v2, 1.0
	v_rcp_f32_e32 v25, v24
	s_waitcnt lgkmcnt(3)
	v_mfma_f32_16x16x32_bf16 v[20:23], v[80:83], v[32:35], v[20:23]
	v_fma_f32 v26, -v24, v25, 1.0
	v_fmac_f32_e32 v25, v26, v25
	v_div_scale_f32 v26, vcc, 1.0, v2, 1.0
	v_mul_f32_e32 v27, v26, v25
	v_fma_f32 v28, -v24, v27, v26
	v_fmac_f32_e32 v27, v28, v25
	v_fma_f32 v24, -v24, v27, v26
	v_div_fmas_f32 v24, v24, v25, v27
	v_div_fixup_f32 v2, v24, v2, 1.0
	s_waitcnt lgkmcnt(1)
	v_mfma_f32_16x16x32_bf16 v[12:15], v[48:51], v[32:35], v[12:15]
	v_mul_f32_e32 v2, 0x3db8aa3b, v2
	v_pk_mul_f32 v[6:7], v[6:7], v[2:3] op_sel_hi:[1,0]
	v_pk_mul_f32 v[4:5], v[4:5], v[2:3] op_sel_hi:[1,0]
	v_mfma_f32_16x16x32_bf16 v[8:11], v[76:79], v[64:67], v[8:11]
	v_cvt_pk_bf16_f32 v4, v4, v5
	v_cvt_pk_bf16_f32 v5, v6, v7
	v_lshlrev_b64 v[6:7], 13, v[36:37]
	v_mfma_f32_16x16x32_bf16 v[20:23], v[84:87], v[64:67], v[20:23]
	v_lshl_add_u64 v[6:7], s[0:1], 0, v[6:7]
	v_lshl_add_u64 v[6:7], v[6:7], 0, s[46:47]
	s_nop 3
	v_pk_mul_f32 v[8:9], v[8:9], v[2:3] op_sel_hi:[1,0]
	s_waitcnt lgkmcnt(0)
	v_mfma_f32_16x16x32_bf16 v[12:15], v[16:19], v[64:67], v[12:15]
	v_lshlrev_b32_e32 v16, 3, v1
	v_mov_b32_e32 v17, v3
	v_lshl_add_u64 v[6:7], v[6:7], 0, v[16:17]
	global_store_dwordx2 v[6:7], v[4:5], off
	v_pk_mul_f32 v[4:5], v[10:11], v[2:3] op_sel_hi:[1,0]
	v_cvt_pk_bf16_f32 v8, v8, v9
	s_nop 0
	v_cvt_pk_bf16_f32 v9, v4, v5
	global_store_dwordx2 v[6:7], v[8:9], off offset:32
	v_pk_mul_f32 v[8:9], v[20:21], v[2:3] op_sel_hi:[1,0]
	v_pk_mul_f32 v[4:5], v[22:23], v[2:3] op_sel_hi:[1,0]
	v_cvt_pk_bf16_f32 v8, v8, v9
	s_nop 0
	v_cvt_pk_bf16_f32 v9, v4, v5
	global_store_dwordx2 v[6:7], v[8:9], off offset:64
	v_pk_mul_f32 v[8:9], v[12:13], v[2:3] op_sel_hi:[1,0]
	v_pk_mul_f32 v[4:5], v[14:15], v[2:3] op_sel_hi:[1,0]
	v_cvt_pk_bf16_f32 v8, v8, v9
	s_nop 0
	v_cvt_pk_bf16_f32 v9, v4, v5
	global_store_dwordx2 v[6:7], v[8:9], off offset:96

.LBB0_2431:
	s_mov_b32 s34, s47
	s_waitcnt vmcnt(63) expcnt(7) lgkmcnt(15)
	s_load_dwordx2 s[12:13], s[26:27], s34 offset:0xd8
	s_add_i32 s34, s34, s62
	v_readlane_b32 s0, v255, 17
	v_mov_b32_e32 v1, v0
	s_waitcnt lgkmcnt(0)
	s_add_u32 s10, s12, 0x9400000
	s_addc_u32 s11, s13, 0
	s_add_u32 s0, s12, s0
	s_addc_u32 s1, s13, 0
	s_add_u32 s14, s0, 0xc00000
	s_addc_u32 s15, s1, 0
	v_readlane_b32 s0, v255, 18
	v_readlane_b32 s1, v255, 19
	s_add_i32 s46, s0, 0x21000
	s_lshl_b64 s[0:1], s[46:47], 2
	s_add_u32 s2, s12, s0
	s_addc_u32 s3, s13, s1
	s_add_u32 s2, s2, 0x100000
	s_addc_u32 s3, s3, 0
	s_bitcmp0_b32 s34, 0
	s_cselect_b64 s[16:17], -1, 0
	s_and_b64 vcc, exec, s[16:17]
	s_cbranch_vccnz .LBB0_2435
	v_mov_b32_e32 v1, v0
	s_lshl_b32 s5, s34, 3
	v_ashrrev_i32_e32 v2, 31, v1
	v_lshrrev_b32_e32 v2, 28, v2
	v_add_u32_e32 v2, v1, v2
	v_ashrrev_i32_e32 v17, 4, v2
	s_and_b32 s5, s5, 0xffffff80
	v_and_b32_e32 v2, -16, v2
	v_add_u32_e32 v4, s5, v17
	v_sub_u32_e32 v19, v1, v2
	v_ashrrev_i32_e32 v5, 31, v4
	s_lshl_b32 s4, s34, 6
	v_lshlrev_b64 v[6:7], 13, v[4:5]
	v_lshlrev_b32_e32 v4, 3, v19
	s_and_b32 s4, s4, 0x3c0
	v_ashrrev_i32_e32 v5, 31, v4
	v_add_u32_e32 v8, s4, v17
	v_lshlrev_b64 v[10:11], 1, v[4:5]
	v_lshl_add_u64 v[6:7], s[12:13], 0, v[6:7]
	v_ashrrev_i32_e32 v9, 31, v8
	v_lshl_add_u64 v[14:15], v[6:7], 0, v[10:11]
	v_lshlrev_b64 v[8:9], 11, v[8:9]
	v_add_co_u32_e32 v6, vcc, s76, v14
	v_lshl_add_u64 v[8:9], s[14:15], 0, v[8:9]
	s_nop 0
	v_addc_co_u32_e32 v7, vcc, 0, v15, vcc
	v_lshl_add_u64 v[4:5], v[8:9], 0, v[10:11]
	v_add_co_u32_e32 v8, vcc, s89, v14
	global_load_dwordx4 v[20:23], v[6:7], off offset:2048
	s_nop 0
	v_addc_co_u32_e32 v9, vcc, 0, v15, vcc
	v_add_co_u32_e32 v12, vcc, s96, v14
	global_load_dwordx4 v[24:27], v[8:9], off offset:2048
	s_nop 0
	v_addc_co_u32_e32 v13, vcc, 0, v15, vcc
	v_add_co_u32_e32 v6, vcc, s97, v14
	global_load_dwordx4 v[28:31], v[12:13], off offset:2048
	s_nop 0
	v_addc_co_u32_e32 v7, vcc, 0, v15, vcc
	global_load_dwordx4 v[32:35], v[6:7], off offset:2048
	global_load_dwordx4 v[36:39], v[4:5], off
	v_add_co_u32_e32 v10, vcc, s63, v4
	s_mov_b64 s[8:9], 0x31800800
	s_nop 0
	v_addc_co_u32_e32 v11, vcc, 0, v5, vcc
	global_load_dwordx4 v[40:43], v[10:11], off
	v_lshl_add_u64 v[14:15], v[14:15], 0, s[8:9]
	global_load_dwordx4 v[44:47], v[4:5], off offset:256
	global_load_dwordx4 v[48:51], v[14:15], off offset:256
	global_load_dwordx4 v[52:55], v[8:9], off offset:2304
	global_load_dwordx4 v[56:59], v[12:13], off offset:2304
	global_load_dwordx4 v[60:63], v[6:7], off offset:2304
	global_load_dwordx4 v[64:67], v[10:11], off offset:256
	v_mul_lo_u32 v17, v17, s81
	v_lshlrev_b32_e32 v19, 4, v19
	v_and_b32_e32 v16, 15, v1
	v_bfe_u32 v2, v1, 4, 2
	v_add3_u32 v17, v17, v19, 0
	v_lshlrev_b32_e32 v68, 4, v2
	v_mul_u32_u24_e32 v18, 0x110, v16
	v_add3_u32 v18, v18, v68, 0
	v_readfirstlane_b32 s6, v1
	s_ashr_i32 s6, s6, 2
	s_add_i32 s5, s5, 0x10000
	v_bfi_b32 v19, -16, s6, v1
	v_mul_lo_u32 v19, v19, s81
	v_add3_u32 v19, v19, v68, 0
	s_and_b32 s6, s6, -16
	s_lshl_b32 s46, s4, 1
	v_and_b32_e32 v1, 16, v1
	v_cmp_eq_u32_e32 vcc, 0, v1
	s_waitcnt vmcnt(0)
	ds_write_b128 v17, v[36:39] offset:34816
	ds_write_b128 v17, v[20:23]
	ds_write_b128 v17, v[24:27] offset:8704
	ds_write_b128 v17, v[28:31] offset:17408
	ds_write_b128 v17, v[32:35] offset:26112
	ds_write_b128 v17, v[40:43] offset:43520
	s_waitcnt lgkmcnt(0)
	s_barrier
	ds_read_b128 v[88:91], v18 offset:34816
	ds_read_b128 v[92:95], v19
	ds_read_b128 v[96:99], v19 offset:64
	ds_read_b128 v[100:103], v18 offset:34880
	ds_read_b128 v[104:107], v18 offset:39168
	ds_read_b128 v[108:111], v18 offset:39232
	ds_read_b128 v[112:115], v18 offset:43520
	s_waitcnt lgkmcnt(5)
	v_mfma_f32_16x16x32_bf16 v[20:23], v[88:91], v[92:95], 0
	ds_read_b128 v[88:91], v18 offset:43584
	ds_read_b128 v[116:119], v18 offset:47872
	ds_read_b128 v[120:123], v18 offset:47936
	s_waitcnt lgkmcnt(5)
	v_mfma_f32_16x16x32_bf16 v[36:39], v[104:107], v[92:95], 0
	s_waitcnt lgkmcnt(6)
	v_mfma_f32_16x16x32_bf16 v[20:23], v[100:103], v[96:99], v[20:23]
	ds_read_b128 v[100:103], v18 offset:34944
	s_waitcnt lgkmcnt(5)
	v_mfma_f32_16x16x32_bf16 v[32:35], v[108:111], v[96:99], v[36:39]
	ds_read_b128 v[104:107], v19 offset:128
	s_waitcnt lgkmcnt(5)
	v_mfma_f32_16x16x32_bf16 v[68:71], v[112:115], v[92:95], 0
	s_waitcnt lgkmcnt(3)
	v_mfma_f32_16x16x32_bf16 v[24:27], v[116:119], v[92:95], 0
	s_waitcnt lgkmcnt(4)
	v_mfma_f32_16x16x32_bf16 v[36:39], v[88:91], v[96:99], v[68:71]
	s_nop 2
	ds_read_b128 v[68:71], v19 offset:192
	ds_read_b128 v[72:75], v18 offset:35008
	ds_read_b128 v[88:91], v18 offset:39296
	s_waitcnt lgkmcnt(5)
	v_mfma_f32_16x16x32_bf16 v[24:27], v[120:123], v[96:99], v[24:27]
	ds_read_b128 v[76:79], v18 offset:39360
	ds_read_b128 v[92:95], v18 offset:43648
	s_waitcnt lgkmcnt(5)
	v_mfma_f32_16x16x32_bf16 v[40:43], v[100:103], v[104:107], v[20:23]
	ds_read_b128 v[80:83], v18 offset:43712
	ds_read_b128 v[96:99], v18 offset:48000
	ds_read_b128 v[84:87], v18 offset:48064
	s_waitcnt lgkmcnt(5)
	v_mfma_f32_16x16x32_bf16 v[32:35], v[88:91], v[104:107], v[32:35]
	s_waitcnt lgkmcnt(3)
	v_mfma_f32_16x16x32_bf16 v[36:39], v[92:95], v[104:107], v[36:39]
	s_waitcnt lgkmcnt(1)
	v_mfma_f32_16x16x32_bf16 v[24:27], v[96:99], v[104:107], v[24:27]
	s_waitcnt lgkmcnt(1)
	v_add_u32_e32 v21, 0xcc00, v17
	v_add_u32_e32 v22, 0x15400, v17
	v_add_u32_e32 v23, 0x17600, v17
	v_mfma_f32_16x16x32_bf16 v[28:31], v[72:75], v[68:71], v[40:43]
	s_nop 2
	global_load_dwordx4 v[40:43], v[8:9], off offset:2560
	global_load_dwordx4 v[72:75], v[12:13], off offset:2560
	v_add_u32_e32 v20, 0x8800, v18
	v_mfma_f32_16x16x32_bf16 v[32:35], v[76:79], v[68:71], v[32:35]
	global_load_dwordx4 v[76:79], v[14:15], off offset:512
	global_load_dwordx4 v[88:91], v[4:5], off offset:512
	global_load_dwordx4 v[92:95], v[6:7], off offset:2560
	global_load_dwordx4 v[96:99], v[10:11], off offset:512
	ds_write_b128 v17, v[48:51] offset:52224
	ds_write_b128 v17, v[52:55] offset:60928
	ds_write_b128 v21, v[56:59] offset:17408
	ds_write_b128 v21, v[60:63] offset:26112
	ds_write_b128 v22, v[44:47]
	ds_write_b128 v23, v[64:67]
	s_waitcnt lgkmcnt(0)
	s_barrier
	ds_read_b128 v[100:103], v20 offset:52224
	ds_read_b128 v[104:107], v19 offset:52224
	ds_read_b128 v[108:111], v19 offset:52288
	ds_read_b128 v[112:115], v20 offset:52288
	ds_read_b128 v[116:119], v20 offset:56576
	ds_read_b128 v[120:123], v20 offset:56640
	ds_read_b128 v[124:127], v20 offset:60928
	s_waitcnt lgkmcnt(5)
	v_mfma_f32_16x16x32_bf16 v[28:31], v[100:103], v[104:107], v[28:31]
	v_mfma_f32_16x16x32_bf16 v[36:39], v[80:83], v[68:71], v[36:39]
	ds_read_b128 v[100:103], v20 offset:60992
	ds_read_b128 v[128:131], v20 offset:65280
	ds_read_b128 v[132:135], v20 offset:65344
	s_waitcnt lgkmcnt(5)
	v_mfma_f32_16x16x32_bf16 v[32:35], v[116:119], v[104:107], v[32:35]
	v_mfma_f32_16x16x32_bf16 v[24:27], v[84:87], v[68:71], v[24:27]
	ds_read_b128 v[116:119], v20 offset:52352
	ds_read_b128 v[136:139], v19 offset:52352
	s_waitcnt lgkmcnt(5)
	v_mfma_f32_16x16x32_bf16 v[36:39], v[124:127], v[104:107], v[36:39]
	ds_read_b128 v[52:55], v19 offset:52416
	ds_read_b128 v[56:59], v20 offset:52416
	s_waitcnt lgkmcnt(5)
	v_mfma_f32_16x16x32_bf16 v[24:27], v[128:131], v[104:107], v[24:27]
	s_waitcnt lgkmcnt(10)
	v_mfma_f32_16x16x32_bf16 v[28:31], v[112:115], v[108:111], v[28:31]
	s_waitcnt lgkmcnt(8)
	v_mfma_f32_16x16x32_bf16 v[32:35], v[120:123], v[108:111], v[32:35]
	s_waitcnt lgkmcnt(6)
	v_mfma_f32_16x16x32_bf16 v[36:39], v[100:103], v[108:111], v[36:39]
	ds_read_b128 v[100:103], v20 offset:56704
	s_waitcnt lgkmcnt(5)
	v_mfma_f32_16x16x32_bf16 v[24:27], v[132:135], v[108:111], v[24:27]
	ds_read_b128 v[60:63], v20 offset:56768
	ds_read_b128 v[104:107], v20 offset:61056
	s_waitcnt lgkmcnt(5)
	v_mfma_f32_16x16x32_bf16 v[28:31], v[116:119], v[136:139], v[28:31]
	ds_read_b128 v[64:67], v20 offset:61120
	ds_read_b128 v[108:111], v20 offset:65408
	ds_read_b128 v[68:71], v20 offset:65472
	s_waitcnt lgkmcnt(5)
	v_mfma_f32_16x16x32_bf16 v[32:35], v[100:103], v[136:139], v[32:35]
	s_waitcnt lgkmcnt(3)
	v_mfma_f32_16x16x32_bf16 v[36:39], v[104:107], v[136:139], v[36:39]
	s_waitcnt lgkmcnt(1)
	v_mfma_f32_16x16x32_bf16 v[24:27], v[108:111], v[136:139], v[24:27]
	s_waitcnt lgkmcnt(1)
	global_load_dwordx4 v[44:47], v[8:9], off offset:2816
	global_load_dwordx4 v[48:51], v[12:13], off offset:2816
	v_mfma_f32_16x16x32_bf16 v[28:31], v[56:59], v[52:55], v[28:31]
	v_mfma_f32_16x16x32_bf16 v[32:35], v[60:63], v[52:55], v[32:35]
	global_load_dwordx4 v[56:59], v[14:15], off offset:768
	global_load_dwordx4 v[60:63], v[4:5], off offset:768
	global_load_dwordx4 v[80:83], v[6:7], off offset:2816
	global_load_dwordx4 v[84:87], v[10:11], off offset:768
	s_waitcnt vmcnt(9)
	ds_write_b128 v17, v[76:79]
	ds_write_b128 v17, v[40:43] offset:8704
	ds_write_b128 v17, v[72:75] offset:17408
	s_waitcnt vmcnt(7)
	ds_write_b128 v17, v[92:95] offset:26112
	ds_write_b128 v17, v[88:91] offset:34816
	s_waitcnt vmcnt(6)
	ds_write_b128 v17, v[96:99] offset:43520
	s_waitcnt lgkmcnt(0)
	s_barrier
	ds_read_b128 v[92:95], v18 offset:34816
	ds_read_b128 v[96:99], v19
	ds_read_b128 v[100:103], v19 offset:64
	ds_read_b128 v[104:107], v18 offset:34880
	ds_read_b128 v[108:111], v18 offset:39168
	v_mfma_f32_16x16x32_bf16 v[36:39], v[64:67], v[52:55], v[36:39]
	v_mfma_f32_16x16x32_bf16 v[24:27], v[68:71], v[52:55], v[24:27]
	ds_read_b128 v[112:115], v18 offset:39232
	ds_read_b128 v[116:119], v18 offset:43520
	s_waitcnt lgkmcnt(5)
	v_mfma_f32_16x16x32_bf16 v[28:31], v[92:95], v[96:99], v[28:31]
	ds_read_b128 v[92:95], v18 offset:43584
	ds_read_b128 v[120:123], v18 offset:47872
	ds_read_b128 v[124:127], v18 offset:47936
	s_waitcnt lgkmcnt(5)
	v_mfma_f32_16x16x32_bf16 v[32:35], v[108:111], v[96:99], v[32:35]
	ds_read_b128 v[108:111], v18 offset:34944
	ds_read_b128 v[128:131], v19 offset:128
	s_waitcnt lgkmcnt(5)
	v_mfma_f32_16x16x32_bf16 v[36:39], v[116:119], v[96:99], v[36:39]
	ds_read_b128 v[64:67], v19 offset:192
	ds_read_b128 v[68:71], v18 offset:35008
	s_waitcnt lgkmcnt(5)
	v_mfma_f32_16x16x32_bf16 v[24:27], v[120:123], v[96:99], v[24:27]
	s_waitcnt lgkmcnt(10)
	v_mfma_f32_16x16x32_bf16 v[28:31], v[104:107], v[100:103], v[28:31]
	s_waitcnt lgkmcnt(8)
	v_mfma_f32_16x16x32_bf16 v[32:35], v[112:115], v[100:103], v[32:35]
	s_waitcnt lgkmcnt(6)
	v_mfma_f32_16x16x32_bf16 v[36:39], v[92:95], v[100:103], v[36:39]
	ds_read_b128 v[92:95], v18 offset:39296
	s_waitcnt lgkmcnt(5)
	v_mfma_f32_16x16x32_bf16 v[24:27], v[124:127], v[100:103], v[24:27]
	ds_read_b128 v[72:75], v18 offset:39360
	ds_read_b128 v[96:99], v18 offset:43648
	s_waitcnt lgkmcnt(5)
	v_mfma_f32_16x16x32_bf16 v[28:31], v[108:111], v[128:131], v[28:31]
	ds_read_b128 v[76:79], v18 offset:43712
	ds_read_b128 v[100:103], v18 offset:48000
	ds_read_b128 v[88:91], v18 offset:48064
	s_waitcnt lgkmcnt(5)
	v_mfma_f32_16x16x32_bf16 v[32:35], v[92:95], v[128:131], v[32:35]
	s_waitcnt lgkmcnt(3)
	v_mfma_f32_16x16x32_bf16 v[36:39], v[96:99], v[128:131], v[36:39]
	s_waitcnt lgkmcnt(1)
	v_mfma_f32_16x16x32_bf16 v[24:27], v[100:103], v[128:131], v[24:27]
	s_waitcnt lgkmcnt(1)
	global_load_dwordx4 v[40:43], v[8:9], off offset:3072
	global_load_dwordx4 v[52:55], v[12:13], off offset:3072
	v_mfma_f32_16x16x32_bf16 v[28:31], v[68:71], v[64:67], v[28:31]
	v_mfma_f32_16x16x32_bf16 v[32:35], v[72:75], v[64:67], v[32:35]
	global_load_dwordx4 v[68:71], v[14:15], off offset:1024
	global_load_dwordx4 v[72:75], v[4:5], off offset:1024
	global_load_dwordx4 v[92:95], v[6:7], off offset:3072
	global_load_dwordx4 v[96:99], v[10:11], off offset:1024
	s_waitcnt vmcnt(9)
	ds_write_b128 v17, v[56:59] offset:52224
	ds_write_b128 v17, v[44:47] offset:60928
	ds_write_b128 v21, v[48:51] offset:17408
	s_waitcnt vmcnt(7)
	ds_write_b128 v21, v[80:83] offset:26112
	ds_write_b128 v22, v[60:63]
	s_waitcnt vmcnt(6)
	ds_write_b128 v23, v[84:87]
	s_waitcnt lgkmcnt(0)
	s_barrier
	ds_read_b128 v[84:87], v20 offset:52224
	ds_read_b128 v[100:103], v19 offset:52224
	ds_read_b128 v[104:107], v19 offset:52288
	ds_read_b128 v[108:111], v20 offset:52288
	ds_read_b128 v[112:115], v20 offset:56576
	v_mfma_f32_16x16x32_bf16 v[36:39], v[76:79], v[64:67], v[36:39]
	v_mfma_f32_16x16x32_bf16 v[24:27], v[88:91], v[64:67], v[24:27]
	ds_read_b128 v[116:119], v20 offset:56640
	ds_read_b128 v[120:123], v20 offset:60928
	s_waitcnt lgkmcnt(5)
	v_mfma_f32_16x16x32_bf16 v[28:31], v[84:87], v[100:103], v[28:31]
	ds_read_b128 v[84:87], v20 offset:60992
	ds_read_b128 v[124:127], v20 offset:65280
	ds_read_b128 v[128:131], v20 offset:65344
	s_waitcnt lgkmcnt(5)
	v_mfma_f32_16x16x32_bf16 v[32:35], v[112:115], v[100:103], v[32:35]
	ds_read_b128 v[112:115], v20 offset:52352
	ds_read_b128 v[132:135], v19 offset:52352
	s_waitcnt lgkmcnt(5)
	v_mfma_f32_16x16x32_bf16 v[36:39], v[120:123], v[100:103], v[36:39]
	ds_read_b128 v[56:59], v19 offset:52416
	ds_read_b128 v[60:63], v20 offset:52416
	s_waitcnt lgkmcnt(5)
	v_mfma_f32_16x16x32_bf16 v[24:27], v[124:127], v[100:103], v[24:27]
	s_waitcnt lgkmcnt(10)
	v_mfma_f32_16x16x32_bf16 v[28:31], v[108:111], v[104:107], v[28:31]
	s_waitcnt lgkmcnt(8)
	v_mfma_f32_16x16x32_bf16 v[32:35], v[116:119], v[104:107], v[32:35]
	s_waitcnt lgkmcnt(6)
	v_mfma_f32_16x16x32_bf16 v[36:39], v[84:87], v[104:107], v[36:39]
	ds_read_b128 v[84:87], v20 offset:56704
	s_waitcnt lgkmcnt(5)
	v_mfma_f32_16x16x32_bf16 v[24:27], v[128:131], v[104:107], v[24:27]
	ds_read_b128 v[64:67], v20 offset:56768
	ds_read_b128 v[100:103], v20 offset:61056
	s_waitcnt lgkmcnt(5)
	v_mfma_f32_16x16x32_bf16 v[28:31], v[112:115], v[132:135], v[28:31]
	ds_read_b128 v[76:79], v20 offset:61120
	ds_read_b128 v[104:107], v20 offset:65408
	ds_read_b128 v[80:83], v20 offset:65472
	s_waitcnt lgkmcnt(5)
	v_mfma_f32_16x16x32_bf16 v[32:35], v[84:87], v[132:135], v[32:35]
	s_waitcnt lgkmcnt(3)
	v_mfma_f32_16x16x32_bf16 v[36:39], v[100:103], v[132:135], v[36:39]
	s_waitcnt lgkmcnt(1)
	v_mfma_f32_16x16x32_bf16 v[24:27], v[104:107], v[132:135], v[24:27]
	s_waitcnt lgkmcnt(1)
	global_load_dwordx4 v[44:47], v[8:9], off offset:3328
	global_load_dwordx4 v[48:51], v[12:13], off offset:3328
	v_mfma_f32_16x16x32_bf16 v[28:31], v[60:63], v[56:59], v[28:31]
	v_mfma_f32_16x16x32_bf16 v[32:35], v[64:67], v[56:59], v[32:35]
	global_load_dwordx4 v[60:63], v[14:15], off offset:1280
	global_load_dwordx4 v[64:67], v[4:5], off offset:1280
	global_load_dwordx4 v[84:87], v[6:7], off offset:3328
	global_load_dwordx4 v[88:91], v[10:11], off offset:1280
	s_waitcnt vmcnt(9)
	ds_write_b128 v17, v[68:71]
	ds_write_b128 v17, v[40:43] offset:8704
	ds_write_b128 v17, v[52:55] offset:17408
	s_waitcnt vmcnt(7)
	ds_write_b128 v17, v[92:95] offset:26112
	ds_write_b128 v17, v[72:75] offset:34816
	s_waitcnt vmcnt(6)
	ds_write_b128 v17, v[96:99] offset:43520
	s_waitcnt lgkmcnt(0)
	s_barrier
	ds_read_b128 v[92:95], v18 offset:34816
	ds_read_b128 v[96:99], v19
	ds_read_b128 v[100:103], v19 offset:64
	ds_read_b128 v[104:107], v18 offset:34880
	ds_read_b128 v[108:111], v18 offset:39168
	v_mfma_f32_16x16x32_bf16 v[36:39], v[76:79], v[56:59], v[36:39]
	v_mfma_f32_16x16x32_bf16 v[24:27], v[80:83], v[56:59], v[24:27]
	ds_read_b128 v[112:115], v18 offset:39232
	ds_read_b128 v[116:119], v18 offset:43520
	s_waitcnt lgkmcnt(5)
	v_mfma_f32_16x16x32_bf16 v[28:31], v[92:95], v[96:99], v[28:31]
	ds_read_b128 v[92:95], v18 offset:43584
	ds_read_b128 v[120:123], v18 offset:47872
	ds_read_b128 v[124:127], v18 offset:47936
	s_waitcnt lgkmcnt(5)
	v_mfma_f32_16x16x32_bf16 v[32:35], v[108:111], v[96:99], v[32:35]
	ds_read_b128 v[108:111], v18 offset:34944
	ds_read_b128 v[128:131], v19 offset:128
	s_waitcnt lgkmcnt(5)
	v_mfma_f32_16x16x32_bf16 v[36:39], v[116:119], v[96:99], v[36:39]
	ds_read_b128 v[56:59], v19 offset:192
	ds_read_b128 v[68:71], v18 offset:35008
	s_waitcnt lgkmcnt(5)
	v_mfma_f32_16x16x32_bf16 v[24:27], v[120:123], v[96:99], v[24:27]
	s_waitcnt lgkmcnt(10)
	v_mfma_f32_16x16x32_bf16 v[28:31], v[104:107], v[100:103], v[28:31]
	s_waitcnt lgkmcnt(8)
	v_mfma_f32_16x16x32_bf16 v[32:35], v[112:115], v[100:103], v[32:35]
	s_waitcnt lgkmcnt(6)
	v_mfma_f32_16x16x32_bf16 v[36:39], v[92:95], v[100:103], v[36:39]
	ds_read_b128 v[92:95], v18 offset:39296
	s_waitcnt lgkmcnt(5)
	v_mfma_f32_16x16x32_bf16 v[24:27], v[124:127], v[100:103], v[24:27]
	ds_read_b128 v[72:75], v18 offset:39360
	ds_read_b128 v[96:99], v18 offset:43648
	s_waitcnt lgkmcnt(5)
	v_mfma_f32_16x16x32_bf16 v[28:31], v[108:111], v[128:131], v[28:31]
	ds_read_b128 v[76:79], v18 offset:43712
	ds_read_b128 v[100:103], v18 offset:48000
	ds_read_b128 v[80:83], v18 offset:48064
	s_waitcnt lgkmcnt(5)
	v_mfma_f32_16x16x32_bf16 v[32:35], v[92:95], v[128:131], v[32:35]
	s_waitcnt lgkmcnt(3)
	v_mfma_f32_16x16x32_bf16 v[36:39], v[96:99], v[128:131], v[36:39]
	s_waitcnt lgkmcnt(1)
	v_mfma_f32_16x16x32_bf16 v[24:27], v[100:103], v[128:131], v[24:27]
	s_waitcnt lgkmcnt(1)
	global_load_dwordx4 v[40:43], v[8:9], off offset:3584
	global_load_dwordx4 v[52:55], v[12:13], off offset:3584
	v_mfma_f32_16x16x32_bf16 v[28:31], v[68:71], v[56:59], v[28:31]
	v_mfma_f32_16x16x32_bf16 v[32:35], v[72:75], v[56:59], v[32:35]
	global_load_dwordx4 v[68:71], v[14:15], off offset:1536
	global_load_dwordx4 v[72:75], v[4:5], off offset:1536
	global_load_dwordx4 v[92:95], v[6:7], off offset:3584
	global_load_dwordx4 v[96:99], v[10:11], off offset:1536
	s_waitcnt vmcnt(9)
	ds_write_b128 v17, v[60:63] offset:52224
	ds_write_b128 v17, v[44:47] offset:60928
	ds_write_b128 v21, v[48:51] offset:17408
	s_waitcnt vmcnt(7)
	ds_write_b128 v21, v[84:87] offset:26112
	ds_write_b128 v22, v[64:67]
	s_waitcnt vmcnt(6)
	ds_write_b128 v23, v[88:91]
	s_waitcnt lgkmcnt(0)
	s_barrier
	ds_read_b128 v[84:87], v20 offset:52224
	ds_read_b128 v[88:91], v19 offset:52224
	ds_read_b128 v[100:103], v19 offset:52288
	ds_read_b128 v[104:107], v20 offset:52288
	ds_read_b128 v[108:111], v20 offset:56576
	v_mfma_f32_16x16x32_bf16 v[36:39], v[76:79], v[56:59], v[36:39]
	v_mfma_f32_16x16x32_bf16 v[24:27], v[80:83], v[56:59], v[24:27]
	ds_read_b128 v[112:115], v20 offset:56640
	ds_read_b128 v[116:119], v20 offset:60928
	s_waitcnt lgkmcnt(5)
	v_mfma_f32_16x16x32_bf16 v[28:31], v[84:87], v[88:91], v[28:31]
	ds_read_b128 v[84:87], v20 offset:60992
	ds_read_b128 v[120:123], v20 offset:65280
	ds_read_b128 v[124:127], v20 offset:65344
	s_waitcnt lgkmcnt(5)
	v_mfma_f32_16x16x32_bf16 v[32:35], v[108:111], v[88:91], v[32:35]
	ds_read_b128 v[108:111], v20 offset:52352
	ds_read_b128 v[128:131], v19 offset:52352
	s_waitcnt lgkmcnt(5)
	v_mfma_f32_16x16x32_bf16 v[36:39], v[116:119], v[88:91], v[36:39]
	ds_read_b128 v[56:59], v19 offset:52416
	ds_read_b128 v[60:63], v20 offset:52416
	s_waitcnt lgkmcnt(5)
	v_mfma_f32_16x16x32_bf16 v[24:27], v[120:123], v[88:91], v[24:27]
	s_waitcnt lgkmcnt(10)
	v_mfma_f32_16x16x32_bf16 v[28:31], v[104:107], v[100:103], v[28:31]
	s_waitcnt lgkmcnt(8)
	v_mfma_f32_16x16x32_bf16 v[32:35], v[112:115], v[100:103], v[32:35]
	s_waitcnt lgkmcnt(6)
	v_mfma_f32_16x16x32_bf16 v[36:39], v[84:87], v[100:103], v[36:39]
	ds_read_b128 v[84:87], v20 offset:56704
	s_waitcnt lgkmcnt(5)
	v_mfma_f32_16x16x32_bf16 v[24:27], v[124:127], v[100:103], v[24:27]
	ds_read_b128 v[64:67], v20 offset:56768
	ds_read_b128 v[88:91], v20 offset:61056
	s_waitcnt lgkmcnt(5)
	v_mfma_f32_16x16x32_bf16 v[28:31], v[108:111], v[128:131], v[28:31]
	ds_read_b128 v[76:79], v20 offset:61120
	ds_read_b128 v[100:103], v20 offset:65408
	ds_read_b128 v[80:83], v20 offset:65472
	s_waitcnt lgkmcnt(5)
	v_mfma_f32_16x16x32_bf16 v[32:35], v[84:87], v[128:131], v[32:35]
	s_waitcnt lgkmcnt(3)
	v_mfma_f32_16x16x32_bf16 v[36:39], v[88:91], v[128:131], v[36:39]
	s_waitcnt lgkmcnt(1)
	v_mfma_f32_16x16x32_bf16 v[24:27], v[100:103], v[128:131], v[24:27]
	s_waitcnt lgkmcnt(1)
	global_load_dwordx4 v[44:47], v[8:9], off offset:3840
	global_load_dwordx4 v[48:51], v[12:13], off offset:3840
	v_mfma_f32_16x16x32_bf16 v[28:31], v[60:63], v[56:59], v[28:31]
	global_load_dwordx4 v[12:15], v[14:15], off offset:1792
	s_nop 0
	global_load_dwordx4 v[60:63], v[4:5], off offset:1792
	s_nop 0
	global_load_dwordx4 v[4:7], v[6:7], off offset:3840
	s_nop 0
	global_load_dwordx4 v[8:11], v[10:11], off offset:1792
	s_waitcnt vmcnt(9)
	ds_write_b128 v17, v[68:71]
	ds_write_b128 v17, v[40:43] offset:8704
	ds_write_b128 v17, v[52:55] offset:17408
	s_waitcnt vmcnt(7)
	ds_write_b128 v17, v[92:95] offset:26112
	ds_write_b128 v17, v[72:75] offset:34816
	s_waitcnt vmcnt(6)
	ds_write_b128 v17, v[96:99] offset:43520
	s_waitcnt lgkmcnt(0)
	s_barrier
	ds_read_b128 v[84:87], v18 offset:34816
	ds_read_b128 v[88:91], v19
	ds_read_b128 v[92:95], v19 offset:64
	ds_read_b128 v[96:99], v18 offset:34880
	ds_read_b128 v[100:103], v18 offset:39168
	v_mfma_f32_16x16x32_bf16 v[32:35], v[64:67], v[56:59], v[32:35]
	v_mfma_f32_16x16x32_bf16 v[36:39], v[76:79], v[56:59], v[36:39]
	v_mfma_f32_16x16x32_bf16 v[24:27], v[80:83], v[56:59], v[24:27]
	ds_read_b128 v[104:107], v18 offset:39232
	ds_read_b128 v[108:111], v18 offset:43520
	s_waitcnt lgkmcnt(5)
	v_mfma_f32_16x16x32_bf16 v[28:31], v[84:87], v[88:91], v[28:31]
	ds_read_b128 v[84:87], v18 offset:43584
	ds_read_b128 v[112:115], v18 offset:47872
	ds_read_b128 v[116:119], v18 offset:47936
	s_waitcnt lgkmcnt(5)
	v_mfma_f32_16x16x32_bf16 v[32:35], v[100:103], v[88:91], v[32:35]
	ds_read_b128 v[100:103], v18 offset:34944
	ds_read_b128 v[52:55], v19 offset:128
	s_waitcnt lgkmcnt(5)
	v_mfma_f32_16x16x32_bf16 v[36:39], v[108:111], v[88:91], v[36:39]
	ds_read_b128 v[56:59], v19 offset:192
	ds_read_b128 v[64:67], v18 offset:35008
	s_waitcnt lgkmcnt(5)
	v_mfma_f32_16x16x32_bf16 v[24:27], v[112:115], v[88:91], v[24:27]
	s_waitcnt lgkmcnt(10)
	v_mfma_f32_16x16x32_bf16 v[28:31], v[96:99], v[92:95], v[28:31]
	s_waitcnt lgkmcnt(8)
	v_mfma_f32_16x16x32_bf16 v[32:35], v[104:107], v[92:95], v[32:35]
	s_waitcnt lgkmcnt(6)
	v_mfma_f32_16x16x32_bf16 v[36:39], v[84:87], v[92:95], v[36:39]
	ds_read_b128 v[84:87], v18 offset:39296
	s_waitcnt lgkmcnt(5)
	v_mfma_f32_16x16x32_bf16 v[24:27], v[116:119], v[92:95], v[24:27]
	ds_read_b128 v[68:71], v18 offset:39360
	ds_read_b128 v[88:91], v18 offset:43648
	s_waitcnt lgkmcnt(5)
	v_mfma_f32_16x16x32_bf16 v[28:31], v[100:103], v[52:55], v[28:31]
	ds_read_b128 v[72:75], v18 offset:43712
	s_waitcnt lgkmcnt(3)
	v_mfma_f32_16x16x32_bf16 v[32:35], v[84:87], v[52:55], v[32:35]
	s_waitcnt lgkmcnt(1)
	v_mfma_f32_16x16x32_bf16 v[36:39], v[88:91], v[52:55], v[36:39]
	s_waitcnt lgkmcnt(1)
	ds_read_b128 v[40:43], v18 offset:48000
	ds_read_b128 v[76:79], v18 offset:48064
	s_waitcnt vmcnt(3)
	ds_write_b128 v17, v[12:15] offset:52224
	ds_write_b128 v17, v[44:47] offset:60928
	ds_write_b128 v21, v[48:51] offset:17408
	s_waitcnt vmcnt(1)
	ds_write_b128 v21, v[4:7] offset:26112
	ds_write_b128 v22, v[60:63]
	s_waitcnt vmcnt(0)
	ds_write_b128 v23, v[8:11]
	s_waitcnt lgkmcnt(0)
	s_barrier
	v_mfma_f32_16x16x32_bf16 v[12:15], v[64:67], v[56:59], v[28:31]
	v_mfma_f32_16x16x32_bf16 v[4:7], v[68:71], v[56:59], v[32:35]
	s_nop 1
	ds_read_b128 v[28:31], v20 offset:52224
	ds_read_b128 v[32:35], v19 offset:52224
	s_waitcnt lgkmcnt(9)
	v_mfma_f32_16x16x32_bf16 v[24:27], v[40:43], v[52:55], v[24:27]
	v_mfma_f32_16x16x32_bf16 v[8:11], v[72:75], v[56:59], v[36:39]
	s_nop 2
	ds_read_b128 v[36:39], v20 offset:56576
	ds_read_b128 v[40:43], v19 offset:52288
	ds_read_b128 v[44:47], v20 offset:52288
	s_waitcnt lgkmcnt(11)
	v_mfma_f32_16x16x32_bf16 v[22:25], v[76:79], v[56:59], v[24:27]
	s_waitcnt lgkmcnt(3)
	v_mfma_f32_16x16x32_bf16 v[12:15], v[28:31], v[32:35], v[12:15]
	s_nop 0
	ds_read_b128 v[26:29], v20 offset:60928
	ds_read_b128 v[48:51], v20 offset:65280
	ds_read_b128 v[52:55], v20 offset:56640
	s_waitcnt lgkmcnt(5)
	v_mfma_f32_16x16x32_bf16 v[4:7], v[36:39], v[32:35], v[4:7]
	ds_read_b128 v[36:39], v20 offset:60992
	ds_read_b128 v[56:59], v20 offset:65344
	s_waitcnt lgkmcnt(4)
	v_mfma_f32_16x16x32_bf16 v[8:11], v[26:29], v[32:35], v[8:11]
	ds_read_b128 v[26:29], v19 offset:52352
	ds_read_b128 v[60:63], v19 offset:52416
	ds_read_b128 v[64:67], v20 offset:52352
	ds_read_b128 v[68:71], v20 offset:52416
	s_waitcnt lgkmcnt(6)
	v_mfma_f32_16x16x32_bf16 v[52:55], v[52:55], v[40:43], v[4:7]
	s_nop 2
	v_or_b32_e32 v4, s5, v16
	v_mfma_f32_16x16x32_bf16 v[12:15], v[44:47], v[40:43], v[12:15]
	v_add_u32_e32 v4, s6, v4
	v_ashrrev_i32_e32 v5, 31, v4
	s_waitcnt lgkmcnt(5)
	v_mfma_f32_16x16x32_bf16 v[6:9], v[36:39], v[40:43], v[8:11]
	s_nop 2
	v_lshlrev_b64 v[10:11], 11, v[4:5]
	v_lshl_add_u64 v[10:11], s[10:11], 0, v[10:11]
	v_mfma_f32_16x16x32_bf16 v[22:25], v[48:51], v[32:35], v[22:25]
	ds_read_b128 v[30:33], v20 offset:56704
	ds_read_b128 v[48:51], v20 offset:56768
	ds_read_b128 v[72:75], v20 offset:61056
	ds_read_b128 v[76:79], v20 offset:61120
	v_lshl_add_u64 v[16:17], v[10:11], 0, s[46:47]
	ds_read_b128 v[44:47], v20 offset:65408
	ds_read_b128 v[18:21], v20 offset:65472
	s_waitcnt lgkmcnt(7)
	v_mfma_f32_16x16x32_bf16 v[10:13], v[64:67], v[26:29], v[12:15]
	s_waitcnt lgkmcnt(0)
	s_barrier
	s_waitcnt lgkmcnt(6)
	v_mfma_f32_16x16x32_bf16 v[10:13], v[68:71], v[60:63], v[10:13]
	v_lshlrev_b32_e32 v14, 3, v2
	v_mov_b32_e32 v15, v3
	v_lshl_add_u64 v[34:35], v[16:17], 0, v[14:15]
	s_waitcnt lgkmcnt(5)
	v_mfma_f32_16x16x32_bf16 v[14:17], v[30:33], v[26:29], v[52:55]
	global_load_dwordx2 v[30:31], v[34:35], off
	s_waitcnt vmcnt(0)
	v_lshlrev_b32_e32 v32, 16, v30
	v_mfma_f32_16x16x32_bf16 v[22:25], v[56:59], v[40:43], v[22:25]
	v_and_b32_e32 v33, 0xffff0000, v30
	v_lshlrev_b32_e32 v30, 16, v31
	v_and_b32_e32 v31, 0xffff0000, v31
	v_pk_add_f32 v[12:13], v[12:13], v[30:31]
	v_pk_add_f32 v[10:11], v[10:11], v[32:33]
	s_waitcnt lgkmcnt(4)
	v_mfma_f32_16x16x32_bf16 v[14:17], v[48:51], v[60:63], v[14:17]
	v_cvt_pk_bf16_f32 v30, v10, v11
	v_cvt_pk_bf16_f32 v31, v12, v13
	global_store_dwordx2 v[34:35], v[30:31], off
	s_waitcnt lgkmcnt(1)
	v_mfma_f32_16x16x32_bf16 v[10:13], v[44:47], v[26:29], v[22:25]
	v_lshlrev_b32_e32 v2, 16, v30
	s_nop 1
	global_load_dwordx2 v[22:23], v[34:35], off offset:32
	v_mfma_f32_16x16x32_bf16 v[6:9], v[72:75], v[26:29], v[6:9]
	s_waitcnt vmcnt(0)
	v_lshlrev_b32_e32 v24, 16, v22
	v_and_b32_e32 v25, 0xffff0000, v22
	v_lshlrev_b32_e32 v22, 16, v23
	v_and_b32_e32 v23, 0xffff0000, v23
	v_pk_add_f32 v[16:17], v[16:17], v[22:23]
	v_pk_add_f32 v[14:15], v[14:15], v[24:25]
	v_mfma_f32_16x16x32_bf16 v[6:9], v[76:79], v[60:63], v[6:9]
	v_cvt_pk_bf16_f32 v14, v14, v15
	v_cvt_pk_bf16_f32 v15, v16, v17
	global_load_dwordx2 v[16:17], v[34:35], off offset:64
	s_waitcnt vmcnt(0)
	v_lshlrev_b32_e32 v22, 16, v16
	v_and_b32_e32 v23, 0xffff0000, v16
	v_lshlrev_b32_e32 v16, 16, v17
	v_and_b32_e32 v17, 0xffff0000, v17
	global_store_dwordx2 v[34:35], v[14:15], off offset:32
	s_nop 0
	v_pk_add_f32 v[8:9], v[8:9], v[16:17]
	v_pk_add_f32 v[6:7], v[6:7], v[22:23]
	s_nop 0
	v_cvt_pk_bf16_f32 v16, v6, v7
	v_cvt_pk_bf16_f32 v17, v8, v9
	global_load_dwordx2 v[22:23], v[34:35], off offset:96
	s_waitcnt lgkmcnt(0)
	v_mfma_f32_16x16x32_bf16 v[6:9], v[18:21], v[60:63], v[10:13]
	global_store_dwordx2 v[34:35], v[16:17], off offset:64
	s_nop 1
	v_and_b32_e32 v10, 0xffff0000, v30
	v_and_b32_e32 v12, 0xffff0000, v31
	v_lshlrev_b32_e32 v11, 16, v31
	v_mul_f32_e32 v10, v10, v10
	v_mul_f32_e32 v12, v12, v12
	v_fmac_f32_e32 v10, v2, v2
	v_fmac_f32_e32 v12, v11, v11
	v_and_b32_e32 v11, 0xffff0000, v14
	v_and_b32_e32 v13, 0xffff0000, v15
	v_add_f32_e32 v2, v10, v12
	v_lshlrev_b32_e32 v10, 16, v14
	v_lshlrev_b32_e32 v12, 16, v15
	v_mul_f32_e32 v11, v11, v11
	v_mul_f32_e32 v13, v13, v13
	v_fmac_f32_e32 v11, v10, v10
	v_fmac_f32_e32 v13, v12, v12
	v_add_f32_e32 v10, v11, v13
	v_and_b32_e32 v11, 0xffff0000, v16
	v_and_b32_e32 v13, 0xffff0000, v17
	v_add_f32_e32 v2, v2, v10
	v_lshlrev_b32_e32 v10, 16, v16
	v_lshlrev_b32_e32 v12, 16, v17
	v_mul_f32_e32 v11, v11, v11
	v_mul_f32_e32 v13, v13, v13
	v_fmac_f32_e32 v11, v10, v10
	v_fmac_f32_e32 v13, v12, v12
	v_add_f32_e32 v10, v11, v13
	v_add_f32_e32 v2, v2, v10
	s_waitcnt vmcnt(1)
	v_lshlrev_b32_e32 v10, 16, v22
	v_and_b32_e32 v11, 0xffff0000, v22
	v_lshlrev_b32_e32 v12, 16, v23
	v_and_b32_e32 v13, 0xffff0000, v23
	v_pk_add_f32 v[8:9], v[8:9], v[12:13]
	v_pk_add_f32 v[6:7], v[6:7], v[10:11]
	s_nop 0
	v_cvt_pk_bf16_f32 v10, v6, v7
	v_cvt_pk_bf16_f32 v11, v8, v9
	global_store_dwordx2 v[34:35], v[10:11], off offset:96
	v_and_b32_e32 v7, 0xffff0000, v10
	v_and_b32_e32 v9, 0xffff0000, v11
	v_lshlrev_b32_e32 v6, 16, v10
	v_lshlrev_b32_e32 v8, 16, v11
	v_mul_f32_e32 v7, v7, v7
	v_mul_f32_e32 v9, v9, v9
	v_fmac_f32_e32 v7, v6, v6
	v_fmac_f32_e32 v9, v8, v8
	v_add_f32_e32 v6, v7, v9
	v_add_f32_e32 v2, v2, v6
	ds_swizzle_b32 v6, v2 offset:swizzle(SWAP,16)
	s_and_saveexec_b64 s[4:5], vcc
	s_cbranch_execz .LBB0_2434
	v_lshl_add_u64 v[4:5], v[4:5], 2, s[2:3]
	s_waitcnt lgkmcnt(0)
	v_add_f32_e32 v1, v2, v6
	global_atomic_add_f32 v[4:5], v1, off

.LBB0_2447:
	s_waitcnt vmcnt(0)
	v_readlane_b32 s28, v255, 8
	s_andn2_b64 vcc, exec, s[16:17]
	v_readlane_b32 s29, v255, 9
	s_barrier
	s_cbranch_vccnz .LBB0_2451
	v_mov_b32_e32 v1, v0
	s_lshl_b32 s5, s34, 3
	v_ashrrev_i32_e32 v2, 31, v1
	v_lshrrev_b32_e32 v2, 28, v2
	v_add_u32_e32 v2, v1, v2
	v_ashrrev_i32_e32 v17, 4, v2
	s_and_b32 s5, s5, 0xffffff80
	v_and_b32_e32 v2, -16, v2
	v_add_u32_e32 v4, s5, v17
	v_sub_u32_e32 v19, v1, v2
	v_ashrrev_i32_e32 v5, 31, v4
	s_lshl_b32 s4, s34, 6
	v_lshlrev_b64 v[6:7], 13, v[4:5]
	v_lshlrev_b32_e32 v4, 3, v19
	s_and_b32 s4, s4, 0x380
	v_ashrrev_i32_e32 v5, 31, v4
	v_add_u32_e32 v8, s4, v17
	v_lshlrev_b64 v[10:11], 1, v[4:5]
	v_lshl_add_u64 v[6:7], s[12:13], 0, v[6:7]
	v_ashrrev_i32_e32 v9, 31, v8
	v_lshl_add_u64 v[14:15], v[6:7], 0, v[10:11]
	v_lshlrev_b64 v[8:9], 11, v[8:9]
	v_add_co_u32_e32 v6, vcc, s76, v14
	v_lshl_add_u64 v[8:9], s[14:15], 0, v[8:9]
	s_nop 0
	v_addc_co_u32_e32 v7, vcc, 0, v15, vcc
	v_lshl_add_u64 v[4:5], v[8:9], 0, v[10:11]
	v_add_co_u32_e32 v8, vcc, s89, v14
	global_load_dwordx4 v[20:23], v[6:7], off offset:2048
	s_nop 0
	v_addc_co_u32_e32 v9, vcc, 0, v15, vcc
	v_add_co_u32_e32 v12, vcc, s96, v14
	global_load_dwordx4 v[24:27], v[8:9], off offset:2048
	s_nop 0
	v_addc_co_u32_e32 v13, vcc, 0, v15, vcc
	v_add_co_u32_e32 v6, vcc, s97, v14
	global_load_dwordx4 v[28:31], v[12:13], off offset:2048
	s_nop 0
	v_addc_co_u32_e32 v7, vcc, 0, v15, vcc
	global_load_dwordx4 v[32:35], v[6:7], off offset:2048
	global_load_dwordx4 v[36:39], v[4:5], off
	v_add_co_u32_e32 v10, vcc, s63, v4
	s_mov_b64 s[8:9], 0x31800800
	s_nop 0
	v_addc_co_u32_e32 v11, vcc, 0, v5, vcc
	global_load_dwordx4 v[40:43], v[10:11], off
	v_lshl_add_u64 v[14:15], v[14:15], 0, s[8:9]
	global_load_dwordx4 v[44:47], v[4:5], off offset:256
	global_load_dwordx4 v[48:51], v[14:15], off offset:256
	global_load_dwordx4 v[52:55], v[8:9], off offset:2304
	global_load_dwordx4 v[56:59], v[12:13], off offset:2304
	global_load_dwordx4 v[60:63], v[6:7], off offset:2304
	global_load_dwordx4 v[64:67], v[10:11], off offset:256
	v_mul_lo_u32 v17, v17, s81
	v_lshlrev_b32_e32 v19, 4, v19
	v_and_b32_e32 v16, 15, v1
	v_bfe_u32 v2, v1, 4, 2
	v_add3_u32 v17, v17, v19, 0
	v_lshlrev_b32_e32 v68, 4, v2
	v_mul_u32_u24_e32 v18, 0x110, v16
	v_add3_u32 v18, v18, v68, 0
	v_readfirstlane_b32 s6, v1
	s_ashr_i32 s6, s6, 2
	s_add_i32 s5, s5, 0x10000
	v_bfi_b32 v19, -16, s6, v1
	v_mul_lo_u32 v19, v19, s81
	v_add3_u32 v19, v19, v68, 0
	s_and_b32 s6, s6, -16
	s_lshl_b32 s46, s4, 1
	v_and_b32_e32 v1, 16, v1
	v_cmp_eq_u32_e32 vcc, 0, v1
	s_waitcnt vmcnt(7)
	ds_write_b128 v17, v[36:39] offset:34816
	ds_write_b128 v17, v[20:23]
	ds_write_b128 v17, v[24:27] offset:8704
	ds_write_b128 v17, v[28:31] offset:17408
	ds_write_b128 v17, v[32:35] offset:26112
	s_waitcnt vmcnt(6)
	ds_write_b128 v17, v[40:43] offset:43520
	s_waitcnt lgkmcnt(0)
	s_barrier
	ds_read_b128 v[88:91], v18 offset:34816
	ds_read_b128 v[92:95], v19
	ds_read_b128 v[96:99], v19 offset:64
	ds_read_b128 v[100:103], v18 offset:34880
	ds_read_b128 v[104:107], v18 offset:39168
	ds_read_b128 v[108:111], v18 offset:39232
	ds_read_b128 v[112:115], v18 offset:43520
	s_waitcnt lgkmcnt(5)
	v_mfma_f32_16x16x32_bf16 v[20:23], v[88:91], v[92:95], 0
	ds_read_b128 v[88:91], v18 offset:43584
	ds_read_b128 v[116:119], v18 offset:47872
	ds_read_b128 v[120:123], v18 offset:47936
	s_waitcnt lgkmcnt(5)
	v_mfma_f32_16x16x32_bf16 v[36:39], v[104:107], v[92:95], 0
	s_waitcnt lgkmcnt(6)
	v_mfma_f32_16x16x32_bf16 v[20:23], v[100:103], v[96:99], v[20:23]
	ds_read_b128 v[100:103], v18 offset:34944
	s_waitcnt lgkmcnt(5)
	v_mfma_f32_16x16x32_bf16 v[32:35], v[108:111], v[96:99], v[36:39]
	ds_read_b128 v[104:107], v19 offset:128
	s_waitcnt lgkmcnt(5)
	v_mfma_f32_16x16x32_bf16 v[68:71], v[112:115], v[92:95], 0
	s_waitcnt lgkmcnt(3)
	v_mfma_f32_16x16x32_bf16 v[24:27], v[116:119], v[92:95], 0
	s_waitcnt lgkmcnt(4)
	v_mfma_f32_16x16x32_bf16 v[36:39], v[88:91], v[96:99], v[68:71]
	s_nop 2
	ds_read_b128 v[68:71], v19 offset:192
	ds_read_b128 v[72:75], v18 offset:35008
	ds_read_b128 v[88:91], v18 offset:39296
	s_waitcnt lgkmcnt(5)
	v_mfma_f32_16x16x32_bf16 v[24:27], v[120:123], v[96:99], v[24:27]
	ds_read_b128 v[76:79], v18 offset:39360
	ds_read_b128 v[92:95], v18 offset:43648
	s_waitcnt lgkmcnt(5)
	v_mfma_f32_16x16x32_bf16 v[40:43], v[100:103], v[104:107], v[20:23]
	ds_read_b128 v[80:83], v18 offset:43712
	ds_read_b128 v[96:99], v18 offset:48000
	ds_read_b128 v[84:87], v18 offset:48064
	s_waitcnt lgkmcnt(5)
	v_mfma_f32_16x16x32_bf16 v[32:35], v[88:91], v[104:107], v[32:35]
	s_waitcnt lgkmcnt(3)
	v_mfma_f32_16x16x32_bf16 v[36:39], v[92:95], v[104:107], v[36:39]
	s_waitcnt lgkmcnt(1)
	v_mfma_f32_16x16x32_bf16 v[24:27], v[96:99], v[104:107], v[24:27]
	s_waitcnt lgkmcnt(1)
	v_add_u32_e32 v21, 0xcc00, v17
	v_add_u32_e32 v22, 0x15400, v17
	v_add_u32_e32 v23, 0x17600, v17
	v_mfma_f32_16x16x32_bf16 v[28:31], v[72:75], v[68:71], v[40:43]
	s_nop 2
	global_load_dwordx4 v[40:43], v[8:9], off offset:2560
	global_load_dwordx4 v[72:75], v[12:13], off offset:2560
	v_add_u32_e32 v20, 0x8800, v18
	v_mfma_f32_16x16x32_bf16 v[32:35], v[76:79], v[68:71], v[32:35]
	global_load_dwordx4 v[76:79], v[14:15], off offset:512
	global_load_dwordx4 v[88:91], v[4:5], off offset:512
	global_load_dwordx4 v[92:95], v[6:7], off offset:2560
	global_load_dwordx4 v[96:99], v[10:11], off offset:512
	s_waitcnt vmcnt(10)
	ds_write_b128 v17, v[48:51] offset:52224
	s_waitcnt vmcnt(9)
	ds_write_b128 v17, v[52:55] offset:60928
	s_waitcnt vmcnt(8)
	ds_write_b128 v21, v[56:59] offset:17408
	s_waitcnt vmcnt(7)
	ds_write_b128 v21, v[60:63] offset:26112
	ds_write_b128 v22, v[44:47]
	s_waitcnt vmcnt(6)
	ds_write_b128 v23, v[64:67]
	s_waitcnt lgkmcnt(0)
	s_barrier
	ds_read_b128 v[100:103], v20 offset:52224
	ds_read_b128 v[104:107], v19 offset:52224
	ds_read_b128 v[108:111], v19 offset:52288
	ds_read_b128 v[112:115], v20 offset:52288
	ds_read_b128 v[116:119], v20 offset:56576
	ds_read_b128 v[120:123], v20 offset:56640
	ds_read_b128 v[124:127], v20 offset:60928
	s_waitcnt lgkmcnt(5)
	v_mfma_f32_16x16x32_bf16 v[28:31], v[100:103], v[104:107], v[28:31]
	v_mfma_f32_16x16x32_bf16 v[36:39], v[80:83], v[68:71], v[36:39]
	ds_read_b128 v[100:103], v20 offset:60992
	ds_read_b128 v[128:131], v20 offset:65280
	ds_read_b128 v[132:135], v20 offset:65344
	s_waitcnt lgkmcnt(5)
	v_mfma_f32_16x16x32_bf16 v[32:35], v[116:119], v[104:107], v[32:35]
	v_mfma_f32_16x16x32_bf16 v[24:27], v[84:87], v[68:71], v[24:27]
	ds_read_b128 v[116:119], v20 offset:52352
	ds_read_b128 v[136:139], v19 offset:52352
	s_waitcnt lgkmcnt(5)
	v_mfma_f32_16x16x32_bf16 v[36:39], v[124:127], v[104:107], v[36:39]
	ds_read_b128 v[52:55], v19 offset:52416
	ds_read_b128 v[56:59], v20 offset:52416
	s_waitcnt lgkmcnt(5)
	v_mfma_f32_16x16x32_bf16 v[24:27], v[128:131], v[104:107], v[24:27]
	s_waitcnt lgkmcnt(10)
	v_mfma_f32_16x16x32_bf16 v[28:31], v[112:115], v[108:111], v[28:31]
	s_waitcnt lgkmcnt(8)
	v_mfma_f32_16x16x32_bf16 v[32:35], v[120:123], v[108:111], v[32:35]
	s_waitcnt lgkmcnt(6)
	v_mfma_f32_16x16x32_bf16 v[36:39], v[100:103], v[108:111], v[36:39]
	ds_read_b128 v[100:103], v20 offset:56704
	s_waitcnt lgkmcnt(5)
	v_mfma_f32_16x16x32_bf16 v[24:27], v[132:135], v[108:111], v[24:27]
	ds_read_b128 v[60:63], v20 offset:56768
	ds_read_b128 v[104:107], v20 offset:61056
	s_waitcnt lgkmcnt(5)
	v_mfma_f32_16x16x32_bf16 v[28:31], v[116:119], v[136:139], v[28:31]
	ds_read_b128 v[64:67], v20 offset:61120
	ds_read_b128 v[108:111], v20 offset:65408
	ds_read_b128 v[68:71], v20 offset:65472
	s_waitcnt lgkmcnt(5)
	v_mfma_f32_16x16x32_bf16 v[32:35], v[100:103], v[136:139], v[32:35]
	s_waitcnt lgkmcnt(3)
	v_mfma_f32_16x16x32_bf16 v[36:39], v[104:107], v[136:139], v[36:39]
	s_waitcnt lgkmcnt(1)
	v_mfma_f32_16x16x32_bf16 v[24:27], v[108:111], v[136:139], v[24:27]
	s_waitcnt lgkmcnt(1)
	global_load_dwordx4 v[44:47], v[8:9], off offset:2816
	global_load_dwordx4 v[48:51], v[12:13], off offset:2816
	v_mfma_f32_16x16x32_bf16 v[28:31], v[56:59], v[52:55], v[28:31]
	v_mfma_f32_16x16x32_bf16 v[32:35], v[60:63], v[52:55], v[32:35]
	global_load_dwordx4 v[56:59], v[14:15], off offset:768
	global_load_dwordx4 v[60:63], v[4:5], off offset:768
	global_load_dwordx4 v[80:83], v[6:7], off offset:2816
	global_load_dwordx4 v[84:87], v[10:11], off offset:768
	s_waitcnt vmcnt(9)
	ds_write_b128 v17, v[76:79]
	ds_write_b128 v17, v[40:43] offset:8704
	ds_write_b128 v17, v[72:75] offset:17408
	s_waitcnt vmcnt(7)
	ds_write_b128 v17, v[92:95] offset:26112
	ds_write_b128 v17, v[88:91] offset:34816
	s_waitcnt vmcnt(6)
	ds_write_b128 v17, v[96:99] offset:43520
	s_waitcnt lgkmcnt(0)
	s_barrier
	ds_read_b128 v[92:95], v18 offset:34816
	ds_read_b128 v[96:99], v19
	ds_read_b128 v[100:103], v19 offset:64
	ds_read_b128 v[104:107], v18 offset:34880
	ds_read_b128 v[108:111], v18 offset:39168
	v_mfma_f32_16x16x32_bf16 v[36:39], v[64:67], v[52:55], v[36:39]
	v_mfma_f32_16x16x32_bf16 v[24:27], v[68:71], v[52:55], v[24:27]
	ds_read_b128 v[112:115], v18 offset:39232
	ds_read_b128 v[116:119], v18 offset:43520
	s_waitcnt lgkmcnt(5)
	v_mfma_f32_16x16x32_bf16 v[28:31], v[92:95], v[96:99], v[28:31]
	ds_read_b128 v[92:95], v18 offset:43584
	ds_read_b128 v[120:123], v18 offset:47872
	ds_read_b128 v[124:127], v18 offset:47936
	s_waitcnt lgkmcnt(5)
	v_mfma_f32_16x16x32_bf16 v[32:35], v[108:111], v[96:99], v[32:35]
	ds_read_b128 v[108:111], v18 offset:34944
	ds_read_b128 v[128:131], v19 offset:128
	s_waitcnt lgkmcnt(5)
	v_mfma_f32_16x16x32_bf16 v[36:39], v[116:119], v[96:99], v[36:39]
	ds_read_b128 v[64:67], v19 offset:192
	ds_read_b128 v[68:71], v18 offset:35008
	s_waitcnt lgkmcnt(5)
	v_mfma_f32_16x16x32_bf16 v[24:27], v[120:123], v[96:99], v[24:27]
	s_waitcnt lgkmcnt(10)
	v_mfma_f32_16x16x32_bf16 v[28:31], v[104:107], v[100:103], v[28:31]
	s_waitcnt lgkmcnt(8)
	v_mfma_f32_16x16x32_bf16 v[32:35], v[112:115], v[100:103], v[32:35]
	s_waitcnt lgkmcnt(6)
	v_mfma_f32_16x16x32_bf16 v[36:39], v[92:95], v[100:103], v[36:39]
	ds_read_b128 v[92:95], v18 offset:39296
	s_waitcnt lgkmcnt(5)
	v_mfma_f32_16x16x32_bf16 v[24:27], v[124:127], v[100:103], v[24:27]
	ds_read_b128 v[72:75], v18 offset:39360
	ds_read_b128 v[96:99], v18 offset:43648
	s_waitcnt lgkmcnt(5)
	v_mfma_f32_16x16x32_bf16 v[28:31], v[108:111], v[128:131], v[28:31]
	ds_read_b128 v[76:79], v18 offset:43712
	ds_read_b128 v[100:103], v18 offset:48000
	ds_read_b128 v[88:91], v18 offset:48064
	s_waitcnt lgkmcnt(5)
	v_mfma_f32_16x16x32_bf16 v[32:35], v[92:95], v[128:131], v[32:35]
	s_waitcnt lgkmcnt(3)
	v_mfma_f32_16x16x32_bf16 v[36:39], v[96:99], v[128:131], v[36:39]
	s_waitcnt lgkmcnt(1)
	v_mfma_f32_16x16x32_bf16 v[24:27], v[100:103], v[128:131], v[24:27]
	s_waitcnt lgkmcnt(1)
	global_load_dwordx4 v[40:43], v[8:9], off offset:3072
	global_load_dwordx4 v[52:55], v[12:13], off offset:3072
	v_mfma_f32_16x16x32_bf16 v[28:31], v[68:71], v[64:67], v[28:31]
	v_mfma_f32_16x16x32_bf16 v[32:35], v[72:75], v[64:67], v[32:35]
	global_load_dwordx4 v[68:71], v[14:15], off offset:1024
	global_load_dwordx4 v[72:75], v[4:5], off offset:1024
	global_load_dwordx4 v[92:95], v[6:7], off offset:3072
	global_load_dwordx4 v[96:99], v[10:11], off offset:1024
	s_waitcnt vmcnt(9)
	ds_write_b128 v17, v[56:59] offset:52224
	ds_write_b128 v17, v[44:47] offset:60928
	ds_write_b128 v21, v[48:51] offset:17408
	s_waitcnt vmcnt(7)
	ds_write_b128 v21, v[80:83] offset:26112
	ds_write_b128 v22, v[60:63]
	s_waitcnt vmcnt(6)
	ds_write_b128 v23, v[84:87]
	s_waitcnt lgkmcnt(0)
	s_barrier
	ds_read_b128 v[84:87], v20 offset:52224
	ds_read_b128 v[100:103], v19 offset:52224
	ds_read_b128 v[104:107], v19 offset:52288
	ds_read_b128 v[108:111], v20 offset:52288
	ds_read_b128 v[112:115], v20 offset:56576
	v_mfma_f32_16x16x32_bf16 v[36:39], v[76:79], v[64:67], v[36:39]
	v_mfma_f32_16x16x32_bf16 v[24:27], v[88:91], v[64:67], v[24:27]
	ds_read_b128 v[116:119], v20 offset:56640
	ds_read_b128 v[120:123], v20 offset:60928
	s_waitcnt lgkmcnt(5)
	v_mfma_f32_16x16x32_bf16 v[28:31], v[84:87], v[100:103], v[28:31]
	ds_read_b128 v[84:87], v20 offset:60992
	ds_read_b128 v[124:127], v20 offset:65280
	ds_read_b128 v[128:131], v20 offset:65344
	s_waitcnt lgkmcnt(5)
	v_mfma_f32_16x16x32_bf16 v[32:35], v[112:115], v[100:103], v[32:35]
	ds_read_b128 v[112:115], v20 offset:52352
	ds_read_b128 v[132:135], v19 offset:52352
	s_waitcnt lgkmcnt(5)
	v_mfma_f32_16x16x32_bf16 v[36:39], v[120:123], v[100:103], v[36:39]
	ds_read_b128 v[56:59], v19 offset:52416
	ds_read_b128 v[60:63], v20 offset:52416
	s_waitcnt lgkmcnt(5)
	v_mfma_f32_16x16x32_bf16 v[24:27], v[124:127], v[100:103], v[24:27]
	s_waitcnt lgkmcnt(10)
	v_mfma_f32_16x16x32_bf16 v[28:31], v[108:111], v[104:107], v[28:31]
	s_waitcnt lgkmcnt(8)
	v_mfma_f32_16x16x32_bf16 v[32:35], v[116:119], v[104:107], v[32:35]
	s_waitcnt lgkmcnt(6)
	v_mfma_f32_16x16x32_bf16 v[36:39], v[84:87], v[104:107], v[36:39]
	ds_read_b128 v[84:87], v20 offset:56704
	s_waitcnt lgkmcnt(5)
	v_mfma_f32_16x16x32_bf16 v[24:27], v[128:131], v[104:107], v[24:27]
	ds_read_b128 v[64:67], v20 offset:56768
	ds_read_b128 v[100:103], v20 offset:61056
	s_waitcnt lgkmcnt(5)
	v_mfma_f32_16x16x32_bf16 v[28:31], v[112:115], v[132:135], v[28:31]
	ds_read_b128 v[76:79], v20 offset:61120
	ds_read_b128 v[104:107], v20 offset:65408
	ds_read_b128 v[80:83], v20 offset:65472
	s_waitcnt lgkmcnt(5)
	v_mfma_f32_16x16x32_bf16 v[32:35], v[84:87], v[132:135], v[32:35]
	s_waitcnt lgkmcnt(3)
	v_mfma_f32_16x16x32_bf16 v[36:39], v[100:103], v[132:135], v[36:39]
	s_waitcnt lgkmcnt(1)
	v_mfma_f32_16x16x32_bf16 v[24:27], v[104:107], v[132:135], v[24:27]
	s_waitcnt lgkmcnt(1)
	global_load_dwordx4 v[44:47], v[8:9], off offset:3328
	global_load_dwordx4 v[48:51], v[12:13], off offset:3328
	v_mfma_f32_16x16x32_bf16 v[28:31], v[60:63], v[56:59], v[28:31]
	v_mfma_f32_16x16x32_bf16 v[32:35], v[64:67], v[56:59], v[32:35]
	global_load_dwordx4 v[60:63], v[14:15], off offset:1280
	global_load_dwordx4 v[64:67], v[4:5], off offset:1280
	global_load_dwordx4 v[84:87], v[6:7], off offset:3328
	global_load_dwordx4 v[88:91], v[10:11], off offset:1280
	s_waitcnt vmcnt(9)
	ds_write_b128 v17, v[68:71]
	ds_write_b128 v17, v[40:43] offset:8704
	ds_write_b128 v17, v[52:55] offset:17408
	s_waitcnt vmcnt(7)
	ds_write_b128 v17, v[92:95] offset:26112
	ds_write_b128 v17, v[72:75] offset:34816
	s_waitcnt vmcnt(6)
	ds_write_b128 v17, v[96:99] offset:43520
	s_waitcnt lgkmcnt(0)
	s_barrier
	ds_read_b128 v[92:95], v18 offset:34816
	ds_read_b128 v[96:99], v19
	ds_read_b128 v[100:103], v19 offset:64
	ds_read_b128 v[104:107], v18 offset:34880
	ds_read_b128 v[108:111], v18 offset:39168
	v_mfma_f32_16x16x32_bf16 v[36:39], v[76:79], v[56:59], v[36:39]
	v_mfma_f32_16x16x32_bf16 v[24:27], v[80:83], v[56:59], v[24:27]
	ds_read_b128 v[112:115], v18 offset:39232
	ds_read_b128 v[116:119], v18 offset:43520
	s_waitcnt lgkmcnt(5)
	v_mfma_f32_16x16x32_bf16 v[28:31], v[92:95], v[96:99], v[28:31]
	ds_read_b128 v[92:95], v18 offset:43584
	ds_read_b128 v[120:123], v18 offset:47872
	ds_read_b128 v[124:127], v18 offset:47936
	s_waitcnt lgkmcnt(5)
	v_mfma_f32_16x16x32_bf16 v[32:35], v[108:111], v[96:99], v[32:35]
	ds_read_b128 v[108:111], v18 offset:34944
	ds_read_b128 v[128:131], v19 offset:128
	s_waitcnt lgkmcnt(5)
	v_mfma_f32_16x16x32_bf16 v[36:39], v[116:119], v[96:99], v[36:39]
	ds_read_b128 v[56:59], v19 offset:192
	ds_read_b128 v[68:71], v18 offset:35008
	s_waitcnt lgkmcnt(5)
	v_mfma_f32_16x16x32_bf16 v[24:27], v[120:123], v[96:99], v[24:27]
	s_waitcnt lgkmcnt(10)
	v_mfma_f32_16x16x32_bf16 v[28:31], v[104:107], v[100:103], v[28:31]
	s_waitcnt lgkmcnt(8)
	v_mfma_f32_16x16x32_bf16 v[32:35], v[112:115], v[100:103], v[32:35]
	s_waitcnt lgkmcnt(6)
	v_mfma_f32_16x16x32_bf16 v[36:39], v[92:95], v[100:103], v[36:39]
	ds_read_b128 v[92:95], v18 offset:39296
	s_waitcnt lgkmcnt(5)
	v_mfma_f32_16x16x32_bf16 v[24:27], v[124:127], v[100:103], v[24:27]
	ds_read_b128 v[72:75], v18 offset:39360
	ds_read_b128 v[96:99], v18 offset:43648
	s_waitcnt lgkmcnt(5)
	v_mfma_f32_16x16x32_bf16 v[28:31], v[108:111], v[128:131], v[28:31]
	ds_read_b128 v[76:79], v18 offset:43712
	ds_read_b128 v[100:103], v18 offset:48000
	ds_read_b128 v[80:83], v18 offset:48064
	s_waitcnt lgkmcnt(5)
	v_mfma_f32_16x16x32_bf16 v[32:35], v[92:95], v[128:131], v[32:35]
	s_waitcnt lgkmcnt(3)
	v_mfma_f32_16x16x32_bf16 v[36:39], v[96:99], v[128:131], v[36:39]
	s_waitcnt lgkmcnt(1)
	v_mfma_f32_16x16x32_bf16 v[24:27], v[100:103], v[128:131], v[24:27]
	s_waitcnt lgkmcnt(1)
	global_load_dwordx4 v[40:43], v[8:9], off offset:3584
	global_load_dwordx4 v[52:55], v[12:13], off offset:3584
	v_mfma_f32_16x16x32_bf16 v[28:31], v[68:71], v[56:59], v[28:31]
	v_mfma_f32_16x16x32_bf16 v[32:35], v[72:75], v[56:59], v[32:35]
	global_load_dwordx4 v[68:71], v[14:15], off offset:1536
	global_load_dwordx4 v[72:75], v[4:5], off offset:1536
	global_load_dwordx4 v[92:95], v[6:7], off offset:3584
	global_load_dwordx4 v[96:99], v[10:11], off offset:1536
	s_waitcnt vmcnt(9)
	ds_write_b128 v17, v[60:63] offset:52224
	ds_write_b128 v17, v[44:47] offset:60928
	ds_write_b128 v21, v[48:51] offset:17408
	s_waitcnt vmcnt(7)
	ds_write_b128 v21, v[84:87] offset:26112
	ds_write_b128 v22, v[64:67]
	s_waitcnt vmcnt(6)
	ds_write_b128 v23, v[88:91]
	s_waitcnt lgkmcnt(0)
	s_barrier
	ds_read_b128 v[84:87], v20 offset:52224
	ds_read_b128 v[88:91], v19 offset:52224
	ds_read_b128 v[100:103], v19 offset:52288
	ds_read_b128 v[104:107], v20 offset:52288
	ds_read_b128 v[108:111], v20 offset:56576
	v_mfma_f32_16x16x32_bf16 v[36:39], v[76:79], v[56:59], v[36:39]
	v_mfma_f32_16x16x32_bf16 v[24:27], v[80:83], v[56:59], v[24:27]
	ds_read_b128 v[112:115], v20 offset:56640
	ds_read_b128 v[116:119], v20 offset:60928
	s_waitcnt lgkmcnt(5)
	v_mfma_f32_16x16x32_bf16 v[28:31], v[84:87], v[88:91], v[28:31]
	ds_read_b128 v[84:87], v20 offset:60992
	ds_read_b128 v[120:123], v20 offset:65280
	ds_read_b128 v[124:127], v20 offset:65344
	s_waitcnt lgkmcnt(5)
	v_mfma_f32_16x16x32_bf16 v[32:35], v[108:111], v[88:91], v[32:35]
	ds_read_b128 v[108:111], v20 offset:52352
	ds_read_b128 v[128:131], v19 offset:52352
	s_waitcnt lgkmcnt(5)
	v_mfma_f32_16x16x32_bf16 v[36:39], v[116:119], v[88:91], v[36:39]
	ds_read_b128 v[56:59], v19 offset:52416
	ds_read_b128 v[60:63], v20 offset:52416
	s_waitcnt lgkmcnt(5)
	v_mfma_f32_16x16x32_bf16 v[24:27], v[120:123], v[88:91], v[24:27]
	s_waitcnt lgkmcnt(10)
	v_mfma_f32_16x16x32_bf16 v[28:31], v[104:107], v[100:103], v[28:31]
	s_waitcnt lgkmcnt(8)
	v_mfma_f32_16x16x32_bf16 v[32:35], v[112:115], v[100:103], v[32:35]
	s_waitcnt lgkmcnt(6)
	v_mfma_f32_16x16x32_bf16 v[36:39], v[84:87], v[100:103], v[36:39]
	ds_read_b128 v[84:87], v20 offset:56704
	s_waitcnt lgkmcnt(5)
	v_mfma_f32_16x16x32_bf16 v[24:27], v[124:127], v[100:103], v[24:27]
	ds_read_b128 v[64:67], v20 offset:56768
	ds_read_b128 v[88:91], v20 offset:61056
	s_waitcnt lgkmcnt(5)
	v_mfma_f32_16x16x32_bf16 v[28:31], v[108:111], v[128:131], v[28:31]
	ds_read_b128 v[76:79], v20 offset:61120
	ds_read_b128 v[100:103], v20 offset:65408
	ds_read_b128 v[80:83], v20 offset:65472
	s_waitcnt lgkmcnt(5)
	v_mfma_f32_16x16x32_bf16 v[32:35], v[84:87], v[128:131], v[32:35]
	s_waitcnt lgkmcnt(3)
	v_mfma_f32_16x16x32_bf16 v[36:39], v[88:91], v[128:131], v[36:39]
	s_waitcnt lgkmcnt(1)
	v_mfma_f32_16x16x32_bf16 v[24:27], v[100:103], v[128:131], v[24:27]
	s_waitcnt lgkmcnt(1)
	global_load_dwordx4 v[44:47], v[8:9], off offset:3840
	global_load_dwordx4 v[48:51], v[12:13], off offset:3840
	v_mfma_f32_16x16x32_bf16 v[28:31], v[60:63], v[56:59], v[28:31]
	global_load_dwordx4 v[12:15], v[14:15], off offset:1792
	s_nop 0
	global_load_dwordx4 v[60:63], v[4:5], off offset:1792
	s_nop 0
	global_load_dwordx4 v[4:7], v[6:7], off offset:3840
	s_nop 0
	global_load_dwordx4 v[8:11], v[10:11], off offset:1792
	s_waitcnt vmcnt(9)
	ds_write_b128 v17, v[68:71]
	ds_write_b128 v17, v[40:43] offset:8704
	ds_write_b128 v17, v[52:55] offset:17408
	s_waitcnt vmcnt(7)
	ds_write_b128 v17, v[92:95] offset:26112
	ds_write_b128 v17, v[72:75] offset:34816
	s_waitcnt vmcnt(6)
	ds_write_b128 v17, v[96:99] offset:43520
	s_waitcnt lgkmcnt(0)
	s_barrier
	ds_read_b128 v[84:87], v18 offset:34816
	ds_read_b128 v[88:91], v19
	ds_read_b128 v[92:95], v19 offset:64
	ds_read_b128 v[96:99], v18 offset:34880
	ds_read_b128 v[100:103], v18 offset:39168
	v_mfma_f32_16x16x32_bf16 v[32:35], v[64:67], v[56:59], v[32:35]
	v_mfma_f32_16x16x32_bf16 v[36:39], v[76:79], v[56:59], v[36:39]
	v_mfma_f32_16x16x32_bf16 v[24:27], v[80:83], v[56:59], v[24:27]
	ds_read_b128 v[104:107], v18 offset:39232
	ds_read_b128 v[108:111], v18 offset:43520
	s_waitcnt lgkmcnt(5)
	v_mfma_f32_16x16x32_bf16 v[28:31], v[84:87], v[88:91], v[28:31]
	ds_read_b128 v[84:87], v18 offset:43584
	ds_read_b128 v[112:115], v18 offset:47872
	ds_read_b128 v[116:119], v18 offset:47936
	s_waitcnt lgkmcnt(5)
	v_mfma_f32_16x16x32_bf16 v[32:35], v[100:103], v[88:91], v[32:35]
	ds_read_b128 v[100:103], v18 offset:34944
	ds_read_b128 v[52:55], v19 offset:128
	s_waitcnt lgkmcnt(5)
	v_mfma_f32_16x16x32_bf16 v[36:39], v[108:111], v[88:91], v[36:39]
	ds_read_b128 v[56:59], v19 offset:192
	ds_read_b128 v[64:67], v18 offset:35008
	s_waitcnt lgkmcnt(5)
	v_mfma_f32_16x16x32_bf16 v[24:27], v[112:115], v[88:91], v[24:27]
	s_waitcnt lgkmcnt(10)
	v_mfma_f32_16x16x32_bf16 v[28:31], v[96:99], v[92:95], v[28:31]
	s_waitcnt lgkmcnt(8)
	v_mfma_f32_16x16x32_bf16 v[32:35], v[104:107], v[92:95], v[32:35]
	s_waitcnt lgkmcnt(6)
	v_mfma_f32_16x16x32_bf16 v[36:39], v[84:87], v[92:95], v[36:39]
	ds_read_b128 v[84:87], v18 offset:39296
	s_waitcnt lgkmcnt(5)
	v_mfma_f32_16x16x32_bf16 v[24:27], v[116:119], v[92:95], v[24:27]
	ds_read_b128 v[68:71], v18 offset:39360
	ds_read_b128 v[88:91], v18 offset:43648
	s_waitcnt lgkmcnt(5)
	v_mfma_f32_16x16x32_bf16 v[28:31], v[100:103], v[52:55], v[28:31]
	ds_read_b128 v[72:75], v18 offset:43712
	s_waitcnt lgkmcnt(3)
	v_mfma_f32_16x16x32_bf16 v[32:35], v[84:87], v[52:55], v[32:35]
	s_waitcnt lgkmcnt(1)
	v_mfma_f32_16x16x32_bf16 v[36:39], v[88:91], v[52:55], v[36:39]
	s_waitcnt lgkmcnt(1)
	ds_read_b128 v[40:43], v18 offset:48000
	ds_read_b128 v[76:79], v18 offset:48064
	s_waitcnt vmcnt(3)
	ds_write_b128 v17, v[12:15] offset:52224
	ds_write_b128 v17, v[44:47] offset:60928
	ds_write_b128 v21, v[48:51] offset:17408
	s_waitcnt vmcnt(1)
	ds_write_b128 v21, v[4:7] offset:26112
	ds_write_b128 v22, v[60:63]
	s_waitcnt vmcnt(0)
	ds_write_b128 v23, v[8:11]
	s_waitcnt lgkmcnt(0)
	s_barrier
	v_mfma_f32_16x16x32_bf16 v[12:15], v[64:67], v[56:59], v[28:31]
	v_mfma_f32_16x16x32_bf16 v[4:7], v[68:71], v[56:59], v[32:35]
	s_nop 1
	ds_read_b128 v[28:31], v20 offset:52224
	ds_read_b128 v[32:35], v19 offset:52224
	s_waitcnt lgkmcnt(9)
	v_mfma_f32_16x16x32_bf16 v[24:27], v[40:43], v[52:55], v[24:27]
	v_mfma_f32_16x16x32_bf16 v[8:11], v[72:75], v[56:59], v[36:39]
	s_nop 2
	ds_read_b128 v[36:39], v20 offset:56576
	ds_read_b128 v[40:43], v19 offset:52288
	ds_read_b128 v[44:47], v20 offset:52288
	s_waitcnt lgkmcnt(11)
	v_mfma_f32_16x16x32_bf16 v[22:25], v[76:79], v[56:59], v[24:27]
	s_waitcnt lgkmcnt(3)
	v_mfma_f32_16x16x32_bf16 v[12:15], v[28:31], v[32:35], v[12:15]
	s_nop 0
	ds_read_b128 v[26:29], v20 offset:60928
	ds_read_b128 v[48:51], v20 offset:65280
	ds_read_b128 v[52:55], v20 offset:56640
	s_waitcnt lgkmcnt(5)
	v_mfma_f32_16x16x32_bf16 v[4:7], v[36:39], v[32:35], v[4:7]
	ds_read_b128 v[36:39], v20 offset:60992
	ds_read_b128 v[56:59], v20 offset:65344
	s_waitcnt lgkmcnt(4)
	v_mfma_f32_16x16x32_bf16 v[8:11], v[26:29], v[32:35], v[8:11]
	ds_read_b128 v[26:29], v19 offset:52352
	ds_read_b128 v[60:63], v19 offset:52416
	ds_read_b128 v[64:67], v20 offset:52352
	ds_read_b128 v[68:71], v20 offset:52416
	s_waitcnt lgkmcnt(6)
	v_mfma_f32_16x16x32_bf16 v[52:55], v[52:55], v[40:43], v[4:7]
	s_nop 2
	v_or_b32_e32 v4, s5, v16
	v_mfma_f32_16x16x32_bf16 v[12:15], v[44:47], v[40:43], v[12:15]
	v_add_u32_e32 v4, s6, v4
	v_ashrrev_i32_e32 v5, 31, v4
	s_waitcnt lgkmcnt(5)
	v_mfma_f32_16x16x32_bf16 v[6:9], v[36:39], v[40:43], v[8:11]
	s_nop 2
	v_lshlrev_b64 v[10:11], 11, v[4:5]
	v_lshl_add_u64 v[10:11], s[10:11], 0, v[10:11]
	v_mfma_f32_16x16x32_bf16 v[22:25], v[48:51], v[32:35], v[22:25]
	ds_read_b128 v[30:33], v20 offset:56704
	ds_read_b128 v[48:51], v20 offset:56768
	ds_read_b128 v[72:75], v20 offset:61056
	ds_read_b128 v[76:79], v20 offset:61120
	v_lshl_add_u64 v[16:17], v[10:11], 0, s[46:47]
	ds_read_b128 v[44:47], v20 offset:65408
	ds_read_b128 v[18:21], v20 offset:65472
	s_waitcnt lgkmcnt(7)
	v_mfma_f32_16x16x32_bf16 v[10:13], v[64:67], v[26:29], v[12:15]
	s_waitcnt lgkmcnt(0)
	s_barrier
	s_waitcnt lgkmcnt(6)
	v_mfma_f32_16x16x32_bf16 v[10:13], v[68:71], v[60:63], v[10:13]
	v_lshlrev_b32_e32 v14, 3, v2
	v_mov_b32_e32 v15, v3
	v_lshl_add_u64 v[34:35], v[16:17], 0, v[14:15]
	s_waitcnt lgkmcnt(5)
	v_mfma_f32_16x16x32_bf16 v[14:17], v[30:33], v[26:29], v[52:55]
	global_load_dwordx2 v[30:31], v[34:35], off
	s_waitcnt vmcnt(0)
	v_lshlrev_b32_e32 v32, 16, v30
	v_mfma_f32_16x16x32_bf16 v[22:25], v[56:59], v[40:43], v[22:25]
	v_and_b32_e32 v33, 0xffff0000, v30
	v_lshlrev_b32_e32 v30, 16, v31
	v_and_b32_e32 v31, 0xffff0000, v31
	v_pk_add_f32 v[12:13], v[12:13], v[30:31]
	v_pk_add_f32 v[10:11], v[10:11], v[32:33]
	s_waitcnt lgkmcnt(4)
	v_mfma_f32_16x16x32_bf16 v[14:17], v[48:51], v[60:63], v[14:17]
	v_cvt_pk_bf16_f32 v30, v10, v11
	v_cvt_pk_bf16_f32 v31, v12, v13
	global_store_dwordx2 v[34:35], v[30:31], off
	s_waitcnt lgkmcnt(1)
	v_mfma_f32_16x16x32_bf16 v[10:13], v[44:47], v[26:29], v[22:25]
	v_lshlrev_b32_e32 v2, 16, v30
	s_nop 1
	global_load_dwordx2 v[22:23], v[34:35], off offset:32
	v_mfma_f32_16x16x32_bf16 v[6:9], v[72:75], v[26:29], v[6:9]
	s_waitcnt vmcnt(0)
	v_lshlrev_b32_e32 v24, 16, v22
	v_and_b32_e32 v25, 0xffff0000, v22
	v_lshlrev_b32_e32 v22, 16, v23
	v_and_b32_e32 v23, 0xffff0000, v23
	v_pk_add_f32 v[16:17], v[16:17], v[22:23]
	v_pk_add_f32 v[14:15], v[14:15], v[24:25]
	v_mfma_f32_16x16x32_bf16 v[6:9], v[76:79], v[60:63], v[6:9]
	v_cvt_pk_bf16_f32 v14, v14, v15
	v_cvt_pk_bf16_f32 v15, v16, v17
	global_load_dwordx2 v[16:17], v[34:35], off offset:64
	s_waitcnt vmcnt(0)
	v_lshlrev_b32_e32 v22, 16, v16
	v_and_b32_e32 v23, 0xffff0000, v16
	v_lshlrev_b32_e32 v16, 16, v17
	v_and_b32_e32 v17, 0xffff0000, v17
	global_store_dwordx2 v[34:35], v[14:15], off offset:32
	s_nop 0
	v_pk_add_f32 v[8:9], v[8:9], v[16:17]
	v_pk_add_f32 v[6:7], v[6:7], v[22:23]
	s_nop 0
	v_cvt_pk_bf16_f32 v16, v6, v7
	v_cvt_pk_bf16_f32 v17, v8, v9
	global_load_dwordx2 v[22:23], v[34:35], off offset:96
	s_waitcnt lgkmcnt(0)
	v_mfma_f32_16x16x32_bf16 v[6:9], v[18:21], v[60:63], v[10:13]
	global_store_dwordx2 v[34:35], v[16:17], off offset:64
	s_nop 1
	v_and_b32_e32 v10, 0xffff0000, v30
	v_and_b32_e32 v12, 0xffff0000, v31
	v_lshlrev_b32_e32 v11, 16, v31
	v_mul_f32_e32 v10, v10, v10
	v_mul_f32_e32 v12, v12, v12
	v_fmac_f32_e32 v10, v2, v2
	v_fmac_f32_e32 v12, v11, v11
	v_and_b32_e32 v11, 0xffff0000, v14
	v_and_b32_e32 v13, 0xffff0000, v15
	v_add_f32_e32 v2, v10, v12
	v_lshlrev_b32_e32 v10, 16, v14
	v_lshlrev_b32_e32 v12, 16, v15
	v_mul_f32_e32 v11, v11, v11
	v_mul_f32_e32 v13, v13, v13
	v_fmac_f32_e32 v11, v10, v10
	v_fmac_f32_e32 v13, v12, v12
	v_add_f32_e32 v10, v11, v13
	v_and_b32_e32 v11, 0xffff0000, v16
	v_and_b32_e32 v13, 0xffff0000, v17
	v_add_f32_e32 v2, v2, v10
	v_lshlrev_b32_e32 v10, 16, v16
	v_lshlrev_b32_e32 v12, 16, v17
	v_mul_f32_e32 v11, v11, v11
	v_mul_f32_e32 v13, v13, v13
	v_fmac_f32_e32 v11, v10, v10
	v_fmac_f32_e32 v13, v12, v12
	v_add_f32_e32 v10, v11, v13
	v_add_f32_e32 v2, v2, v10
	s_waitcnt vmcnt(1)
	v_lshlrev_b32_e32 v10, 16, v22
	v_and_b32_e32 v11, 0xffff0000, v22
	v_lshlrev_b32_e32 v12, 16, v23
	v_and_b32_e32 v13, 0xffff0000, v23
	v_pk_add_f32 v[8:9], v[8:9], v[12:13]
	v_pk_add_f32 v[6:7], v[6:7], v[10:11]
	s_nop 0
	v_cvt_pk_bf16_f32 v10, v6, v7
	v_cvt_pk_bf16_f32 v11, v8, v9
	global_store_dwordx2 v[34:35], v[10:11], off offset:96
	v_and_b32_e32 v7, 0xffff0000, v10
	v_and_b32_e32 v9, 0xffff0000, v11
	v_lshlrev_b32_e32 v6, 16, v10
	v_lshlrev_b32_e32 v8, 16, v11
	v_mul_f32_e32 v7, v7, v7
	v_mul_f32_e32 v9, v9, v9
	v_fmac_f32_e32 v7, v6, v6
	v_fmac_f32_e32 v9, v8, v8
	v_add_f32_e32 v6, v7, v9
	v_add_f32_e32 v2, v2, v6
	ds_swizzle_b32 v6, v2 offset:swizzle(SWAP,16)
	s_and_saveexec_b64 s[4:5], vcc
	s_cbranch_execz .LBB0_2450
	v_lshl_add_u64 v[4:5], v[4:5], 2, s[2:3]
	s_waitcnt lgkmcnt(0)
	v_add_f32_e32 v1, v2, v6
	global_atomic_add_f32 v[4:5], v1, off
